# GEMM tiles: dropped the workgroup barrier after the last k-step (LDS buffers are next written only after the next tile's own barrier)
# speedup vs baseline: 1.0038x; 1.0038x over previous
.Ltail84:
	s_add_i32 s3, s24, 2
	v_add_u32_e32 v181, v144, v145
	ds_read_b128 v[80:83], v181 offset:16384
	ds_read_b128 v[84:87], v181 offset:18432
	ds_read_b128 v[88:91], v181 offset:20480
	ds_read_b128 v[92:95], v181 offset:22528
	v_add_u32_e32 v180, v143, v145
	ds_read_b128 v[64:67], v180
	s_add_i32 s24, s24, 4
	ds_read_b128 v[68:71], v180 offset:2048
	s_min_u32 s24, s24, 15
	s_lshl_b32 s92, s24, 7
	ds_read_b128 v[72:75], v180 offset:4096
	ds_read_b128 v[76:79], v180 offset:6144
	v_add_u32_e32 v182, v143, v146
	v_add_u32_e32 v186, v144, v146
	v_lshl_add_u64 v[224:225], v[138:139], 0, s[92:93]
	ds_read_b128 v[192:195], v182
	ds_read_b128 v[196:199], v182 offset:2048
	ds_read_b128 v[200:203], v182 offset:4096
	ds_read_b128 v[204:207], v182 offset:6144
	ds_read_b128 v[208:211], v186 offset:16384
	ds_read_b128 v[212:215], v186 offset:18432
	ds_read_b128 v[216:219], v186 offset:20480
	ds_read_b128 v[220:223], v186 offset:22528
	s_waitcnt lgkmcnt(11)
	v_mfma_f32_16x16x32_bf16 v[60:63], v[80:83], v[64:67], v[60:63]
	v_mfma_f32_16x16x32_bf16 v[56:59], v[84:87], v[64:67], v[56:59]
	v_mfma_f32_16x16x32_bf16 v[52:55], v[88:91], v[64:67], v[52:55]
	v_mfma_f32_16x16x32_bf16 v[48:51], v[92:95], v[64:67], v[48:51]
	s_waitcnt vmcnt(7)
	ds_write_b128 v156, v[96:99] offset:32768
	v_add_co_u32_e32 v96, vcc, s11, v224
	s_waitcnt lgkmcnt(11)
	v_mfma_f32_16x16x32_bf16 v[44:47], v[80:83], v[68:71], v[44:47]
	v_addc_co_u32_e32 v97, vcc, 0, v225, vcc
	v_mfma_f32_16x16x32_bf16 v[40:43], v[84:87], v[68:71], v[40:43]
	v_mfma_f32_16x16x32_bf16 v[36:39], v[88:91], v[68:71], v[36:39]
	v_mfma_f32_16x16x32_bf16 v[32:35], v[92:95], v[68:71], v[32:35]
	v_add_co_u32_e32 v96, vcc, s33, v224
	s_waitcnt vmcnt(6)
	ds_write_b128 v156, v[100:103] offset:36864
	s_nop 0
	v_addc_co_u32_e32 v97, vcc, 0, v225, vcc
	s_waitcnt lgkmcnt(11)
	v_mfma_f32_16x16x32_bf16 v[28:31], v[80:83], v[72:75], v[28:31]
	v_mfma_f32_16x16x32_bf16 v[24:27], v[84:87], v[72:75], v[24:27]
	v_mfma_f32_16x16x32_bf16 v[20:23], v[88:91], v[72:75], v[20:23]
	v_mfma_f32_16x16x32_bf16 v[16:19], v[92:95], v[72:75], v[16:19]
	s_waitcnt vmcnt(5)
	ds_write_b128 v156, v[104:107] offset:40960
	s_waitcnt lgkmcnt(11)
	v_mfma_f32_16x16x32_bf16 v[12:15], v[80:83], v[76:79], v[12:15]
	v_add_co_u32_e32 v80, vcc, s59, v224
	v_mfma_f32_16x16x32_bf16 v[0:3], v[92:95], v[76:79], v[0:3]
	s_nop 0
	v_addc_co_u32_e32 v81, vcc, 0, v225, vcc
	v_lshl_add_u64 v[92:93], v[140:141], 0, s[92:93]
	v_mfma_f32_16x16x32_bf16 v[8:11], v[84:87], v[76:79], v[8:11]
	v_add_co_u32_e32 v84, vcc, s11, v92
	s_nop 1
	v_addc_co_u32_e32 v85, vcc, 0, v93, vcc
	v_mfma_f32_16x16x32_bf16 v[4:7], v[88:91], v[76:79], v[4:7]
	v_add_co_u32_e32 v88, vcc, s33, v92
	s_nop 0
	s_nop 0
	v_addc_co_u32_e32 v89, vcc, 0, v93, vcc
	s_waitcnt vmcnt(4)
	ds_write_b128 v156, v[112:115] offset:45056
	s_waitcnt lgkmcnt(7)
	v_mfma_f32_16x16x32_bf16 v[60:63], v[208:211], v[192:195], v[60:63]
	s_waitcnt lgkmcnt(6)
	v_mfma_f32_16x16x32_bf16 v[56:59], v[212:215], v[192:195], v[56:59]
	s_waitcnt lgkmcnt(5)
	v_mfma_f32_16x16x32_bf16 v[52:55], v[216:219], v[192:195], v[52:55]
	s_waitcnt lgkmcnt(4)
	v_mfma_f32_16x16x32_bf16 v[48:51], v[220:223], v[192:195], v[48:51]
	v_add_co_u32_e32 v92, vcc, s59, v92
	s_waitcnt vmcnt(3)
	ds_write_b128 v156, v[108:111] offset:49152
	s_nop 0
	v_addc_co_u32_e32 v93, vcc, 0, v93, vcc
	v_mfma_f32_16x16x32_bf16 v[44:47], v[208:211], v[196:199], v[44:47]
	v_mfma_f32_16x16x32_bf16 v[40:43], v[212:215], v[196:199], v[40:43]
	v_mfma_f32_16x16x32_bf16 v[36:39], v[216:219], v[196:199], v[36:39]
	v_mfma_f32_16x16x32_bf16 v[32:35], v[220:223], v[196:199], v[32:35]
	s_waitcnt vmcnt(2)
	ds_write_b128 v156, v[116:119] offset:53248
	v_mfma_f32_16x16x32_bf16 v[28:31], v[208:211], v[200:203], v[28:31]
	v_mfma_f32_16x16x32_bf16 v[24:27], v[212:215], v[200:203], v[24:27]
	v_mfma_f32_16x16x32_bf16 v[20:23], v[216:219], v[200:203], v[20:23]
	v_mfma_f32_16x16x32_bf16 v[16:19], v[220:223], v[200:203], v[16:19]
	s_waitcnt vmcnt(1)
	ds_write_b128 v156, v[120:123] offset:57344
	v_mfma_f32_16x16x32_bf16 v[12:15], v[208:211], v[204:207], v[12:15]
	v_mfma_f32_16x16x32_bf16 v[8:11], v[212:215], v[204:207], v[8:11]
	v_mfma_f32_16x16x32_bf16 v[4:7], v[216:219], v[204:207], v[4:7]
	v_mfma_f32_16x16x32_bf16 v[0:3], v[220:223], v[204:207], v[0:3]
	s_waitcnt vmcnt(0)
	ds_write_b128 v156, v[124:127] offset:61440
	s_waitcnt lgkmcnt(0)
	s_barrier
	ds_read_b128 v[112:115], v181 offset:49152
	ds_read_b128 v[116:119], v181 offset:51200
	ds_read_b128 v[120:123], v181 offset:53248
	ds_read_b128 v[124:127], v181 offset:55296
	ds_read_b128 v[96:99], v180 offset:32768
	ds_read_b128 v[100:103], v180 offset:34816
	s_min_u32 s24, s3, 12
	s_lshl_b32 s92, s24, 7
	ds_read_b128 v[104:107], v180 offset:36864
	v_lshl_add_u64 v[224:225], v[138:139], 0, s[92:93]
	ds_read_b128 v[108:111], v180 offset:38912
	ds_read_b128 v[192:195], v182 offset:32768
	ds_read_b128 v[196:199], v182 offset:34816
	ds_read_b128 v[200:203], v182 offset:36864
	ds_read_b128 v[204:207], v182 offset:38912
	ds_read_b128 v[208:211], v186 offset:49152
	ds_read_b128 v[212:215], v186 offset:51200
	ds_read_b128 v[216:219], v186 offset:53248
	ds_read_b128 v[220:223], v186 offset:55296
	s_waitcnt lgkmcnt(11)
	v_mfma_f32_16x16x32_bf16 v[60:63], v[112:115], v[96:99], v[60:63]
	v_mfma_f32_16x16x32_bf16 v[56:59], v[116:119], v[96:99], v[56:59]
	v_mfma_f32_16x16x32_bf16 v[52:55], v[120:123], v[96:99], v[52:55]
	v_mfma_f32_16x16x32_bf16 v[48:51], v[124:127], v[96:99], v[48:51]
	v_add_co_u32_e32 v64, vcc, s11, v224
	s_waitcnt lgkmcnt(10)
	v_mfma_f32_16x16x32_bf16 v[44:47], v[112:115], v[100:103], v[44:47]
	v_addc_co_u32_e32 v65, vcc, 0, v225, vcc
	v_mfma_f32_16x16x32_bf16 v[40:43], v[116:119], v[100:103], v[40:43]
	v_mfma_f32_16x16x32_bf16 v[36:39], v[120:123], v[100:103], v[36:39]
	v_mfma_f32_16x16x32_bf16 v[32:35], v[124:127], v[100:103], v[32:35]
	v_add_co_u32_e32 v64, vcc, s33, v224
	s_nop 1
	v_addc_co_u32_e32 v65, vcc, 0, v225, vcc
	s_waitcnt lgkmcnt(9)
	v_mfma_f32_16x16x32_bf16 v[28:31], v[112:115], v[104:107], v[28:31]
	v_mfma_f32_16x16x32_bf16 v[24:27], v[116:119], v[104:107], v[24:27]
	v_mfma_f32_16x16x32_bf16 v[20:23], v[120:123], v[104:107], v[20:23]
	v_mfma_f32_16x16x32_bf16 v[16:19], v[124:127], v[104:107], v[16:19]
	v_add_co_u32_e32 v64, vcc, s59, v224
	s_nop 1
	v_addc_co_u32_e32 v65, vcc, 0, v225, vcc
	s_waitcnt lgkmcnt(8)
	v_mfma_f32_16x16x32_bf16 v[12:15], v[112:115], v[108:111], v[12:15]
	v_mfma_f32_16x16x32_bf16 v[8:11], v[116:119], v[108:111], v[8:11]
	v_mfma_f32_16x16x32_bf16 v[4:7], v[120:123], v[108:111], v[4:7]
	v_mfma_f32_16x16x32_bf16 v[0:3], v[124:127], v[108:111], v[0:3]
	v_lshl_add_u64 v[64:65], v[140:141], 0, s[92:93]
	v_add_co_u32_e32 v66, vcc, s11, v64
	s_nop 1
	v_addc_co_u32_e32 v67, vcc, 0, v65, vcc
	s_waitcnt lgkmcnt(3)
	v_mfma_f32_16x16x32_bf16 v[60:63], v[208:211], v[192:195], v[60:63]
	s_waitcnt lgkmcnt(2)
	v_mfma_f32_16x16x32_bf16 v[56:59], v[212:215], v[192:195], v[56:59]
	s_waitcnt lgkmcnt(1)
	v_mfma_f32_16x16x32_bf16 v[52:55], v[216:219], v[192:195], v[52:55]
	s_waitcnt lgkmcnt(0)
	v_mfma_f32_16x16x32_bf16 v[48:51], v[220:223], v[192:195], v[48:51]
	v_mfma_f32_16x16x32_bf16 v[44:47], v[208:211], v[196:199], v[44:47]
	v_mfma_f32_16x16x32_bf16 v[40:43], v[212:215], v[196:199], v[40:43]
	v_mfma_f32_16x16x32_bf16 v[36:39], v[216:219], v[196:199], v[36:39]
	v_mfma_f32_16x16x32_bf16 v[32:35], v[220:223], v[196:199], v[32:35]
	v_add_co_u32_e32 v66, vcc, s33, v64
	s_nop 1
	v_addc_co_u32_e32 v67, vcc, 0, v65, vcc
	v_add_co_u32_e32 v64, vcc, s59, v64
	v_mfma_f32_16x16x32_bf16 v[28:31], v[208:211], v[200:203], v[28:31]
	s_nop 0
	v_addc_co_u32_e32 v65, vcc, 0, v65, vcc
	v_mfma_f32_16x16x32_bf16 v[24:27], v[212:215], v[200:203], v[24:27]
	v_mfma_f32_16x16x32_bf16 v[20:23], v[216:219], v[200:203], v[20:23]
	v_mfma_f32_16x16x32_bf16 v[16:19], v[220:223], v[200:203], v[16:19]
	v_mfma_f32_16x16x32_bf16 v[12:15], v[208:211], v[204:207], v[12:15]
	v_mfma_f32_16x16x32_bf16 v[8:11], v[212:215], v[204:207], v[8:11]
	v_mfma_f32_16x16x32_bf16 v[4:7], v[216:219], v[204:207], v[4:7]
	v_mfma_f32_16x16x32_bf16 v[0:3], v[220:223], v[204:207], v[0:3]
	s_mov_b32 s24, s3
	s_waitcnt lgkmcnt(0)
	s_and_saveexec_b64 s[24:25], s[36:37]
	s_cbranch_execz .LBB0_82
	v_add_f32_e32 v64, 0, v128
	v_add_f32_e32 v64, v64, v157
	v_add_f32_e32 v64, v64, v158
	v_add_f32_e32 v64, v64, v159
	v_add_f32_e32 v64, v64, v160
	v_add_f32_e32 v64, v64, v161
	v_add_f32_e32 v64, v64, v162
	v_add_f32_e32 v64, v64, v163
	v_add_f32_e32 v64, v64, v164
	v_add_f32_e32 v64, v64, v165
	v_add_f32_e32 v64, v64, v168
	v_add_f32_e32 v64, v64, v175
	v_add_f32_e32 v64, v64, v179
	v_add_f32_e32 v64, v64, v183
	v_add_f32_e32 v64, v64, v190
	v_add_f32_e32 v64, v64, v191
	v_fmamk_f32 v64, v64, 0x3a800000, v167
	s_mov_b32 s3, 0x800000
	v_mul_f32_e32 v65, 0x4b800000, v64
	v_cmp_gt_f32_e32 vcc, s3, v64
	s_nop 1
	v_cndmask_b32_e32 v64, v64, v65, vcc
	v_rsq_f32_e32 v64, v64
	s_nop 0
	v_mul_f32_e32 v65, 0x45800000, v64
	v_cndmask_b32_e32 v64, v64, v65, vcc
	ds_write_b32 v155, v64
	s_branch .LBB0_82

.Ltail92:
	s_add_i32 s0, s1, 2
	v_add_u32_e32 v111, v104, v105
	ds_read_b128 v[136:139], v111 offset:16384
	ds_read_b128 v[140:143], v111 offset:18432
	ds_read_b128 v[144:147], v111 offset:20480
	ds_read_b128 v[148:151], v111 offset:22528
	v_add_u32_e32 v110, v103, v105
	ds_read_b128 v[116:119], v110
	s_add_i32 s1, s1, 4
	ds_read_b128 v[120:123], v110 offset:2048
	s_min_u32 s1, s1, 15
	v_add_u32_e32 v113, v104, v114
	s_lshl_b32 s92, s1, 7
	ds_read_b128 v[124:127], v110 offset:4096
	v_add_u32_e32 v112, v103, v114
	ds_read_b128 v[194:197], v113 offset:16384
	ds_read_b128 v[198:201], v113 offset:18432
	ds_read_b128 v[202:205], v113 offset:20480
	ds_read_b128 v[206:209], v113 offset:22528
	v_lshl_add_u64 v[164:165], v[98:99], 0, s[92:93]
	ds_read_b128 v[132:135], v110 offset:6144
	ds_read_b128 v[152:155], v112
	ds_read_b128 v[156:159], v112 offset:2048
	ds_read_b128 v[160:163], v112 offset:4096
	ds_read_b128 v[190:193], v112 offset:6144
	s_waitcnt lgkmcnt(11)
	v_mfma_f32_16x16x32_bf16 v[92:95], v[136:139], v[116:119], v[92:95]
	v_mfma_f32_16x16x32_bf16 v[88:91], v[140:143], v[116:119], v[88:91]
	v_mfma_f32_16x16x32_bf16 v[52:55], v[144:147], v[116:119], v[52:55]
	v_mfma_f32_16x16x32_bf16 v[48:51], v[148:151], v[116:119], v[48:51]
	s_waitcnt vmcnt(7)
	ds_write_b128 v109, v[56:59] offset:32768
	v_add_co_u32_e32 v56, vcc, s11, v164
	s_waitcnt lgkmcnt(11)
	v_mfma_f32_16x16x32_bf16 v[44:47], v[136:139], v[120:123], v[44:47]
	v_addc_co_u32_e32 v57, vcc, 0, v165, vcc
	v_mfma_f32_16x16x32_bf16 v[40:43], v[140:143], v[120:123], v[40:43]
	v_mfma_f32_16x16x32_bf16 v[36:39], v[144:147], v[120:123], v[36:39]
	v_mfma_f32_16x16x32_bf16 v[32:35], v[148:151], v[120:123], v[32:35]
	v_add_co_u32_e32 v56, vcc, s33, v164
	s_waitcnt vmcnt(6)
	ds_write_b128 v109, v[60:63] offset:36864
	s_nop 0
	v_addc_co_u32_e32 v57, vcc, 0, v165, vcc
	s_waitcnt lgkmcnt(11)
	v_mfma_f32_16x16x32_bf16 v[28:31], v[136:139], v[124:127], v[28:31]
	v_mfma_f32_16x16x32_bf16 v[24:27], v[140:143], v[124:127], v[24:27]
	v_mfma_f32_16x16x32_bf16 v[20:23], v[144:147], v[124:127], v[20:23]
	v_mfma_f32_16x16x32_bf16 v[16:19], v[148:151], v[124:127], v[16:19]
	v_add_co_u32_e32 v56, vcc, s59, v164
	s_waitcnt vmcnt(5)
	ds_write_b128 v109, v[64:67] offset:40960
	s_nop 0
	v_addc_co_u32_e32 v57, vcc, 0, v165, vcc
	v_lshl_add_u64 v[64:65], v[100:101], 0, s[92:93]
	v_add_co_u32_e32 v66, vcc, s11, v64
	s_waitcnt lgkmcnt(7)
	v_mfma_f32_16x16x32_bf16 v[12:15], v[136:139], v[132:135], v[12:15]
	v_addc_co_u32_e32 v67, vcc, 0, v65, vcc
	v_mfma_f32_16x16x32_bf16 v[8:11], v[140:143], v[132:135], v[8:11]
	v_mfma_f32_16x16x32_bf16 v[4:7], v[144:147], v[132:135], v[4:7]
	v_mfma_f32_16x16x32_bf16 v[0:3], v[148:151], v[132:135], v[0:3]
	s_waitcnt vmcnt(4)
	ds_write_b128 v109, v[72:75] offset:45056
	s_waitcnt lgkmcnt(7)
	v_mfma_f32_16x16x32_bf16 v[56:59], v[194:197], v[152:155], v[92:95]
	v_mfma_f32_16x16x32_bf16 v[60:63], v[198:201], v[152:155], v[88:91]
	v_mfma_f32_16x16x32_bf16 v[52:55], v[202:205], v[152:155], v[52:55]
	v_mfma_f32_16x16x32_bf16 v[48:51], v[206:209], v[152:155], v[48:51]
	s_waitcnt vmcnt(3)
	ds_write_b128 v109, v[68:71] offset:49152
	s_waitcnt lgkmcnt(7)
	v_mfma_f32_16x16x32_bf16 v[44:47], v[194:197], v[156:159], v[44:47]
	v_mfma_f32_16x16x32_bf16 v[40:43], v[198:201], v[156:159], v[40:43]
	v_mfma_f32_16x16x32_bf16 v[36:39], v[202:205], v[156:159], v[36:39]
	v_mfma_f32_16x16x32_bf16 v[32:35], v[206:209], v[156:159], v[32:35]
	v_add_co_u32_e32 v66, vcc, s33, v64
	s_waitcnt vmcnt(2)
	ds_write_b128 v109, v[76:79] offset:53248
	v_addc_co_u32_e32 v67, vcc, 0, v65, vcc
	v_add_co_u32_e32 v64, vcc, s59, v64
	s_waitcnt lgkmcnt(7)
	v_mfma_f32_16x16x32_bf16 v[28:31], v[194:197], v[160:163], v[28:31]
	v_addc_co_u32_e32 v65, vcc, 0, v65, vcc
	v_mfma_f32_16x16x32_bf16 v[24:27], v[198:201], v[160:163], v[24:27]
	v_mfma_f32_16x16x32_bf16 v[20:23], v[202:205], v[160:163], v[20:23]
	v_mfma_f32_16x16x32_bf16 v[16:19], v[206:209], v[160:163], v[16:19]
	s_waitcnt vmcnt(1)
	ds_write_b128 v109, v[80:83] offset:57344
	s_waitcnt lgkmcnt(7)
	v_mfma_f32_16x16x32_bf16 v[12:15], v[194:197], v[190:193], v[12:15]
	v_mfma_f32_16x16x32_bf16 v[8:11], v[198:201], v[190:193], v[8:11]
	v_mfma_f32_16x16x32_bf16 v[4:7], v[202:205], v[190:193], v[4:7]
	v_mfma_f32_16x16x32_bf16 v[0:3], v[206:209], v[190:193], v[0:3]
	s_waitcnt vmcnt(0)
	ds_write_b128 v109, v[84:87] offset:61440
	s_waitcnt lgkmcnt(0)
	s_barrier
	ds_read_b128 v[84:87], v111 offset:51200
	ds_read_b128 v[80:83], v111 offset:49152
	ds_read_b128 v[88:91], v111 offset:53248
	ds_read_b128 v[92:95], v111 offset:55296
	ds_read_b128 v[64:67], v110 offset:32768
	s_min_u32 s1, s0, 12
	s_lshl_b32 s92, s1, 7
	ds_read_b128 v[68:71], v110 offset:34816
	v_lshl_add_u64 v[164:165], v[98:99], 0, s[92:93]
	ds_read_b128 v[72:75], v110 offset:36864
	ds_read_b128 v[76:79], v110 offset:38912
	ds_read_b128 v[152:155], v112 offset:32768
	ds_read_b128 v[156:159], v112 offset:34816
	ds_read_b128 v[160:163], v112 offset:36864
	ds_read_b128 v[190:193], v112 offset:38912
	ds_read_b128 v[194:197], v113 offset:49152
	ds_read_b128 v[198:201], v113 offset:51200
	ds_read_b128 v[202:205], v113 offset:53248
	ds_read_b128 v[206:209], v113 offset:55296
	s_waitcnt lgkmcnt(11)
	v_mfma_f32_16x16x32_bf16 v[214:217], v[84:87], v[64:67], v[60:63]
	v_mfma_f32_16x16x32_bf16 v[210:213], v[80:83], v[64:67], v[56:59]
	s_nop 1
	v_add_co_u32_e32 v60, vcc, s11, v164
	s_nop 1
	v_addc_co_u32_e32 v61, vcc, 0, v165, vcc
	v_mfma_f32_16x16x32_bf16 v[52:55], v[88:91], v[64:67], v[52:55]
	v_mfma_f32_16x16x32_bf16 v[48:51], v[92:95], v[64:67], v[48:51]
	v_add_co_u32_e32 v64, vcc, s33, v164
	s_nop 0
	s_nop 0
	v_addc_co_u32_e32 v65, vcc, 0, v165, vcc
	s_waitcnt lgkmcnt(10)
	v_mfma_f32_16x16x32_bf16 v[44:47], v[80:83], v[68:71], v[44:47]
	v_mfma_f32_16x16x32_bf16 v[40:43], v[84:87], v[68:71], v[40:43]
	v_mfma_f32_16x16x32_bf16 v[36:39], v[88:91], v[68:71], v[36:39]
	v_mfma_f32_16x16x32_bf16 v[32:35], v[92:95], v[68:71], v[32:35]
	v_add_co_u32_e32 v68, vcc, s59, v164
	s_waitcnt lgkmcnt(9)
	v_mfma_f32_16x16x32_bf16 v[28:31], v[80:83], v[72:75], v[28:31]
	v_addc_co_u32_e32 v69, vcc, 0, v165, vcc
	v_mfma_f32_16x16x32_bf16 v[24:27], v[84:87], v[72:75], v[24:27]
	v_mfma_f32_16x16x32_bf16 v[20:23], v[88:91], v[72:75], v[20:23]
	v_mfma_f32_16x16x32_bf16 v[16:19], v[92:95], v[72:75], v[16:19]
	s_waitcnt lgkmcnt(8)
	v_mfma_f32_16x16x32_bf16 v[8:11], v[84:87], v[76:79], v[8:11]
	v_lshl_add_u64 v[84:85], v[100:101], 0, s[92:93]
	v_mfma_f32_16x16x32_bf16 v[12:15], v[80:83], v[76:79], v[12:15]
	v_mfma_f32_16x16x32_bf16 v[4:7], v[88:91], v[76:79], v[4:7]
	v_mfma_f32_16x16x32_bf16 v[0:3], v[92:95], v[76:79], v[0:3]
	v_add_co_u32_e32 v76, vcc, s11, v84
	s_nop 0
	s_nop 0
	v_addc_co_u32_e32 v77, vcc, 0, v85, vcc
	v_add_co_u32_e32 v80, vcc, s33, v84
	s_nop 1
	v_addc_co_u32_e32 v81, vcc, 0, v85, vcc
	s_waitcnt lgkmcnt(3)
	v_mfma_f32_16x16x32_bf16 v[92:95], v[194:197], v[152:155], v[210:213]
	s_waitcnt lgkmcnt(2)
	v_mfma_f32_16x16x32_bf16 v[88:91], v[198:201], v[152:155], v[214:217]
	s_waitcnt lgkmcnt(1)
	v_mfma_f32_16x16x32_bf16 v[52:55], v[202:205], v[152:155], v[52:55]
	s_waitcnt lgkmcnt(0)
	v_mfma_f32_16x16x32_bf16 v[48:51], v[206:209], v[152:155], v[48:51]
	v_add_co_u32_e32 v84, vcc, s59, v84
	s_nop 1
	v_addc_co_u32_e32 v85, vcc, 0, v85, vcc
	v_mfma_f32_16x16x32_bf16 v[44:47], v[194:197], v[156:159], v[44:47]
	v_mfma_f32_16x16x32_bf16 v[40:43], v[198:201], v[156:159], v[40:43]
	v_mfma_f32_16x16x32_bf16 v[36:39], v[202:205], v[156:159], v[36:39]
	v_mfma_f32_16x16x32_bf16 v[32:35], v[206:209], v[156:159], v[32:35]
	v_mfma_f32_16x16x32_bf16 v[28:31], v[194:197], v[160:163], v[28:31]
	v_mfma_f32_16x16x32_bf16 v[24:27], v[198:201], v[160:163], v[24:27]
	v_mfma_f32_16x16x32_bf16 v[20:23], v[202:205], v[160:163], v[20:23]
	v_mfma_f32_16x16x32_bf16 v[16:19], v[206:209], v[160:163], v[16:19]
	v_mfma_f32_16x16x32_bf16 v[12:15], v[194:197], v[190:193], v[12:15]
	v_mfma_f32_16x16x32_bf16 v[8:11], v[198:201], v[190:193], v[8:11]
	v_mfma_f32_16x16x32_bf16 v[4:7], v[202:205], v[190:193], v[4:7]
	v_mfma_f32_16x16x32_bf16 v[0:3], v[206:209], v[190:193], v[0:3]
	s_mov_b32 s1, s0
	s_waitcnt lgkmcnt(0)
	s_mul_i32 s0, s69, 0x12000
	v_readlane_b32 s16, v250, 25
	s_add_u32 s24, s16, s0
	v_readlane_b32 s0, v251, 5
	v_lshlrev_b32_e32 v114, 6, v102
	v_readlane_b32 s17, v250, 26
	s_waitcnt vmcnt(5)
	v_add_u32_e32 v64, s0, v108
	v_readlane_b32 s0, v251, 6
	v_add_u32_e32 v56, 0xffffe000, v64
	v_or_b32_e32 v62, v64, v107
	v_or_b32_e32 v65, s0, v114
	v_lshrrev_b32_e32 v56, 10, v56
	s_movk_i32 s0, 0x1800
	v_mad_u32_u24 v56, v56, s0, s0
	v_cmp_lt_i32_e32 vcc, s13, v62
	s_addc_u32 s25, s17, 0
	v_lshlrev_b32_e32 v115, 2, v97
	v_cndmask_b32_e32 v56, 0, v56, vcc
	s_add_u32 s40, s24, 0x2000
	v_or_b32_e32 v58, v65, v115
	v_ashrrev_i32_e32 v57, 31, v56
	s_addc_u32 s41, s25, 0
	s_waitcnt vmcnt(4)
	v_lshlrev_b64 v[74:75], 2, v[56:57]
	v_ashrrev_i32_e32 v59, 31, v58
	v_ashrrev_i32_e32 v63, 31, v62
	v_lshl_add_u64 v[56:57], s[40:41], 0, v[74:75]
	v_lshlrev_b64 v[60:61], 2, v[58:59]
	v_readlane_b32 s0, v250, 15
	s_waitcnt vmcnt(1)
	v_lshl_add_u64 v[82:83], v[56:57], 0, v[60:61]
	v_lshlrev_b64 v[56:57], 12, v[62:63]
	v_readlane_b32 s1, v250, 16
	v_readlane_b32 s16, v250, 21
	v_lshlrev_b64 v[78:79], 11, v[62:63]
	v_lshl_add_u64 v[56:57], s[0:1], 0, v[56:57]
	s_waitcnt vmcnt(0)
	v_lshl_add_u64 v[84:85], v[56:57], 0, v[60:61]
	global_load_dwordx4 v[116:119], v[82:83], off
	global_load_dwordx4 v[120:123], v[82:83], off offset:64
	global_load_dwordx4 v[124:127], v[82:83], off offset:128
	global_load_dwordx4 v[132:135], v[82:83], off offset:192
	global_load_dwordx4 v[190:193], v[84:85], off
	global_load_dwordx4 v[194:197], v[84:85], off offset:64
	global_load_dwordx4 v[198:201], v[84:85], off offset:128
	global_load_dwordx4 v[202:205], v[84:85], off offset:192
	v_add_co_u32_e32 v164, vcc, 0x10000, v84
	s_nop 1
	v_addc_co_u32_e32 v165, vcc, 0, v85, vcc
	v_add_co_u32_e32 v222, vcc, 0x20000, v84
	s_nop 1
	v_addc_co_u32_e32 v223, vcc, 0, v85, vcc
	v_add_co_u32_e32 v224, vcc, 0x30000, v84
	s_nop 1
	v_addc_co_u32_e32 v225, vcc, 0, v85, vcc
	global_load_dwordx4 v[206:209], v[164:165], off
	global_load_dwordx4 v[210:213], v[164:165], off offset:64
	global_load_dwordx4 v[214:217], v[164:165], off offset:128
	global_load_dwordx4 v[218:221], v[164:165], off offset:192
	s_lshl_b32 s0, s69, 12
	v_readlane_b32 s68, v250, 41
	v_readlane_b32 s72, v250, 45
	v_readlane_b32 s73, v250, 46
	s_add_u32 s0, s72, s0
	s_addc_u32 s1, s73, 0
	s_add_u32 s42, s24, 0x4000
	s_addc_u32 s43, s25, 0
	v_lshl_add_u64 v[74:75], s[42:43], 0, v[74:75]
	v_lshl_add_u64 v[56:57], s[0:1], 0, v[60:61]
	v_lshl_add_u64 v[86:87], v[74:75], 0, v[60:61]
	v_readlane_b32 s17, v250, 22
	v_readlane_b32 s69, v250, 42
	v_readlane_b32 s69, v254, 49
	v_lshl_add_u64 v[78:79], s[16:17], 0, v[78:79]
	s_mul_i32 s24, s69, 0x140000
	s_add_u32 s24, s86, s24
	v_lshrrev_b32_e32 v65, 6, v65
	s_mov_b32 s16, 0xa000
	s_addc_u32 s25, s87, 0
	s_add_u32 s26, s24, 0xaf1a000
	s_addc_u32 s27, s25, 0
	v_cmp_eq_u32_e64 s[36:37], 0, v97
	v_readlane_b32 s70, v250, 43
	v_readlane_b32 s71, v250, 44
	v_readlane_b32 s74, v250, 47
	v_readlane_b32 s75, v250, 48
	v_readlane_b32 s76, v250, 49
	v_readlane_b32 s77, v250, 50
	v_readlane_b32 s78, v250, 51
	v_readlane_b32 s79, v250, 52
	v_readlane_b32 s80, v250, 53
	v_readlane_b32 s81, v250, 54
	v_readlane_b32 s82, v250, 55
	v_readlane_b32 s83, v250, 56
	s_waitcnt vmcnt(4)
	v_pk_fma_f32 v[68:69], v[94:95], v[118:119], v[192:193]
	v_pk_fma_f32 v[66:67], v[92:93], v[116:117], v[190:191]
	global_store_dwordx4 v[84:85], v[66:69], off
	global_load_dwordx4 v[136:139], v[56:57], off
	global_load_dwordx4 v[140:143], v[56:57], off offset:64
	global_load_dwordx4 v[144:147], v[56:57], off offset:128
	global_load_dwordx4 v[148:151], v[56:57], off offset:192
	global_load_dwordx4 v[152:155], v[86:87], off
	global_load_dwordx4 v[156:159], v[86:87], off offset:64
	global_load_dwordx4 v[160:163], v[86:87], off offset:128
	global_load_dwordx4 v[180:183], v[86:87], off offset:192
	v_lshl_add_u64 v[92:93], v[58:59], 1, v[78:79]
	s_waitcnt vmcnt(0)
	v_pk_mul_f32 v[72:73], v[68:69], v[138:139]
	v_pk_mul_f32 v[70:71], v[66:67], v[136:137]
	s_waitcnt vmcnt(0)
	v_pk_add_f32 v[76:77], v[154:155], 1.0 op_sel_hi:[1,0]
	v_pk_add_f32 v[74:75], v[152:153], 1.0 op_sel_hi:[1,0]
	v_pk_mul_f32 v[72:73], v[72:73], v[76:77]
	v_pk_mul_f32 v[70:71], v[70:71], v[74:75]
	v_and_b32_sdwa v77, v71, v170 dst_sel:DWORD dst_unused:UNUSED_PAD src0_sel:WORD_1 src1_sel:DWORD
	v_and_b32_sdwa v75, v70, v170 dst_sel:DWORD dst_unused:UNUSED_PAD src0_sel:WORD_1 src1_sel:DWORD
	v_add3_u32 v71, v71, v77, s56
	v_add3_u32 v70, v70, v75, s56
	v_and_b32_e32 v74, 0xffff0000, v71
	v_cvt_pk_bf16_f32 v71, v72, v73
	v_or_b32_sdwa v70, v74, v70 dst_sel:DWORD dst_unused:UNUSED_PAD src0_sel:DWORD src1_sel:WORD_1
	global_store_dwordx2 v[92:93], v[70:71], off
	s_nop 0
	s_waitcnt vmcnt(0)
	v_pk_fma_f32 v[72:73], v[90:91], v[122:123], v[196:197]
	v_pk_fma_f32 v[70:71], v[88:89], v[120:121], v[194:195]
	global_store_dwordx4 v[84:85], v[70:73], off offset:64
	v_pk_mul_f32 v[76:77], v[72:73], v[142:143]
	v_pk_mul_f32 v[74:75], v[70:71], v[140:141]
	v_pk_add_f32 v[80:81], v[158:159], 1.0 op_sel_hi:[1,0]
	v_pk_add_f32 v[78:79], v[156:157], 1.0 op_sel_hi:[1,0]
	v_pk_mul_f32 v[76:77], v[76:77], v[80:81]
	v_pk_mul_f32 v[74:75], v[74:75], v[78:79]
	v_and_b32_sdwa v81, v75, v170 dst_sel:DWORD dst_unused:UNUSED_PAD src0_sel:WORD_1 src1_sel:DWORD
	v_and_b32_sdwa v79, v74, v170 dst_sel:DWORD dst_unused:UNUSED_PAD src0_sel:WORD_1 src1_sel:DWORD
	v_add3_u32 v75, v75, v81, s56
	v_add3_u32 v74, v74, v79, s56
	v_and_b32_e32 v78, 0xffff0000, v75
	v_cvt_pk_bf16_f32 v75, v76, v77
	v_or_b32_sdwa v74, v78, v74 dst_sel:DWORD dst_unused:UNUSED_PAD src0_sel:DWORD src1_sel:WORD_1
	global_store_dwordx2 v[92:93], v[74:75], off offset:32
	s_nop 0
	v_pk_fma_f32 v[54:55], v[54:55], v[126:127], v[200:201]
	v_pk_fma_f32 v[52:53], v[52:53], v[124:125], v[198:199]
	global_store_dwordx4 v[84:85], v[52:55], off offset:128
	v_pk_mul_f32 v[76:77], v[54:55], v[146:147]
	v_pk_mul_f32 v[74:75], v[52:53], v[144:145]
	v_pk_add_f32 v[80:81], v[162:163], 1.0 op_sel_hi:[1,0]
	v_pk_add_f32 v[78:79], v[160:161], 1.0 op_sel_hi:[1,0]
	v_pk_mul_f32 v[76:77], v[76:77], v[80:81]
	v_pk_mul_f32 v[74:75], v[74:75], v[78:79]
	v_and_b32_sdwa v81, v75, v170 dst_sel:DWORD dst_unused:UNUSED_PAD src0_sel:WORD_1 src1_sel:DWORD
	v_and_b32_sdwa v79, v74, v170 dst_sel:DWORD dst_unused:UNUSED_PAD src0_sel:WORD_1 src1_sel:DWORD
	v_add3_u32 v75, v75, v81, s56
	v_add3_u32 v74, v74, v79, s56
	v_and_b32_e32 v78, 0xffff0000, v75
	v_cvt_pk_bf16_f32 v75, v76, v77
	v_or_b32_sdwa v74, v78, v74 dst_sel:DWORD dst_unused:UNUSED_PAD src0_sel:DWORD src1_sel:WORD_1
	global_store_dwordx2 v[92:93], v[74:75], off offset:64
	s_nop 0
	v_pk_fma_f32 v[76:77], v[50:51], v[134:135], v[204:205]
	v_pk_fma_f32 v[74:75], v[48:49], v[132:133], v[202:203]
	global_store_dwordx4 v[84:85], v[74:77], off offset:192
	s_nop 0
	v_mbcnt_lo_u32_b32 v48, -1, 0
	v_mbcnt_hi_u32_b32 v48, -1, v48
	v_and_b32_e32 v50, 64, v48
	v_xor_b32_e32 v49, 16, v48
	v_add_u32_e32 v50, 64, v50
	v_xor_b32_e32 v51, 32, v48
	v_cmp_lt_i32_e32 vcc, v49, v50
	s_nop 1
	v_cndmask_b32_e32 v49, v48, v49, vcc
	v_cmp_lt_i32_e32 vcc, v51, v50
	v_lshlrev_b32_e32 v105, 2, v49
	s_nop 0
	v_cndmask_b32_e32 v50, v48, v51, vcc
	v_lshlrev_b32_e32 v104, 2, v50
	v_mul_f32_e32 v50, v67, v67
	v_mul_f32_e32 v51, v71, v71
	v_fmac_f32_e32 v50, v66, v66
	v_fmac_f32_e32 v51, v70, v70
	v_fmac_f32_e32 v50, v68, v68
	v_fmac_f32_e32 v51, v72, v72
	v_fmac_f32_e32 v50, v69, v69
	v_fmac_f32_e32 v51, v73, v73
	v_add_f32_e32 v50, v50, v51
	v_mul_f32_e32 v51, v53, v53
	v_fmac_f32_e32 v51, v52, v52
	v_fmac_f32_e32 v51, v54, v54
	v_fmac_f32_e32 v51, v55, v55
	v_add_f32_e32 v50, v50, v51
	v_mul_f32_e32 v51, v75, v75
	v_fmac_f32_e32 v51, v74, v74
	v_fmac_f32_e32 v51, v76, v76
	v_fmac_f32_e32 v51, v77, v77
	v_add_f32_e32 v50, v50, v51
	ds_bpermute_b32 v51, v105, v50
	v_mul_lo_u32 v48, v65, s16
	v_ashrrev_i32_e32 v49, 31, v48
	v_lshl_add_u64 v[48:49], s[26:27], 0, v[48:49]
	v_lshl_add_u64 v[48:49], v[62:63], 2, v[48:49]
	s_waitcnt lgkmcnt(0)
	v_add_f32_e32 v50, v50, v51
	ds_bpermute_b32 v51, v104, v50
	v_pk_mul_f32 v[52:53], v[76:77], v[150:151]
	v_pk_mul_f32 v[54:55], v[74:75], v[148:149]
	v_pk_add_f32 v[66:67], v[182:183], 1.0 op_sel_hi:[1,0]
	v_pk_add_f32 v[68:69], v[180:181], 1.0 op_sel_hi:[1,0]
	v_pk_mul_f32 v[52:53], v[52:53], v[66:67]
	v_pk_mul_f32 v[54:55], v[54:55], v[68:69]
	v_cvt_pk_bf16_f32 v53, v52, v53
	v_cvt_pk_bf16_f32 v52, v54, v55
	global_store_dwordx2 v[92:93], v[52:53], off offset:96
	s_and_saveexec_b64 s[24:25], s[36:37]
	s_cbranch_execz .LBB0_95
	s_waitcnt lgkmcnt(0)
	v_add_f32_e32 v50, v50, v51
	global_store_dword v[48:49], v50, off

.Ltail106:
	s_add_i32 s29, s44, 2
	ds_read_b128 v[136:139], v111 offset:16384
	ds_read_b128 v[140:143], v111 offset:18432
	ds_read_b128 v[144:147], v111 offset:20480
	ds_read_b128 v[148:151], v111 offset:22528
	ds_read_b128 v[116:119], v110
	s_add_i32 s44, s44, 4
	ds_read_b128 v[120:123], v110 offset:2048
	s_min_u32 s44, s44, 15
	s_lshl_b32 s92, s44, 7
	ds_read_b128 v[124:127], v110 offset:4096
	ds_read_b128 v[194:197], v113 offset:16384
	ds_read_b128 v[198:201], v113 offset:18432
	ds_read_b128 v[202:205], v113 offset:20480
	ds_read_b128 v[206:209], v113 offset:22528
	v_lshl_add_u64 v[164:165], v[100:101], 0, s[92:93]
	ds_read_b128 v[132:135], v110 offset:6144
	ds_read_b128 v[152:155], v112
	ds_read_b128 v[156:159], v112 offset:2048
	ds_read_b128 v[160:163], v112 offset:4096
	ds_read_b128 v[190:193], v112 offset:6144
	s_waitcnt lgkmcnt(11)
	v_mfma_f32_16x16x32_bf16 v[92:95], v[136:139], v[116:119], v[92:95]
	v_mfma_f32_16x16x32_bf16 v[88:91], v[140:143], v[116:119], v[88:91]
	v_mfma_f32_16x16x32_bf16 v[56:59], v[144:147], v[116:119], v[56:59]
	v_mfma_f32_16x16x32_bf16 v[48:51], v[148:151], v[116:119], v[48:51]
	s_waitcnt vmcnt(7)
	ds_write_b128 v109, v[52:55] offset:32768
	v_add_co_u32_e32 v52, vcc, s11, v164
	s_waitcnt lgkmcnt(11)
	v_mfma_f32_16x16x32_bf16 v[44:47], v[136:139], v[120:123], v[44:47]
	v_addc_co_u32_e32 v53, vcc, 0, v165, vcc
	v_mfma_f32_16x16x32_bf16 v[40:43], v[140:143], v[120:123], v[40:43]
	v_mfma_f32_16x16x32_bf16 v[36:39], v[144:147], v[120:123], v[36:39]
	v_mfma_f32_16x16x32_bf16 v[32:35], v[148:151], v[120:123], v[32:35]
	v_add_co_u32_e32 v52, vcc, s33, v164
	s_waitcnt vmcnt(6)
	ds_write_b128 v109, v[60:63] offset:36864
	s_nop 0
	v_addc_co_u32_e32 v53, vcc, 0, v165, vcc
	s_waitcnt lgkmcnt(11)
	v_mfma_f32_16x16x32_bf16 v[28:31], v[136:139], v[124:127], v[28:31]
	v_mfma_f32_16x16x32_bf16 v[24:27], v[140:143], v[124:127], v[24:27]
	v_mfma_f32_16x16x32_bf16 v[20:23], v[144:147], v[124:127], v[20:23]
	v_mfma_f32_16x16x32_bf16 v[16:19], v[148:151], v[124:127], v[16:19]
	v_add_co_u32_e32 v52, vcc, s59, v164
	s_waitcnt vmcnt(5)
	ds_write_b128 v109, v[64:67] offset:40960
	s_nop 0
	v_addc_co_u32_e32 v53, vcc, 0, v165, vcc
	v_lshl_add_u64 v[64:65], v[102:103], 0, s[92:93]
	v_add_co_u32_e32 v66, vcc, s11, v64
	s_waitcnt lgkmcnt(7)
	v_mfma_f32_16x16x32_bf16 v[12:15], v[136:139], v[132:135], v[12:15]
	v_addc_co_u32_e32 v67, vcc, 0, v65, vcc
	v_mfma_f32_16x16x32_bf16 v[8:11], v[140:143], v[132:135], v[8:11]
	v_mfma_f32_16x16x32_bf16 v[4:7], v[144:147], v[132:135], v[4:7]
	v_mfma_f32_16x16x32_bf16 v[0:3], v[148:151], v[132:135], v[0:3]
	s_waitcnt vmcnt(4)
	ds_write_b128 v109, v[72:75] offset:45056
	s_waitcnt lgkmcnt(7)
	v_mfma_f32_16x16x32_bf16 v[52:55], v[194:197], v[152:155], v[92:95]
	v_mfma_f32_16x16x32_bf16 v[60:63], v[198:201], v[152:155], v[88:91]
	v_mfma_f32_16x16x32_bf16 v[56:59], v[202:205], v[152:155], v[56:59]
	v_mfma_f32_16x16x32_bf16 v[48:51], v[206:209], v[152:155], v[48:51]
	s_waitcnt vmcnt(3)
	ds_write_b128 v109, v[68:71] offset:49152
	s_waitcnt lgkmcnt(7)
	v_mfma_f32_16x16x32_bf16 v[44:47], v[194:197], v[156:159], v[44:47]
	v_mfma_f32_16x16x32_bf16 v[40:43], v[198:201], v[156:159], v[40:43]
	v_mfma_f32_16x16x32_bf16 v[36:39], v[202:205], v[156:159], v[36:39]
	v_mfma_f32_16x16x32_bf16 v[32:35], v[206:209], v[156:159], v[32:35]
	v_add_co_u32_e32 v66, vcc, s33, v64
	s_waitcnt vmcnt(2)
	ds_write_b128 v109, v[76:79] offset:53248
	v_addc_co_u32_e32 v67, vcc, 0, v65, vcc
	v_add_co_u32_e32 v64, vcc, s59, v64
	s_waitcnt lgkmcnt(7)
	v_mfma_f32_16x16x32_bf16 v[28:31], v[194:197], v[160:163], v[28:31]
	v_addc_co_u32_e32 v65, vcc, 0, v65, vcc
	v_mfma_f32_16x16x32_bf16 v[24:27], v[198:201], v[160:163], v[24:27]
	v_mfma_f32_16x16x32_bf16 v[20:23], v[202:205], v[160:163], v[20:23]
	v_mfma_f32_16x16x32_bf16 v[16:19], v[206:209], v[160:163], v[16:19]
	s_waitcnt vmcnt(1)
	ds_write_b128 v109, v[80:83] offset:57344
	s_waitcnt lgkmcnt(7)
	v_mfma_f32_16x16x32_bf16 v[12:15], v[194:197], v[190:193], v[12:15]
	v_mfma_f32_16x16x32_bf16 v[8:11], v[198:201], v[190:193], v[8:11]
	v_mfma_f32_16x16x32_bf16 v[4:7], v[202:205], v[190:193], v[4:7]
	v_mfma_f32_16x16x32_bf16 v[0:3], v[206:209], v[190:193], v[0:3]
	s_waitcnt vmcnt(0)
	ds_write_b128 v109, v[84:87] offset:61440
	s_waitcnt lgkmcnt(0)
	s_barrier
	ds_read_b128 v[84:87], v111 offset:51200
	ds_read_b128 v[80:83], v111 offset:49152
	ds_read_b128 v[88:91], v111 offset:53248
	ds_read_b128 v[92:95], v111 offset:55296
	ds_read_b128 v[64:67], v110 offset:32768
	s_min_u32 s44, s29, 12
	s_lshl_b32 s92, s44, 7
	ds_read_b128 v[68:71], v110 offset:34816
	v_lshl_add_u64 v[164:165], v[100:101], 0, s[92:93]
	ds_read_b128 v[72:75], v110 offset:36864
	ds_read_b128 v[76:79], v110 offset:38912
	ds_read_b128 v[152:155], v112 offset:32768
	ds_read_b128 v[156:159], v112 offset:34816
	ds_read_b128 v[160:163], v112 offset:36864
	ds_read_b128 v[190:193], v112 offset:38912
	ds_read_b128 v[194:197], v113 offset:49152
	ds_read_b128 v[198:201], v113 offset:51200
	ds_read_b128 v[202:205], v113 offset:53248
	ds_read_b128 v[206:209], v113 offset:55296
	s_waitcnt lgkmcnt(11)
	v_mfma_f32_16x16x32_bf16 v[214:217], v[84:87], v[64:67], v[60:63]
	v_mfma_f32_16x16x32_bf16 v[210:213], v[80:83], v[64:67], v[52:55]
	s_nop 1
	v_add_co_u32_e32 v60, vcc, s11, v164
	s_nop 1
	v_addc_co_u32_e32 v61, vcc, 0, v165, vcc
	v_mfma_f32_16x16x32_bf16 v[56:59], v[88:91], v[64:67], v[56:59]
	v_mfma_f32_16x16x32_bf16 v[48:51], v[92:95], v[64:67], v[48:51]
	v_add_co_u32_e32 v64, vcc, s33, v164
	s_nop 0
	s_nop 0
	v_addc_co_u32_e32 v65, vcc, 0, v165, vcc
	s_waitcnt lgkmcnt(10)
	v_mfma_f32_16x16x32_bf16 v[44:47], v[80:83], v[68:71], v[44:47]
	v_mfma_f32_16x16x32_bf16 v[40:43], v[84:87], v[68:71], v[40:43]
	v_mfma_f32_16x16x32_bf16 v[36:39], v[88:91], v[68:71], v[36:39]
	v_mfma_f32_16x16x32_bf16 v[32:35], v[92:95], v[68:71], v[32:35]
	v_add_co_u32_e32 v68, vcc, s59, v164
	s_waitcnt lgkmcnt(9)
	v_mfma_f32_16x16x32_bf16 v[28:31], v[80:83], v[72:75], v[28:31]
	v_addc_co_u32_e32 v69, vcc, 0, v165, vcc
	v_mfma_f32_16x16x32_bf16 v[24:27], v[84:87], v[72:75], v[24:27]
	v_mfma_f32_16x16x32_bf16 v[20:23], v[88:91], v[72:75], v[20:23]
	v_mfma_f32_16x16x32_bf16 v[16:19], v[92:95], v[72:75], v[16:19]
	s_waitcnt lgkmcnt(8)
	v_mfma_f32_16x16x32_bf16 v[8:11], v[84:87], v[76:79], v[8:11]
	v_lshl_add_u64 v[84:85], v[102:103], 0, s[92:93]
	v_mfma_f32_16x16x32_bf16 v[12:15], v[80:83], v[76:79], v[12:15]
	v_mfma_f32_16x16x32_bf16 v[4:7], v[88:91], v[76:79], v[4:7]
	v_mfma_f32_16x16x32_bf16 v[0:3], v[92:95], v[76:79], v[0:3]
	v_add_co_u32_e32 v76, vcc, s11, v84
	s_nop 0
	s_nop 0
	v_addc_co_u32_e32 v77, vcc, 0, v85, vcc
	v_add_co_u32_e32 v80, vcc, s33, v84
	s_nop 1
	v_addc_co_u32_e32 v81, vcc, 0, v85, vcc
	s_waitcnt lgkmcnt(3)
	v_mfma_f32_16x16x32_bf16 v[92:95], v[194:197], v[152:155], v[210:213]
	s_waitcnt lgkmcnt(2)
	v_mfma_f32_16x16x32_bf16 v[88:91], v[198:201], v[152:155], v[214:217]
	s_waitcnt lgkmcnt(1)
	v_mfma_f32_16x16x32_bf16 v[56:59], v[202:205], v[152:155], v[56:59]
	s_waitcnt lgkmcnt(0)
	v_mfma_f32_16x16x32_bf16 v[48:51], v[206:209], v[152:155], v[48:51]
	v_add_co_u32_e32 v84, vcc, s59, v84
	s_nop 1
	v_addc_co_u32_e32 v85, vcc, 0, v85, vcc
	v_mfma_f32_16x16x32_bf16 v[44:47], v[194:197], v[156:159], v[44:47]
	v_mfma_f32_16x16x32_bf16 v[40:43], v[198:201], v[156:159], v[40:43]
	v_mfma_f32_16x16x32_bf16 v[36:39], v[202:205], v[156:159], v[36:39]
	v_mfma_f32_16x16x32_bf16 v[32:35], v[206:209], v[156:159], v[32:35]
	v_mfma_f32_16x16x32_bf16 v[28:31], v[194:197], v[160:163], v[28:31]
	v_mfma_f32_16x16x32_bf16 v[24:27], v[198:201], v[160:163], v[24:27]
	v_mfma_f32_16x16x32_bf16 v[20:23], v[202:205], v[160:163], v[20:23]
	v_mfma_f32_16x16x32_bf16 v[16:19], v[206:209], v[160:163], v[16:19]
	v_mfma_f32_16x16x32_bf16 v[12:15], v[194:197], v[190:193], v[12:15]
	v_mfma_f32_16x16x32_bf16 v[8:11], v[198:201], v[190:193], v[8:11]
	v_mfma_f32_16x16x32_bf16 v[4:7], v[202:205], v[190:193], v[4:7]
	v_mfma_f32_16x16x32_bf16 v[0:3], v[206:209], v[190:193], v[0:3]
	s_mov_b32 s44, s29
	s_waitcnt lgkmcnt(0)
	s_waitcnt vmcnt(5)
	v_add_u32_e32 v64, s24, v108
	v_add_u32_e32 v52, 0xffffe000, v64
	v_or_b32_e32 v62, v64, v107
	v_lshrrev_b32_e32 v52, 10, v52
	s_movk_i32 s16, 0x1800
	v_mad_u32_u24 v52, v52, s16, s16
	v_cmp_lt_i32_e32 vcc, s13, v62
	v_or_b32_e32 v65, s25, v114
	v_or_b32_e32 v54, v65, v115
	v_cndmask_b32_e32 v52, 0, v52, vcc
	v_ashrrev_i32_e32 v53, 31, v52
	s_waitcnt vmcnt(4)
	v_lshlrev_b64 v[74:75], 2, v[52:53]
	v_ashrrev_i32_e32 v55, 31, v54
	v_ashrrev_i32_e32 v63, 31, v62
	v_lshl_add_u64 v[52:53], s[40:41], 0, v[74:75]
	v_lshlrev_b64 v[60:61], 2, v[54:55]
	v_readlane_b32 s16, v250, 15
	s_waitcnt vmcnt(1)
	v_lshl_add_u64 v[82:83], v[52:53], 0, v[60:61]
	v_lshlrev_b64 v[52:53], 12, v[62:63]
	v_readlane_b32 s17, v250, 16
	v_lshl_add_u64 v[74:75], s[42:43], 0, v[74:75]
	s_waitcnt vmcnt(0)
	v_lshl_add_u64 v[86:87], v[74:75], 0, v[60:61]
	v_lshl_add_u64 v[52:53], s[16:17], 0, v[52:53]
	v_lshl_add_u64 v[84:85], v[52:53], 0, v[60:61]
	global_load_dwordx4 v[66:69], v[82:83], off
	global_load_dwordx4 v[70:73], v[84:85], off
	v_lshl_add_u64 v[52:53], s[0:1], 0, v[60:61]
	v_readlane_b32 s16, v250, 21
	v_lshlrev_b64 v[78:79], 11, v[62:63]
	v_readlane_b32 s17, v250, 22
	s_waitcnt vmcnt(0)
	v_pk_fma_f32 v[68:69], v[94:95], v[68:69], v[72:73]
	v_pk_fma_f32 v[66:67], v[92:93], v[66:67], v[70:71]
	global_store_dwordx4 v[84:85], v[66:69], off
	global_load_dwordx4 v[70:73], v[52:53], off
	global_load_dwordx4 v[74:77], v[86:87], off
	v_lshl_add_u64 v[78:79], s[16:17], 0, v[78:79]
	v_lshl_add_u64 v[92:93], v[54:55], 1, v[78:79]
	s_mov_b32 s16, 0xa000
	s_waitcnt vmcnt(1)
	v_pk_mul_f32 v[72:73], v[68:69], v[72:73]
	v_pk_mul_f32 v[70:71], v[66:67], v[70:71]
	s_waitcnt vmcnt(0)
	v_pk_add_f32 v[76:77], v[76:77], 1.0 op_sel_hi:[1,0]
	v_pk_add_f32 v[74:75], v[74:75], 1.0 op_sel_hi:[1,0]
	v_pk_mul_f32 v[72:73], v[72:73], v[76:77]
	v_pk_mul_f32 v[70:71], v[70:71], v[74:75]
	v_and_b32_sdwa v77, v71, v170 dst_sel:DWORD dst_unused:UNUSED_PAD src0_sel:WORD_1 src1_sel:DWORD
	v_and_b32_sdwa v75, v70, v170 dst_sel:DWORD dst_unused:UNUSED_PAD src0_sel:WORD_1 src1_sel:DWORD
	v_add3_u32 v71, v71, v77, s56
	v_add3_u32 v70, v70, v75, s56
	v_and_b32_e32 v74, 0xffff0000, v71
	v_cvt_pk_bf16_f32 v71, v72, v73
	v_or_b32_sdwa v70, v74, v70 dst_sel:DWORD dst_unused:UNUSED_PAD src0_sel:DWORD src1_sel:WORD_1
	global_store_dwordx2 v[92:93], v[70:71], off
	global_load_dwordx4 v[70:73], v[82:83], off offset:64
	s_nop 0
	global_load_dwordx4 v[74:77], v[84:85], off offset:64
	s_waitcnt vmcnt(0)
	v_pk_fma_f32 v[72:73], v[90:91], v[72:73], v[76:77]
	v_pk_fma_f32 v[70:71], v[88:89], v[70:71], v[74:75]
	global_store_dwordx4 v[84:85], v[70:73], off offset:64
	global_load_dwordx4 v[74:77], v[52:53], off offset:64
	global_load_dwordx4 v[78:81], v[86:87], off offset:64
	s_waitcnt vmcnt(1)
	v_pk_mul_f32 v[76:77], v[72:73], v[76:77]
	v_pk_mul_f32 v[74:75], v[70:71], v[74:75]
	s_waitcnt vmcnt(0)
	v_pk_add_f32 v[80:81], v[80:81], 1.0 op_sel_hi:[1,0]
	v_pk_add_f32 v[78:79], v[78:79], 1.0 op_sel_hi:[1,0]
	v_pk_mul_f32 v[76:77], v[76:77], v[80:81]
	v_pk_mul_f32 v[74:75], v[74:75], v[78:79]
	v_and_b32_sdwa v81, v75, v170 dst_sel:DWORD dst_unused:UNUSED_PAD src0_sel:WORD_1 src1_sel:DWORD
	v_and_b32_sdwa v79, v74, v170 dst_sel:DWORD dst_unused:UNUSED_PAD src0_sel:WORD_1 src1_sel:DWORD
	v_add3_u32 v75, v75, v81, s56
	v_add3_u32 v74, v74, v79, s56
	v_and_b32_e32 v78, 0xffff0000, v75
	v_cvt_pk_bf16_f32 v75, v76, v77
	v_or_b32_sdwa v74, v78, v74 dst_sel:DWORD dst_unused:UNUSED_PAD src0_sel:DWORD src1_sel:WORD_1
	global_store_dwordx2 v[92:93], v[74:75], off offset:32
	global_load_dwordx4 v[74:77], v[82:83], off offset:128
	s_nop 0
	global_load_dwordx4 v[78:81], v[84:85], off offset:128
	s_waitcnt vmcnt(0)
	v_pk_fma_f32 v[58:59], v[58:59], v[76:77], v[80:81]
	v_pk_fma_f32 v[56:57], v[56:57], v[74:75], v[78:79]
	global_store_dwordx4 v[84:85], v[56:59], off offset:128
	global_load_dwordx4 v[74:77], v[52:53], off offset:128
	global_load_dwordx4 v[78:81], v[86:87], off offset:128
	s_waitcnt vmcnt(1)
	v_pk_mul_f32 v[76:77], v[58:59], v[76:77]
	v_pk_mul_f32 v[74:75], v[56:57], v[74:75]
	s_waitcnt vmcnt(0)
	v_pk_add_f32 v[80:81], v[80:81], 1.0 op_sel_hi:[1,0]
	v_pk_add_f32 v[78:79], v[78:79], 1.0 op_sel_hi:[1,0]
	v_pk_mul_f32 v[76:77], v[76:77], v[80:81]
	v_pk_mul_f32 v[74:75], v[74:75], v[78:79]
	v_and_b32_sdwa v81, v75, v170 dst_sel:DWORD dst_unused:UNUSED_PAD src0_sel:WORD_1 src1_sel:DWORD
	v_and_b32_sdwa v79, v74, v170 dst_sel:DWORD dst_unused:UNUSED_PAD src0_sel:WORD_1 src1_sel:DWORD
	v_add3_u32 v75, v75, v81, s56
	v_add3_u32 v74, v74, v79, s56
	v_and_b32_e32 v78, 0xffff0000, v75
	v_cvt_pk_bf16_f32 v75, v76, v77
	v_or_b32_sdwa v74, v78, v74 dst_sel:DWORD dst_unused:UNUSED_PAD src0_sel:DWORD src1_sel:WORD_1
	global_store_dwordx2 v[92:93], v[74:75], off offset:64
	global_load_dwordx4 v[74:77], v[82:83], off offset:192
	s_nop 0
	global_load_dwordx4 v[78:81], v[84:85], off offset:192
	s_waitcnt vmcnt(0)
	v_pk_fma_f32 v[76:77], v[50:51], v[76:77], v[80:81]
	v_pk_fma_f32 v[74:75], v[48:49], v[74:75], v[78:79]
	global_store_dwordx4 v[84:85], v[74:77], off offset:192
	global_load_dwordx4 v[78:81], v[52:53], off offset:192
	s_nop 0
	global_load_dwordx4 v[82:85], v[86:87], off offset:192
	v_mul_f32_e32 v48, v67, v67
	v_mul_f32_e32 v49, v71, v71
	v_fmac_f32_e32 v48, v66, v66
	v_fmac_f32_e32 v49, v70, v70
	v_fmac_f32_e32 v48, v68, v68
	v_fmac_f32_e32 v49, v72, v72
	v_fmac_f32_e32 v48, v69, v69
	v_fmac_f32_e32 v49, v73, v73
	v_add_f32_e32 v48, v48, v49
	v_mul_f32_e32 v49, v57, v57
	v_fmac_f32_e32 v49, v56, v56
	v_fmac_f32_e32 v49, v58, v58
	v_fmac_f32_e32 v49, v59, v59
	v_add_f32_e32 v48, v48, v49
	v_mul_f32_e32 v49, v75, v75
	v_fmac_f32_e32 v49, v74, v74
	v_fmac_f32_e32 v49, v76, v76
	v_fmac_f32_e32 v49, v77, v77
	v_add_f32_e32 v50, v48, v49
	ds_bpermute_b32 v51, v105, v50
	v_lshrrev_b32_e32 v48, 6, v65
	v_mul_lo_u32 v48, v48, s16
	v_ashrrev_i32_e32 v49, 31, v48
	v_lshl_add_u64 v[48:49], s[26:27], 0, v[48:49]
	s_waitcnt lgkmcnt(0)
	v_add_f32_e32 v50, v50, v51
	ds_bpermute_b32 v51, v104, v50
	v_lshl_add_u64 v[48:49], v[62:63], 2, v[48:49]
	s_waitcnt vmcnt(1)
	v_pk_mul_f32 v[56:57], v[76:77], v[80:81]
	v_pk_mul_f32 v[58:59], v[74:75], v[78:79]
	s_waitcnt vmcnt(0)
	v_pk_add_f32 v[66:67], v[84:85], 1.0 op_sel_hi:[1,0]
	v_pk_add_f32 v[68:69], v[82:83], 1.0 op_sel_hi:[1,0]
	v_pk_mul_f32 v[56:57], v[56:57], v[66:67]
	v_pk_mul_f32 v[58:59], v[58:59], v[68:69]
	v_cvt_pk_bf16_f32 v57, v56, v57
	v_cvt_pk_bf16_f32 v56, v58, v59
	global_store_dwordx2 v[92:93], v[56:57], off offset:96
	s_and_saveexec_b64 s[24:25], s[36:37]
	s_cbranch_execz .LBB0_109
	s_waitcnt lgkmcnt(0)
	v_add_f32_e32 v50, v50, v51
	global_store_dword v[48:49], v50, off

.Ltail119:
	s_add_i32 s2, s3, 2
	v_add_u32_e32 v127, v89, v90
	ds_read_b128 v[100:103], v127 offset:16384
	ds_read_b128 v[106:109], v127 offset:18432
	ds_read_b128 v[110:113], v127 offset:20480
	ds_read_b128 v[114:117], v127 offset:22528
	v_add_u32_e32 v126, v88, v90
	ds_read_b128 v[92:95], v126
	ds_read_b128 v[96:99], v126 offset:2048
	s_add_i32 s3, s3, 4
	s_min_u32 s3, s3, 15
	v_add_u32_e32 v128, v88, v91
	v_add_u32_e32 v130, v89, v91
	s_lshl_b32 s92, s3, 7
	ds_read_b128 v[118:121], v130 offset:18432
	ds_read_b128 v[122:125], v130 offset:20480
	ds_read_b128 v[132:135], v130 offset:22528
	s_waitcnt lgkmcnt(4)
	v_mfma_f32_16x16x32_bf16 v[76:79], v[100:103], v[92:95], v[76:79]
	v_lshl_add_u64 v[44:45], v[80:81], 0, s[92:93]
	v_add_co_u32_e32 v46, vcc, s11, v44
	v_mfma_f32_16x16x32_bf16 v[68:71], v[106:109], v[92:95], v[68:71]
	s_nop 0
	v_addc_co_u32_e32 v47, vcc, 0, v45, vcc
	v_mfma_f32_16x16x32_bf16 v[52:55], v[110:113], v[92:95], v[52:55]
	v_mfma_f32_16x16x32_bf16 v[40:43], v[114:117], v[92:95], v[40:43]
	s_waitcnt lgkmcnt(3)
	v_mfma_f32_16x16x32_bf16 v[92:95], v[100:103], v[96:99], v[36:39]
	s_nop 2
	ds_read_b128 v[36:39], v128
	v_mfma_f32_16x16x32_bf16 v[100:103], v[106:109], v[96:99], v[8:11]
	v_mfma_f32_16x16x32_bf16 v[106:109], v[110:113], v[96:99], v[4:7]
	ds_read_b128 v[110:113], v128 offset:2048
	v_mfma_f32_16x16x32_bf16 v[96:99], v[114:117], v[96:99], v[0:3]
	ds_read_b128 v[114:117], v130 offset:16384
	s_waitcnt vmcnt(0)
	ds_write_b128 v87, v[12:15] offset:53248
	v_add_co_u32_e32 v46, vcc, s33, v44
	s_waitcnt vmcnt(1)
	ds_write_b128 v87, v[16:19] offset:49152
	s_nop 0
	v_addc_co_u32_e32 v47, vcc, 0, v45, vcc
	v_add_co_u32_e32 v44, vcc, s59, v44
	s_nop 0
	s_nop 0
	v_addc_co_u32_e32 v45, vcc, 0, v45, vcc
	s_waitcnt vmcnt(2)
	ds_write_b128 v87, v[20:23] offset:45056
	v_lshl_add_u64 v[44:45], v[82:83], 0, s[92:93]
	s_waitcnt vmcnt(5)
	ds_write_b128 v87, v[28:31] offset:32768
	s_waitcnt lgkmcnt(4)
	v_mfma_f32_16x16x32_bf16 v[0:3], v[114:117], v[36:39], v[76:79]
	v_mfma_f32_16x16x32_bf16 v[4:7], v[118:121], v[36:39], v[68:71]
	v_add_co_u32_e32 v44, vcc, s11, v44
	s_waitcnt vmcnt(4)
	ds_write_b128 v87, v[32:35] offset:36864
	s_nop 0
	v_addc_co_u32_e32 v45, vcc, 0, v45, vcc
	v_mfma_f32_16x16x32_bf16 v[8:11], v[122:125], v[36:39], v[52:55]
	v_mfma_f32_16x16x32_bf16 v[36:39], v[132:135], v[36:39], v[40:43]
	s_waitcnt vmcnt(3)
	ds_write_b128 v87, v[24:27] offset:40960
	v_mfma_f32_16x16x32_bf16 v[40:43], v[114:117], v[110:113], v[92:95]
	v_mfma_f32_16x16x32_bf16 v[52:55], v[118:121], v[110:113], v[100:103]
	v_mfma_f32_16x16x32_bf16 v[68:71], v[122:125], v[110:113], v[106:109]
	v_mfma_f32_16x16x32_bf16 v[76:79], v[132:135], v[110:113], v[96:99]
	s_waitcnt lgkmcnt(0)
	s_barrier
	ds_read_b128 v[100:103], v127 offset:49152
	ds_read_b128 v[106:109], v127 offset:51200
	ds_read_b128 v[110:113], v127 offset:53248
	ds_read_b128 v[114:117], v127 offset:55296
	ds_read_b128 v[92:95], v126 offset:32768
	ds_read_b128 v[96:99], v126 offset:34816
	s_min_u32 s3, s2, 12
	s_lshl_b32 s92, s3, 7
	ds_read_b128 v[118:121], v130 offset:51200
	ds_read_b128 v[122:125], v130 offset:53248
	ds_read_b128 v[132:135], v130 offset:55296
	s_waitcnt lgkmcnt(4)
	v_mfma_f32_16x16x32_bf16 v[0:3], v[100:103], v[92:95], v[0:3]
	v_lshl_add_u64 v[12:13], v[80:81], 0, s[92:93]
	v_add_co_u32_e32 v14, vcc, s11, v12
	v_mfma_f32_16x16x32_bf16 v[4:7], v[106:109], v[92:95], v[4:7]
	s_nop 0
	v_addc_co_u32_e32 v15, vcc, 0, v13, vcc
	v_mfma_f32_16x16x32_bf16 v[8:11], v[110:113], v[92:95], v[8:11]
	v_mfma_f32_16x16x32_bf16 v[36:39], v[114:117], v[92:95], v[36:39]
	s_waitcnt lgkmcnt(3)
	v_mfma_f32_16x16x32_bf16 v[92:95], v[100:103], v[96:99], v[40:43]
	s_nop 2
	ds_read_b128 v[40:43], v128 offset:32768
	v_mfma_f32_16x16x32_bf16 v[100:103], v[106:109], v[96:99], v[52:55]
	v_mfma_f32_16x16x32_bf16 v[106:109], v[110:113], v[96:99], v[68:71]
	ds_read_b128 v[110:113], v128 offset:34816
	v_mfma_f32_16x16x32_bf16 v[96:99], v[114:117], v[96:99], v[76:79]
	ds_read_b128 v[114:117], v130 offset:49152
	v_add_co_u32_e32 v14, vcc, s33, v12
	s_nop 0
	s_nop 0
	v_addc_co_u32_e32 v15, vcc, 0, v13, vcc
	v_add_co_u32_e32 v12, vcc, s59, v12
	s_nop 0
	s_nop 0
	v_addc_co_u32_e32 v13, vcc, 0, v13, vcc
	v_lshl_add_u64 v[12:13], v[82:83], 0, s[92:93]
	s_waitcnt lgkmcnt(0)
	v_mfma_f32_16x16x32_bf16 v[76:79], v[114:117], v[40:43], v[0:3]
	v_mfma_f32_16x16x32_bf16 v[68:71], v[118:121], v[40:43], v[4:7]
	v_add_co_u32_e32 v12, vcc, s11, v12
	s_nop 0
	s_nop 0
	v_addc_co_u32_e32 v13, vcc, 0, v13, vcc
	v_mfma_f32_16x16x32_bf16 v[52:55], v[122:125], v[40:43], v[8:11]
	v_mfma_f32_16x16x32_bf16 v[40:43], v[132:135], v[40:43], v[36:39]
	v_mfma_f32_16x16x32_bf16 v[36:39], v[114:117], v[110:113], v[92:95]
	v_mfma_f32_16x16x32_bf16 v[8:11], v[118:121], v[110:113], v[100:103]
	v_mfma_f32_16x16x32_bf16 v[4:7], v[122:125], v[110:113], v[106:109]
	v_mfma_f32_16x16x32_bf16 v[0:3], v[132:135], v[110:113], v[96:99]
	s_mov_b32 s3, s2
	s_waitcnt lgkmcnt(0)
	v_readlane_b32 s2, v251, 18
	s_waitcnt vmcnt(1)
	s_nop 0
	v_add_u32_e32 v18, s2, v86
	v_readlane_b32 s2, v251, 19
	s_waitcnt vmcnt(0)
	v_add_u32_e32 v13, 0xffffe000, v18
	v_or_b32_e32 v12, v18, v85
	v_lshl_or_b32 v19, v84, 2, s2
	v_lshrrev_b32_e32 v13, 10, v13
	s_movk_i32 s2, 0x1800
	v_mad_u32_u24 v13, v13, s2, s2
	v_cmp_lt_i32_e32 vcc, s13, v12
	v_lshlrev_b32_e32 v128, 2, v19
	v_readlane_b32 s2, v250, 15
	v_cndmask_b32_e32 v14, 0, v13, vcc
	v_ashrrev_i32_e32 v15, 31, v14
	v_lshlrev_b64 v[24:25], 2, v[14:15]
	v_ashrrev_i32_e32 v13, 31, v12
	v_lshl_add_u64 v[14:15], s[40:41], 0, v[24:25]
	v_lshl_add_u64 v[48:49], v[14:15], 0, v[128:129]
	v_lshlrev_b64 v[14:15], 12, v[12:13]
	v_readlane_b32 s3, v250, 16
	v_lshl_add_u64 v[28:29], s[42:43], 0, v[24:25]
	v_lshlrev_b64 v[32:33], 11, v[12:13]
	v_lshl_add_u64 v[14:15], s[2:3], 0, v[14:15]
	v_lshl_add_u64 v[50:51], v[14:15], 0, v[128:129]
	global_load_dwordx4 v[72:75], v[48:49], off
	global_load_dwordx4 v[80:83], v[48:49], off offset:64
	global_load_dwordx4 v[88:91], v[48:49], off offset:128
	global_load_dwordx4 v[136:139], v[48:49], off offset:192
	global_load_dwordx4 v[194:197], v[50:51], off
	global_load_dwordx4 v[198:201], v[50:51], off offset:64
	global_load_dwordx4 v[202:205], v[50:51], off offset:128
	global_load_dwordx4 v[206:209], v[50:51], off offset:192
	v_add_co_u32_e32 v58, vcc, 0x10000, v50
	s_nop 1
	v_addc_co_u32_e32 v59, vcc, 0, v51, vcc
	global_load_dwordx4 v[210:213], v[58:59], off
	global_load_dwordx4 v[214:217], v[58:59], off offset:64
	global_load_dwordx4 v[218:221], v[58:59], off offset:128
	global_load_dwordx4 v[222:225], v[58:59], off offset:192
	v_readlane_b32 s2, v250, 21
	v_readlane_b32 s3, v250, 22
	v_cmp_eq_u32_e32 vcc, 0, v84
	s_waitcnt vmcnt(4)
	v_pk_fma_f32 v[22:23], v[78:79], v[74:75], v[196:197]
	v_pk_fma_f32 v[20:21], v[76:77], v[72:73], v[194:195]
	global_store_dwordx4 v[50:51], v[20:23], off
	v_lshl_add_u64 v[14:15], v[28:29], 0, v[128:129]
	global_load_dwordx4 v[140:143], v128, s[0:1]
	global_load_dwordx4 v[144:147], v128, s[0:1] offset:64
	global_load_dwordx4 v[148:151], v128, s[0:1] offset:128
	global_load_dwordx4 v[152:155], v128, s[0:1] offset:192
	global_load_dwordx4 v[156:159], v[14:15], off
	global_load_dwordx4 v[160:163], v[14:15], off offset:64
	global_load_dwordx4 v[180:183], v[14:15], off offset:128
	global_load_dwordx4 v[190:193], v[14:15], off offset:192
	v_lshlrev_b32_e32 v16, 1, v19
	v_mov_b32_e32 v17, v129
	v_lshl_add_u64 v[32:33], s[2:3], 0, v[32:33]
	v_lshl_add_u64 v[56:57], v[32:33], 0, v[16:17]
	s_waitcnt vmcnt(0)
	v_pk_mul_f32 v[26:27], v[22:23], v[142:143]
	v_pk_mul_f32 v[24:25], v[20:21], v[140:141]
	s_waitcnt vmcnt(0)
	v_pk_add_f32 v[30:31], v[158:159], 1.0 op_sel_hi:[1,0]
	v_pk_add_f32 v[28:29], v[156:157], 1.0 op_sel_hi:[1,0]
	v_pk_mul_f32 v[26:27], v[26:27], v[30:31]
	v_pk_mul_f32 v[24:25], v[24:25], v[28:29]
	v_and_b32_sdwa v19, v26, v170 dst_sel:DWORD dst_unused:UNUSED_PAD src0_sel:WORD_1 src1_sel:DWORD
	v_and_b32_sdwa v29, v27, v170 dst_sel:DWORD dst_unused:UNUSED_PAD src0_sel:WORD_1 src1_sel:DWORD
	v_and_b32_sdwa v30, v25, v170 dst_sel:DWORD dst_unused:UNUSED_PAD src0_sel:WORD_1 src1_sel:DWORD
	v_and_b32_sdwa v28, v24, v170 dst_sel:DWORD dst_unused:UNUSED_PAD src0_sel:WORD_1 src1_sel:DWORD
	v_add3_u32 v19, v26, v19, s56
	v_add3_u32 v26, v27, v29, s56
	v_add3_u32 v25, v25, v30, s56
	v_add3_u32 v24, v24, v28, s56
	v_and_b32_e32 v26, 0xffff0000, v26
	v_and_b32_e32 v27, 0xffff0000, v25
	v_or_b32_sdwa v25, v26, v19 dst_sel:DWORD dst_unused:UNUSED_PAD src0_sel:DWORD src1_sel:WORD_1
	v_or_b32_sdwa v24, v27, v24 dst_sel:DWORD dst_unused:UNUSED_PAD src0_sel:DWORD src1_sel:WORD_1
	global_store_dwordx2 v[56:57], v[24:25], off
	s_nop 0
	s_waitcnt vmcnt(0)
	v_pk_fma_f32 v[26:27], v[70:71], v[82:83], v[200:201]
	v_pk_fma_f32 v[24:25], v[68:69], v[80:81], v[198:199]
	global_store_dwordx4 v[50:51], v[24:27], off offset:64
	v_pk_mul_f32 v[30:31], v[26:27], v[146:147]
	v_pk_mul_f32 v[28:29], v[24:25], v[144:145]
	v_pk_add_f32 v[34:35], v[162:163], 1.0 op_sel_hi:[1,0]
	v_pk_add_f32 v[32:33], v[160:161], 1.0 op_sel_hi:[1,0]
	v_pk_mul_f32 v[30:31], v[30:31], v[34:35]
	v_pk_mul_f32 v[28:29], v[28:29], v[32:33]
	v_and_b32_sdwa v19, v30, v170 dst_sel:DWORD dst_unused:UNUSED_PAD src0_sel:WORD_1 src1_sel:DWORD
	v_and_b32_sdwa v33, v31, v170 dst_sel:DWORD dst_unused:UNUSED_PAD src0_sel:WORD_1 src1_sel:DWORD
	v_and_b32_sdwa v34, v29, v170 dst_sel:DWORD dst_unused:UNUSED_PAD src0_sel:WORD_1 src1_sel:DWORD
	v_and_b32_sdwa v32, v28, v170 dst_sel:DWORD dst_unused:UNUSED_PAD src0_sel:WORD_1 src1_sel:DWORD
	v_add3_u32 v19, v30, v19, s56
	v_add3_u32 v30, v31, v33, s56
	v_add3_u32 v29, v29, v34, s56
	v_add3_u32 v28, v28, v32, s56
	v_and_b32_e32 v30, 0xffff0000, v30
	v_and_b32_e32 v31, 0xffff0000, v29
	v_or_b32_sdwa v29, v30, v19 dst_sel:DWORD dst_unused:UNUSED_PAD src0_sel:DWORD src1_sel:WORD_1
	v_or_b32_sdwa v28, v31, v28 dst_sel:DWORD dst_unused:UNUSED_PAD src0_sel:DWORD src1_sel:WORD_1
	global_store_dwordx2 v[56:57], v[28:29], off offset:32
	s_nop 0
	v_pk_fma_f32 v[30:31], v[54:55], v[90:91], v[204:205]
	v_pk_fma_f32 v[28:29], v[52:53], v[88:89], v[202:203]
	global_store_dwordx4 v[50:51], v[28:31], off offset:128
	v_pk_mul_f32 v[34:35], v[30:31], v[150:151]
	v_pk_mul_f32 v[32:33], v[28:29], v[148:149]
	v_pk_add_f32 v[46:47], v[182:183], 1.0 op_sel_hi:[1,0]
	v_pk_add_f32 v[44:45], v[180:181], 1.0 op_sel_hi:[1,0]
	v_pk_mul_f32 v[34:35], v[34:35], v[46:47]
	v_pk_mul_f32 v[32:33], v[32:33], v[44:45]
	v_and_b32_sdwa v19, v34, v170 dst_sel:DWORD dst_unused:UNUSED_PAD src0_sel:WORD_1 src1_sel:DWORD
	v_and_b32_sdwa v45, v35, v170 dst_sel:DWORD dst_unused:UNUSED_PAD src0_sel:WORD_1 src1_sel:DWORD
	v_and_b32_sdwa v46, v33, v170 dst_sel:DWORD dst_unused:UNUSED_PAD src0_sel:WORD_1 src1_sel:DWORD
	v_and_b32_sdwa v44, v32, v170 dst_sel:DWORD dst_unused:UNUSED_PAD src0_sel:WORD_1 src1_sel:DWORD
	v_add3_u32 v19, v34, v19, s56
	v_add3_u32 v34, v35, v45, s56
	v_add3_u32 v33, v33, v46, s56
	v_add3_u32 v32, v32, v44, s56
	v_and_b32_e32 v34, 0xffff0000, v34
	v_and_b32_e32 v35, 0xffff0000, v33
	v_or_b32_sdwa v33, v34, v19 dst_sel:DWORD dst_unused:UNUSED_PAD src0_sel:DWORD src1_sel:WORD_1
	v_or_b32_sdwa v32, v35, v32 dst_sel:DWORD dst_unused:UNUSED_PAD src0_sel:DWORD src1_sel:WORD_1
	global_store_dwordx2 v[56:57], v[32:33], off offset:64
	s_nop 0
	v_pk_fma_f32 v[34:35], v[42:43], v[138:139], v[208:209]
	v_pk_fma_f32 v[32:33], v[40:41], v[136:137], v[206:207]
	global_store_dwordx4 v[50:51], v[32:35], off offset:192
	v_mul_f32_e32 v14, v21, v21
	v_mul_f32_e32 v15, v25, v25
	v_fmac_f32_e32 v14, v20, v20
	v_fmac_f32_e32 v15, v24, v24
	v_fmac_f32_e32 v14, v22, v22
	v_fmac_f32_e32 v15, v26, v26
	v_fmac_f32_e32 v14, v23, v23
	v_fmac_f32_e32 v15, v27, v27
	v_add_f32_e32 v14, v14, v15
	v_mul_f32_e32 v15, v29, v29
	v_fmac_f32_e32 v15, v28, v28
	v_fmac_f32_e32 v15, v30, v30
	v_fmac_f32_e32 v15, v31, v31
	v_add_f32_e32 v14, v14, v15
	v_mul_f32_e32 v15, v33, v33
	v_fmac_f32_e32 v15, v32, v32
	v_fmac_f32_e32 v15, v34, v34
	v_fmac_f32_e32 v15, v35, v35
	v_add_f32_e32 v14, v14, v15
	ds_bpermute_b32 v15, v105, v14
	s_waitcnt lgkmcnt(0)
	v_add_f32_e32 v14, v14, v15
	ds_bpermute_b32 v15, v104, v14
	v_pk_mul_f32 v[20:21], v[34:35], v[154:155]
	v_pk_mul_f32 v[22:23], v[32:33], v[152:153]
	v_pk_add_f32 v[24:25], v[192:193], 1.0 op_sel_hi:[1,0]
	v_pk_add_f32 v[26:27], v[190:191], 1.0 op_sel_hi:[1,0]
	v_pk_mul_f32 v[20:21], v[20:21], v[24:25]
	v_pk_mul_f32 v[22:23], v[22:23], v[26:27]
	v_and_b32_sdwa v19, v20, v170 dst_sel:DWORD dst_unused:UNUSED_PAD src0_sel:WORD_1 src1_sel:DWORD
	v_and_b32_sdwa v25, v21, v170 dst_sel:DWORD dst_unused:UNUSED_PAD src0_sel:WORD_1 src1_sel:DWORD
	v_and_b32_sdwa v26, v23, v170 dst_sel:DWORD dst_unused:UNUSED_PAD src0_sel:WORD_1 src1_sel:DWORD
	v_and_b32_sdwa v24, v22, v170 dst_sel:DWORD dst_unused:UNUSED_PAD src0_sel:WORD_1 src1_sel:DWORD
	v_add3_u32 v19, v20, v19, s56
	v_add3_u32 v20, v21, v25, s56
	v_add3_u32 v21, v23, v26, s56
	v_add3_u32 v22, v22, v24, s56
	v_and_b32_e32 v20, 0xffff0000, v20
	v_and_b32_e32 v23, 0xffff0000, v21
	v_or_b32_sdwa v21, v20, v19 dst_sel:DWORD dst_unused:UNUSED_PAD src0_sel:DWORD src1_sel:WORD_1
	v_or_b32_sdwa v20, v23, v22 dst_sel:DWORD dst_unused:UNUSED_PAD src0_sel:DWORD src1_sel:WORD_1
	global_store_dwordx2 v[56:57], v[20:21], off offset:96
	s_and_saveexec_b64 s[2:3], vcc
	s_cbranch_execz .LBB0_122
	v_readlane_b32 s16, v253, 20
	s_add_u32 s24, s26, s16
	s_addc_u32 s25, s27, 0
	v_lshl_add_u64 v[20:21], v[12:13], 2, s[24:25]
	s_waitcnt lgkmcnt(0)
	v_add_f32_e32 v13, v14, v15
	global_store_dword v[20:21], v13, off

.Ltail236:
	s_add_i32 s24, s25, 2
	v_add_u32_e32 v111, v104, v105
	ds_read_b128 v[136:139], v111 offset:16384
	ds_read_b128 v[140:143], v111 offset:18432
	ds_read_b128 v[144:147], v111 offset:20480
	ds_read_b128 v[148:151], v111 offset:22528
	v_add_u32_e32 v110, v103, v105
	ds_read_b128 v[116:119], v110
	s_add_i32 s25, s25, 4
	ds_read_b128 v[120:123], v110 offset:2048
	s_min_u32 s25, s25, 63
	v_add_u32_e32 v113, v104, v114
	s_lshl_b32 s92, s25, 7
	ds_read_b128 v[124:127], v110 offset:4096
	v_add_u32_e32 v112, v103, v114
	ds_read_b128 v[194:197], v113 offset:16384
	ds_read_b128 v[198:201], v113 offset:18432
	ds_read_b128 v[202:205], v113 offset:20480
	ds_read_b128 v[206:209], v113 offset:22528
	v_lshl_add_u64 v[164:165], v[98:99], 0, s[92:93]
	ds_read_b128 v[132:135], v110 offset:6144
	ds_read_b128 v[152:155], v112
	ds_read_b128 v[156:159], v112 offset:2048
	ds_read_b128 v[160:163], v112 offset:4096
	ds_read_b128 v[190:193], v112 offset:6144
	s_waitcnt lgkmcnt(11)
	v_mfma_f32_16x16x32_bf16 v[92:95], v[136:139], v[116:119], v[92:95]
	v_mfma_f32_16x16x32_bf16 v[56:59], v[140:143], v[116:119], v[56:59]
	v_mfma_f32_16x16x32_bf16 v[52:55], v[144:147], v[116:119], v[52:55]
	v_mfma_f32_16x16x32_bf16 v[48:51], v[148:151], v[116:119], v[48:51]
	s_waitcnt vmcnt(7)
	ds_write_b128 v109, v[60:63] offset:32768
	v_add_co_u32_e32 v60, vcc, s7, v164
	s_waitcnt lgkmcnt(11)
	v_mfma_f32_16x16x32_bf16 v[44:47], v[136:139], v[120:123], v[44:47]
	v_addc_co_u32_e32 v61, vcc, 0, v165, vcc
	v_mfma_f32_16x16x32_bf16 v[40:43], v[140:143], v[120:123], v[40:43]
	v_mfma_f32_16x16x32_bf16 v[36:39], v[144:147], v[120:123], v[36:39]
	v_mfma_f32_16x16x32_bf16 v[32:35], v[148:151], v[120:123], v[32:35]
	v_add_co_u32_e32 v60, vcc, s52, v164
	s_waitcnt vmcnt(6)
	ds_write_b128 v109, v[64:67] offset:36864
	s_nop 0
	v_addc_co_u32_e32 v61, vcc, 0, v165, vcc
	s_waitcnt lgkmcnt(11)
	v_mfma_f32_16x16x32_bf16 v[28:31], v[136:139], v[124:127], v[28:31]
	v_lshl_add_u64 v[64:65], v[100:101], 0, s[92:93]
	v_mfma_f32_16x16x32_bf16 v[24:27], v[140:143], v[124:127], v[24:27]
	v_mfma_f32_16x16x32_bf16 v[20:23], v[144:147], v[124:127], v[20:23]
	v_mfma_f32_16x16x32_bf16 v[16:19], v[148:151], v[124:127], v[16:19]
	v_add_co_u32_e32 v60, vcc, s34, v164
	s_waitcnt vmcnt(5)
	ds_write_b128 v109, v[68:71] offset:40960
	s_nop 0
	v_addc_co_u32_e32 v61, vcc, 0, v165, vcc
	v_add_co_u32_e32 v66, vcc, s7, v64
	s_waitcnt lgkmcnt(7)
	v_mfma_f32_16x16x32_bf16 v[12:15], v[136:139], v[132:135], v[12:15]
	v_addc_co_u32_e32 v67, vcc, 0, v65, vcc
	v_mfma_f32_16x16x32_bf16 v[8:11], v[140:143], v[132:135], v[8:11]
	v_mfma_f32_16x16x32_bf16 v[4:7], v[144:147], v[132:135], v[4:7]
	v_mfma_f32_16x16x32_bf16 v[0:3], v[148:151], v[132:135], v[0:3]
	s_waitcnt vmcnt(4)
	ds_write_b128 v109, v[76:79] offset:45056
	s_waitcnt lgkmcnt(7)
	v_mfma_f32_16x16x32_bf16 v[60:63], v[194:197], v[152:155], v[92:95]
	v_mfma_f32_16x16x32_bf16 v[56:59], v[198:201], v[152:155], v[56:59]
	v_mfma_f32_16x16x32_bf16 v[52:55], v[202:205], v[152:155], v[52:55]
	v_mfma_f32_16x16x32_bf16 v[48:51], v[206:209], v[152:155], v[48:51]
	s_waitcnt vmcnt(3)
	ds_write_b128 v109, v[72:75] offset:49152
	s_waitcnt lgkmcnt(7)
	v_mfma_f32_16x16x32_bf16 v[44:47], v[194:197], v[156:159], v[44:47]
	v_mfma_f32_16x16x32_bf16 v[40:43], v[198:201], v[156:159], v[40:43]
	v_mfma_f32_16x16x32_bf16 v[36:39], v[202:205], v[156:159], v[36:39]
	v_mfma_f32_16x16x32_bf16 v[32:35], v[206:209], v[156:159], v[32:35]
	v_add_co_u32_e32 v66, vcc, s52, v64
	s_waitcnt vmcnt(2)
	ds_write_b128 v109, v[80:83] offset:53248
	v_addc_co_u32_e32 v67, vcc, 0, v65, vcc
	v_add_co_u32_e32 v64, vcc, s34, v64
	s_waitcnt lgkmcnt(7)
	v_mfma_f32_16x16x32_bf16 v[28:31], v[194:197], v[160:163], v[28:31]
	v_addc_co_u32_e32 v65, vcc, 0, v65, vcc
	v_mfma_f32_16x16x32_bf16 v[24:27], v[198:201], v[160:163], v[24:27]
	v_mfma_f32_16x16x32_bf16 v[20:23], v[202:205], v[160:163], v[20:23]
	v_mfma_f32_16x16x32_bf16 v[16:19], v[206:209], v[160:163], v[16:19]
	s_waitcnt vmcnt(1)
	ds_write_b128 v109, v[84:87] offset:57344
	s_waitcnt lgkmcnt(7)
	v_mfma_f32_16x16x32_bf16 v[12:15], v[194:197], v[190:193], v[12:15]
	v_mfma_f32_16x16x32_bf16 v[8:11], v[198:201], v[190:193], v[8:11]
	v_mfma_f32_16x16x32_bf16 v[4:7], v[202:205], v[190:193], v[4:7]
	v_mfma_f32_16x16x32_bf16 v[0:3], v[206:209], v[190:193], v[0:3]
	s_waitcnt vmcnt(0)
	ds_write_b128 v109, v[88:91] offset:61440
	s_waitcnt lgkmcnt(0)
	s_barrier
	ds_read_b128 v[80:83], v111 offset:49152
	ds_read_b128 v[84:87], v111 offset:51200
	ds_read_b128 v[88:91], v111 offset:53248
	ds_read_b128 v[92:95], v111 offset:55296
	ds_read_b128 v[64:67], v110 offset:32768
	ds_read_b128 v[68:71], v110 offset:34816
	s_min_u32 s25, s24, 60
	s_lshl_b32 s92, s25, 7
	ds_read_b128 v[72:75], v110 offset:36864
	v_lshl_add_u64 v[164:165], v[98:99], 0, s[92:93]
	ds_read_b128 v[76:79], v110 offset:38912
	ds_read_b128 v[152:155], v112 offset:32768
	ds_read_b128 v[156:159], v112 offset:34816
	ds_read_b128 v[160:163], v112 offset:36864
	ds_read_b128 v[190:193], v112 offset:38912
	ds_read_b128 v[194:197], v113 offset:49152
	ds_read_b128 v[198:201], v113 offset:51200
	ds_read_b128 v[202:205], v113 offset:53248
	ds_read_b128 v[206:209], v113 offset:55296
	s_waitcnt lgkmcnt(11)
	v_mfma_f32_16x16x32_bf16 v[210:213], v[80:83], v[64:67], v[60:63]
	v_mfma_f32_16x16x32_bf16 v[56:59], v[84:87], v[64:67], v[56:59]
	v_mfma_f32_16x16x32_bf16 v[52:55], v[88:91], v[64:67], v[52:55]
	v_mfma_f32_16x16x32_bf16 v[48:51], v[92:95], v[64:67], v[48:51]
	v_add_co_u32_e32 v64, vcc, s7, v164
	s_nop 0
	s_nop 0
	v_addc_co_u32_e32 v65, vcc, 0, v165, vcc
	s_waitcnt lgkmcnt(10)
	v_mfma_f32_16x16x32_bf16 v[44:47], v[80:83], v[68:71], v[44:47]
	v_mfma_f32_16x16x32_bf16 v[40:43], v[84:87], v[68:71], v[40:43]
	v_mfma_f32_16x16x32_bf16 v[36:39], v[88:91], v[68:71], v[36:39]
	v_mfma_f32_16x16x32_bf16 v[32:35], v[92:95], v[68:71], v[32:35]
	v_add_co_u32_e32 v68, vcc, s52, v164
	s_nop 0
	s_nop 0
	v_addc_co_u32_e32 v69, vcc, 0, v165, vcc
	s_waitcnt lgkmcnt(9)
	v_mfma_f32_16x16x32_bf16 v[28:31], v[80:83], v[72:75], v[28:31]
	v_mfma_f32_16x16x32_bf16 v[24:27], v[84:87], v[72:75], v[24:27]
	v_mfma_f32_16x16x32_bf16 v[20:23], v[88:91], v[72:75], v[20:23]
	v_mfma_f32_16x16x32_bf16 v[16:19], v[92:95], v[72:75], v[16:19]
	v_add_co_u32_e32 v72, vcc, s34, v164
	s_waitcnt lgkmcnt(8)
	v_mfma_f32_16x16x32_bf16 v[4:7], v[88:91], v[76:79], v[4:7]
	v_addc_co_u32_e32 v73, vcc, 0, v165, vcc
	v_lshl_add_u64 v[88:89], v[100:101], 0, s[92:93]
	v_mfma_f32_16x16x32_bf16 v[12:15], v[80:83], v[76:79], v[12:15]
	v_add_co_u32_e32 v80, vcc, s7, v88
	v_mfma_f32_16x16x32_bf16 v[8:11], v[84:87], v[76:79], v[8:11]
	s_nop 0
	v_addc_co_u32_e32 v81, vcc, 0, v89, vcc
	v_add_co_u32_e32 v84, vcc, s52, v88
	v_mfma_f32_16x16x32_bf16 v[0:3], v[92:95], v[76:79], v[0:3]
	s_nop 0
	v_addc_co_u32_e32 v85, vcc, 0, v89, vcc
	s_waitcnt lgkmcnt(3)
	v_mfma_f32_16x16x32_bf16 v[92:95], v[194:197], v[152:155], v[210:213]
	s_waitcnt lgkmcnt(2)
	v_mfma_f32_16x16x32_bf16 v[56:59], v[198:201], v[152:155], v[56:59]
	s_waitcnt lgkmcnt(1)
	v_mfma_f32_16x16x32_bf16 v[52:55], v[202:205], v[152:155], v[52:55]
	s_waitcnt lgkmcnt(0)
	v_mfma_f32_16x16x32_bf16 v[48:51], v[206:209], v[152:155], v[48:51]
	v_add_co_u32_e32 v88, vcc, s34, v88
	s_nop 1
	v_addc_co_u32_e32 v89, vcc, 0, v89, vcc
	v_mfma_f32_16x16x32_bf16 v[44:47], v[194:197], v[156:159], v[44:47]
	v_mfma_f32_16x16x32_bf16 v[40:43], v[198:201], v[156:159], v[40:43]
	v_mfma_f32_16x16x32_bf16 v[36:39], v[202:205], v[156:159], v[36:39]
	v_mfma_f32_16x16x32_bf16 v[32:35], v[206:209], v[156:159], v[32:35]
	v_mfma_f32_16x16x32_bf16 v[28:31], v[194:197], v[160:163], v[28:31]
	v_mfma_f32_16x16x32_bf16 v[24:27], v[198:201], v[160:163], v[24:27]
	v_mfma_f32_16x16x32_bf16 v[20:23], v[202:205], v[160:163], v[20:23]
	v_mfma_f32_16x16x32_bf16 v[16:19], v[206:209], v[160:163], v[16:19]
	v_mfma_f32_16x16x32_bf16 v[12:15], v[194:197], v[190:193], v[12:15]
	v_mfma_f32_16x16x32_bf16 v[8:11], v[198:201], v[190:193], v[8:11]
	v_mfma_f32_16x16x32_bf16 v[4:7], v[202:205], v[190:193], v[4:7]
	v_mfma_f32_16x16x32_bf16 v[0:3], v[206:209], v[190:193], v[0:3]
	s_mov_b32 s25, s24
	s_waitcnt lgkmcnt(0)
	s_add_i32 s26, s69, 1
	v_readlane_b32 s16, v251, 5
	s_and_b64 s[24:25], s[8:9], exec
	s_mul_i32 s25, s69, 0x12000
	s_waitcnt vmcnt(2)
	v_add_u32_e32 v80, s16, v108
	v_readlane_b32 s28, v250, 25
	v_add_u32_e32 v60, 0xffffe000, v80
	s_cselect_b32 s24, 3, s26
	v_readlane_b32 s29, v250, 26
	s_add_u32 s25, s28, s25
	v_or_b32_e32 v70, v80, v107
	v_lshlrev_b32_e32 v114, 6, v102
	v_readlane_b32 s16, v251, 6
	v_lshrrev_b32_e32 v60, 10, v60
	s_movk_i32 s5, 0x1800
	s_addc_u32 s26, s29, 0
	v_or_b32_e32 v81, s16, v114
	v_lshlrev_b32_e32 v115, 2, v97
	v_mad_u32_u24 v60, v60, s5, s5
	v_cmp_lt_i32_e32 vcc, s13, v70
	s_add_u32 s40, s25, 0x5000
	v_or_b32_e32 v64, v81, v115
	v_cndmask_b32_e32 v76, 0, v60, vcc
	s_addc_u32 s41, s26, 0
	v_ashrrev_i32_e32 v77, 31, v76
	v_ashrrev_i32_e32 v65, 31, v64
	v_ashrrev_i32_e32 v71, 31, v70
	v_lshl_add_u64 v[60:61], v[76:77], 2, s[40:41]
	v_lshlrev_b64 v[66:67], 2, v[64:65]
	v_readlane_b32 s16, v250, 15
	v_lshl_add_u64 v[74:75], v[60:61], 0, v[66:67]
	v_lshlrev_b64 v[60:61], 12, v[70:71]
	v_readlane_b32 s17, v250, 16
	v_readlane_b32 s68, v250, 41
	s_mul_i32 s25, s24, 0x12000
	v_lshl_add_u64 v[60:61], s[16:17], 0, v[60:61]
	v_lshl_add_u64 v[72:73], v[60:61], 0, v[66:67]
	global_load_dwordx4 v[116:119], v[74:75], off
	global_load_dwordx4 v[120:123], v[74:75], off offset:64
	global_load_dwordx4 v[124:127], v[74:75], off offset:128
	global_load_dwordx4 v[132:135], v[74:75], off offset:192
	global_load_dwordx4 v[190:193], v[72:73], off
	global_load_dwordx4 v[194:197], v[72:73], off offset:64
	global_load_dwordx4 v[198:201], v[72:73], off offset:128
	global_load_dwordx4 v[202:205], v[72:73], off offset:192
	v_add_co_u32_e32 v164, vcc, 0x10000, v72
	s_nop 1
	v_addc_co_u32_e32 v165, vcc, 0, v73, vcc
	v_add_co_u32_e32 v222, vcc, 0x20000, v72
	s_nop 1
	v_addc_co_u32_e32 v223, vcc, 0, v73, vcc
	v_add_co_u32_e32 v224, vcc, 0x30000, v72
	s_nop 1
	v_addc_co_u32_e32 v225, vcc, 0, v73, vcc
	global_load_dwordx4 v[206:209], v[164:165], off
	global_load_dwordx4 v[210:213], v[164:165], off offset:64
	global_load_dwordx4 v[214:217], v[164:165], off offset:128
	global_load_dwordx4 v[218:221], v[164:165], off offset:192
	s_lshl_b32 s24, s24, 12
	v_readlane_b32 s70, v250, 43
	v_readlane_b32 s71, v250, 44
	s_add_u32 s26, s70, s24
	s_addc_u32 s27, s71, 0
	s_add_u32 s24, s28, s25
	s_addc_u32 s25, s29, 0
	s_add_u32 s42, s24, 0x1000
	v_cndmask_b32_e64 v68, 0, 1, s[2:3]
	s_addc_u32 s43, s25, 0
	s_andn2_b64 vcc, exec, s[2:3]
	v_readlane_b32 s2, v250, 21
	s_waitcnt vmcnt(3)
	v_lshlrev_b64 v[86:87], 10, v[70:71]
	v_readlane_b32 s3, v250, 22
	v_cmp_ne_u32_e64 s[36:37], 1, v68
	v_lshl_add_u64 v[68:69], s[26:27], 0, v[66:67]
	v_lshl_add_u64 v[78:79], v[76:77], 2, s[42:43]
	v_lshl_add_u64 v[76:77], v[86:87], 1, s[2:3]
	v_readlane_b32 s69, v250, 42
	v_readlane_b32 s72, v250, 45
	v_readlane_b32 s73, v250, 46
	v_readlane_b32 s74, v250, 47
	v_readlane_b32 s75, v250, 48
	v_readlane_b32 s76, v250, 49
	v_readlane_b32 s77, v250, 50
	v_readlane_b32 s78, v250, 51
	v_readlane_b32 s79, v250, 52
	v_readlane_b32 s80, v250, 53
	v_readlane_b32 s81, v250, 54
	v_readlane_b32 s82, v250, 55
	v_readlane_b32 s83, v250, 56
	s_waitcnt vmcnt(4)
	v_pk_fma_f32 v[62:63], v[94:95], v[118:119], v[192:193]
	v_pk_fma_f32 v[60:61], v[92:93], v[116:117], v[190:191]
	global_store_dwordx4 v[72:73], v[60:63], off
	s_cbranch_vccnz .LBB0_239
	v_lshl_add_u64 v[86:87], v[78:79], 0, v[66:67]
	global_load_dwordx4 v[136:139], v[68:69], off
	global_load_dwordx4 v[140:143], v[68:69], off offset:64
	global_load_dwordx4 v[144:147], v[68:69], off offset:128
	global_load_dwordx4 v[148:151], v[68:69], off offset:192
	s_waitcnt vmcnt(0)
	v_pk_mul_f32 v[84:85], v[62:63], v[138:139]
	global_load_dwordx4 v[152:155], v[86:87], off
	global_load_dwordx4 v[156:159], v[86:87], off offset:64
	global_load_dwordx4 v[160:163], v[86:87], off offset:128
	global_load_dwordx4 v[180:183], v[86:87], off offset:192
	v_pk_mul_f32 v[82:83], v[60:61], v[136:137]
	s_waitcnt vmcnt(0)
	v_pk_add_f32 v[88:89], v[154:155], 1.0 op_sel_hi:[1,0]
	v_pk_add_f32 v[86:87], v[152:153], 1.0 op_sel_hi:[1,0]
	v_pk_mul_f32 v[84:85], v[84:85], v[88:89]
	v_pk_mul_f32 v[82:83], v[82:83], v[86:87]
	v_and_b32_sdwa v89, v82, v170 dst_sel:DWORD dst_unused:UNUSED_PAD src0_sel:WORD_1 src1_sel:DWORD
	v_add3_u32 v82, v82, v89, s56
	v_and_b32_sdwa v89, v83, v170 dst_sel:DWORD dst_unused:UNUSED_PAD src0_sel:WORD_1 src1_sel:DWORD
	v_add3_u32 v83, v83, v89, s56
	v_and_b32_e32 v88, 0xffff0000, v83
	v_lshl_add_u64 v[86:87], v[64:65], 1, v[76:77]
	v_cvt_pk_bf16_f32 v83, v84, v85
	v_or_b32_sdwa v82, v88, v82 dst_sel:DWORD dst_unused:UNUSED_PAD src0_sel:DWORD src1_sel:WORD_1
	global_store_dwordx2 v[86:87], v[82:83], off

.Ltail282:
	s_add_i32 s25, s28, 2
	ds_read_b128 v[136:139], v111 offset:16384
	ds_read_b128 v[140:143], v111 offset:18432
	ds_read_b128 v[144:147], v111 offset:20480
	ds_read_b128 v[148:151], v111 offset:22528
	ds_read_b128 v[116:119], v110
	s_add_i32 s28, s28, 4
	ds_read_b128 v[120:123], v110 offset:2048
	s_min_u32 s28, s28, 63
	s_lshl_b32 s92, s28, 7
	ds_read_b128 v[124:127], v110 offset:4096
	ds_read_b128 v[194:197], v113 offset:16384
	ds_read_b128 v[198:201], v113 offset:18432
	ds_read_b128 v[202:205], v113 offset:20480
	ds_read_b128 v[206:209], v113 offset:22528
	v_lshl_add_u64 v[164:165], v[100:101], 0, s[92:93]
	ds_read_b128 v[132:135], v110 offset:6144
	ds_read_b128 v[152:155], v112
	ds_read_b128 v[156:159], v112 offset:2048
	ds_read_b128 v[160:163], v112 offset:4096
	ds_read_b128 v[190:193], v112 offset:6144
	s_waitcnt lgkmcnt(11)
	v_mfma_f32_16x16x32_bf16 v[92:95], v[136:139], v[116:119], v[92:95]
	v_mfma_f32_16x16x32_bf16 v[56:59], v[140:143], v[116:119], v[56:59]
	v_mfma_f32_16x16x32_bf16 v[52:55], v[144:147], v[116:119], v[52:55]
	v_mfma_f32_16x16x32_bf16 v[48:51], v[148:151], v[116:119], v[48:51]
	s_waitcnt vmcnt(7)
	ds_write_b128 v109, v[60:63] offset:32768
	v_add_co_u32_e32 v60, vcc, s7, v164
	s_waitcnt lgkmcnt(11)
	v_mfma_f32_16x16x32_bf16 v[44:47], v[136:139], v[120:123], v[44:47]
	v_addc_co_u32_e32 v61, vcc, 0, v165, vcc
	v_mfma_f32_16x16x32_bf16 v[40:43], v[140:143], v[120:123], v[40:43]
	v_mfma_f32_16x16x32_bf16 v[36:39], v[144:147], v[120:123], v[36:39]
	v_mfma_f32_16x16x32_bf16 v[32:35], v[148:151], v[120:123], v[32:35]
	v_add_co_u32_e32 v60, vcc, s52, v164
	s_waitcnt vmcnt(6)
	ds_write_b128 v109, v[64:67] offset:36864
	s_nop 0
	v_addc_co_u32_e32 v61, vcc, 0, v165, vcc
	s_waitcnt lgkmcnt(11)
	v_mfma_f32_16x16x32_bf16 v[28:31], v[136:139], v[124:127], v[28:31]
	v_lshl_add_u64 v[64:65], v[102:103], 0, s[92:93]
	v_mfma_f32_16x16x32_bf16 v[24:27], v[140:143], v[124:127], v[24:27]
	v_mfma_f32_16x16x32_bf16 v[20:23], v[144:147], v[124:127], v[20:23]
	v_mfma_f32_16x16x32_bf16 v[16:19], v[148:151], v[124:127], v[16:19]
	v_add_co_u32_e32 v60, vcc, s34, v164
	s_waitcnt vmcnt(5)
	ds_write_b128 v109, v[68:71] offset:40960
	s_nop 0
	v_addc_co_u32_e32 v61, vcc, 0, v165, vcc
	v_add_co_u32_e32 v66, vcc, s7, v64
	s_waitcnt lgkmcnt(7)
	v_mfma_f32_16x16x32_bf16 v[12:15], v[136:139], v[132:135], v[12:15]
	v_addc_co_u32_e32 v67, vcc, 0, v65, vcc
	v_mfma_f32_16x16x32_bf16 v[8:11], v[140:143], v[132:135], v[8:11]
	v_mfma_f32_16x16x32_bf16 v[4:7], v[144:147], v[132:135], v[4:7]
	v_mfma_f32_16x16x32_bf16 v[0:3], v[148:151], v[132:135], v[0:3]
	s_waitcnt vmcnt(4)
	ds_write_b128 v109, v[76:79] offset:45056
	s_waitcnt lgkmcnt(7)
	v_mfma_f32_16x16x32_bf16 v[60:63], v[194:197], v[152:155], v[92:95]
	v_mfma_f32_16x16x32_bf16 v[56:59], v[198:201], v[152:155], v[56:59]
	v_mfma_f32_16x16x32_bf16 v[52:55], v[202:205], v[152:155], v[52:55]
	v_mfma_f32_16x16x32_bf16 v[48:51], v[206:209], v[152:155], v[48:51]
	s_waitcnt vmcnt(3)
	ds_write_b128 v109, v[72:75] offset:49152
	s_waitcnt lgkmcnt(7)
	v_mfma_f32_16x16x32_bf16 v[44:47], v[194:197], v[156:159], v[44:47]
	v_mfma_f32_16x16x32_bf16 v[40:43], v[198:201], v[156:159], v[40:43]
	v_mfma_f32_16x16x32_bf16 v[36:39], v[202:205], v[156:159], v[36:39]
	v_mfma_f32_16x16x32_bf16 v[32:35], v[206:209], v[156:159], v[32:35]
	v_add_co_u32_e32 v66, vcc, s52, v64
	s_waitcnt vmcnt(2)
	ds_write_b128 v109, v[80:83] offset:53248
	v_addc_co_u32_e32 v67, vcc, 0, v65, vcc
	v_add_co_u32_e32 v64, vcc, s34, v64
	s_waitcnt lgkmcnt(7)
	v_mfma_f32_16x16x32_bf16 v[28:31], v[194:197], v[160:163], v[28:31]
	v_addc_co_u32_e32 v65, vcc, 0, v65, vcc
	v_mfma_f32_16x16x32_bf16 v[24:27], v[198:201], v[160:163], v[24:27]
	v_mfma_f32_16x16x32_bf16 v[20:23], v[202:205], v[160:163], v[20:23]
	v_mfma_f32_16x16x32_bf16 v[16:19], v[206:209], v[160:163], v[16:19]
	s_waitcnt vmcnt(1)
	ds_write_b128 v109, v[84:87] offset:57344
	s_waitcnt lgkmcnt(7)
	v_mfma_f32_16x16x32_bf16 v[12:15], v[194:197], v[190:193], v[12:15]
	v_mfma_f32_16x16x32_bf16 v[8:11], v[198:201], v[190:193], v[8:11]
	v_mfma_f32_16x16x32_bf16 v[4:7], v[202:205], v[190:193], v[4:7]
	v_mfma_f32_16x16x32_bf16 v[0:3], v[206:209], v[190:193], v[0:3]
	s_waitcnt vmcnt(0)
	ds_write_b128 v109, v[88:91] offset:61440
	s_waitcnt lgkmcnt(0)
	s_barrier
	ds_read_b128 v[80:83], v111 offset:49152
	ds_read_b128 v[84:87], v111 offset:51200
	ds_read_b128 v[88:91], v111 offset:53248
	ds_read_b128 v[92:95], v111 offset:55296
	ds_read_b128 v[64:67], v110 offset:32768
	ds_read_b128 v[68:71], v110 offset:34816
	s_min_u32 s28, s25, 60
	s_lshl_b32 s92, s28, 7
	ds_read_b128 v[72:75], v110 offset:36864
	v_lshl_add_u64 v[164:165], v[100:101], 0, s[92:93]
	ds_read_b128 v[76:79], v110 offset:38912
	ds_read_b128 v[152:155], v112 offset:32768
	ds_read_b128 v[156:159], v112 offset:34816
	ds_read_b128 v[160:163], v112 offset:36864
	ds_read_b128 v[190:193], v112 offset:38912
	ds_read_b128 v[194:197], v113 offset:49152
	ds_read_b128 v[198:201], v113 offset:51200
	ds_read_b128 v[202:205], v113 offset:53248
	ds_read_b128 v[206:209], v113 offset:55296
	s_waitcnt lgkmcnt(11)
	v_mfma_f32_16x16x32_bf16 v[210:213], v[80:83], v[64:67], v[60:63]
	v_mfma_f32_16x16x32_bf16 v[56:59], v[84:87], v[64:67], v[56:59]
	v_mfma_f32_16x16x32_bf16 v[52:55], v[88:91], v[64:67], v[52:55]
	v_mfma_f32_16x16x32_bf16 v[48:51], v[92:95], v[64:67], v[48:51]
	v_add_co_u32_e32 v64, vcc, s7, v164
	s_nop 0
	s_nop 0
	v_addc_co_u32_e32 v65, vcc, 0, v165, vcc
	s_waitcnt lgkmcnt(10)
	v_mfma_f32_16x16x32_bf16 v[44:47], v[80:83], v[68:71], v[44:47]
	v_mfma_f32_16x16x32_bf16 v[40:43], v[84:87], v[68:71], v[40:43]
	v_mfma_f32_16x16x32_bf16 v[36:39], v[88:91], v[68:71], v[36:39]
	v_mfma_f32_16x16x32_bf16 v[32:35], v[92:95], v[68:71], v[32:35]
	v_add_co_u32_e32 v68, vcc, s52, v164
	s_nop 0
	s_nop 0
	v_addc_co_u32_e32 v69, vcc, 0, v165, vcc
	s_waitcnt lgkmcnt(9)
	v_mfma_f32_16x16x32_bf16 v[28:31], v[80:83], v[72:75], v[28:31]
	v_mfma_f32_16x16x32_bf16 v[24:27], v[84:87], v[72:75], v[24:27]
	v_mfma_f32_16x16x32_bf16 v[20:23], v[88:91], v[72:75], v[20:23]
	v_mfma_f32_16x16x32_bf16 v[16:19], v[92:95], v[72:75], v[16:19]
	v_add_co_u32_e32 v72, vcc, s34, v164
	s_waitcnt lgkmcnt(8)
	v_mfma_f32_16x16x32_bf16 v[4:7], v[88:91], v[76:79], v[4:7]
	v_addc_co_u32_e32 v73, vcc, 0, v165, vcc
	v_lshl_add_u64 v[88:89], v[102:103], 0, s[92:93]
	v_mfma_f32_16x16x32_bf16 v[12:15], v[80:83], v[76:79], v[12:15]
	v_add_co_u32_e32 v80, vcc, s7, v88
	v_mfma_f32_16x16x32_bf16 v[8:11], v[84:87], v[76:79], v[8:11]
	s_nop 0
	v_addc_co_u32_e32 v81, vcc, 0, v89, vcc
	v_add_co_u32_e32 v84, vcc, s52, v88
	v_mfma_f32_16x16x32_bf16 v[0:3], v[92:95], v[76:79], v[0:3]
	s_nop 0
	v_addc_co_u32_e32 v85, vcc, 0, v89, vcc
	s_waitcnt lgkmcnt(3)
	v_mfma_f32_16x16x32_bf16 v[92:95], v[194:197], v[152:155], v[210:213]
	s_waitcnt lgkmcnt(2)
	v_mfma_f32_16x16x32_bf16 v[56:59], v[198:201], v[152:155], v[56:59]
	s_waitcnt lgkmcnt(1)
	v_mfma_f32_16x16x32_bf16 v[52:55], v[202:205], v[152:155], v[52:55]
	s_waitcnt lgkmcnt(0)
	v_mfma_f32_16x16x32_bf16 v[48:51], v[206:209], v[152:155], v[48:51]
	v_add_co_u32_e32 v88, vcc, s34, v88
	s_nop 1
	v_addc_co_u32_e32 v89, vcc, 0, v89, vcc
	v_mfma_f32_16x16x32_bf16 v[44:47], v[194:197], v[156:159], v[44:47]
	v_mfma_f32_16x16x32_bf16 v[40:43], v[198:201], v[156:159], v[40:43]
	v_mfma_f32_16x16x32_bf16 v[36:39], v[202:205], v[156:159], v[36:39]
	v_mfma_f32_16x16x32_bf16 v[32:35], v[206:209], v[156:159], v[32:35]
	v_mfma_f32_16x16x32_bf16 v[28:31], v[194:197], v[160:163], v[28:31]
	v_mfma_f32_16x16x32_bf16 v[24:27], v[198:201], v[160:163], v[24:27]
	v_mfma_f32_16x16x32_bf16 v[20:23], v[202:205], v[160:163], v[20:23]
	v_mfma_f32_16x16x32_bf16 v[16:19], v[206:209], v[160:163], v[16:19]
	v_mfma_f32_16x16x32_bf16 v[12:15], v[194:197], v[190:193], v[12:15]
	v_mfma_f32_16x16x32_bf16 v[8:11], v[198:201], v[190:193], v[8:11]
	v_mfma_f32_16x16x32_bf16 v[4:7], v[202:205], v[190:193], v[4:7]
	v_mfma_f32_16x16x32_bf16 v[0:3], v[206:209], v[190:193], v[0:3]
	s_mov_b32 s28, s25
	s_waitcnt lgkmcnt(0)
	s_waitcnt vmcnt(2)
	v_add_u32_e32 v80, s2, v108
	v_add_u32_e32 v60, 0xffffe000, v80
	v_or_b32_e32 v70, v80, v107
	v_lshrrev_b32_e32 v60, 10, v60
	s_movk_i32 s2, 0x1800
	v_or_b32_e32 v81, s3, v114
	v_mad_u32_u24 v60, v60, s2, s2
	v_cmp_lt_i32_e32 vcc, s13, v70
	v_or_b32_e32 v64, v81, v115
	v_ashrrev_i32_e32 v71, 31, v70
	v_cndmask_b32_e32 v82, 0, v60, vcc
	v_readlane_b32 s2, v250, 15
	v_ashrrev_i32_e32 v83, 31, v82
	v_ashrrev_i32_e32 v65, 31, v64
	v_lshlrev_b64 v[68:69], 12, v[70:71]
	v_readlane_b32 s3, v250, 16
	v_lshl_add_u64 v[60:61], v[82:83], 2, s[40:41]
	v_lshlrev_b64 v[66:67], 2, v[64:65]
	v_lshl_add_u64 v[68:69], s[2:3], 0, v[68:69]
	v_lshl_add_u64 v[74:75], v[60:61], 0, v[66:67]
	v_lshl_add_u64 v[72:73], v[68:69], 0, v[66:67]
	global_load_dwordx4 v[60:63], v[74:75], off
	global_load_dwordx4 v[76:79], v[72:73], off
	v_readlane_b32 s2, v250, 21
	s_waitcnt vmcnt(3)
	v_lshlrev_b64 v[84:85], 10, v[70:71]
	v_readlane_b32 s3, v250, 22
	s_and_b64 vcc, exec, s[36:37]
	v_lshl_add_u64 v[68:69], s[26:27], 0, v[66:67]
	s_waitcnt vmcnt(0)
	v_pk_fma_f32 v[62:63], v[94:95], v[62:63], v[78:79]
	v_pk_fma_f32 v[60:61], v[92:93], v[60:61], v[76:77]
	v_lshl_add_u64 v[76:77], v[82:83], 2, s[42:43]
	v_lshl_add_u64 v[78:79], v[84:85], 1, s[2:3]
	global_store_dwordx4 v[72:73], v[60:63], off
	s_cbranch_vccnz .LBB0_285
	v_lshl_add_u64 v[86:87], v[76:77], 0, v[66:67]
	global_load_dwordx4 v[82:85], v[68:69], off
	s_waitcnt vmcnt(0)
	v_pk_mul_f32 v[84:85], v[62:63], v[84:85]
	global_load_dwordx4 v[86:89], v[86:87], off
	v_pk_mul_f32 v[82:83], v[60:61], v[82:83]
	s_waitcnt vmcnt(0)
	v_pk_add_f32 v[88:89], v[88:89], 1.0 op_sel_hi:[1,0]
	v_pk_add_f32 v[86:87], v[86:87], 1.0 op_sel_hi:[1,0]
	v_pk_mul_f32 v[84:85], v[84:85], v[88:89]
	v_pk_mul_f32 v[82:83], v[82:83], v[86:87]
	v_and_b32_sdwa v89, v82, v170 dst_sel:DWORD dst_unused:UNUSED_PAD src0_sel:WORD_1 src1_sel:DWORD
	v_add3_u32 v82, v82, v89, s56
	v_and_b32_sdwa v89, v83, v170 dst_sel:DWORD dst_unused:UNUSED_PAD src0_sel:WORD_1 src1_sel:DWORD
	v_add3_u32 v83, v83, v89, s56
	v_and_b32_e32 v88, 0xffff0000, v83
	v_lshl_add_u64 v[86:87], v[64:65], 1, v[78:79]
	v_cvt_pk_bf16_f32 v83, v84, v85
	v_or_b32_sdwa v82, v88, v82 dst_sel:DWORD dst_unused:UNUSED_PAD src0_sel:DWORD src1_sel:WORD_1
	global_store_dwordx2 v[86:87], v[82:83], off

.Ltail327:
	s_add_i32 s0, s1, 2
	v_add_u32_e32 v127, v89, v90
	ds_read_b128 v[100:103], v127 offset:16384
	ds_read_b128 v[106:109], v127 offset:18432
	ds_read_b128 v[110:113], v127 offset:20480
	ds_read_b128 v[114:117], v127 offset:22528
	v_add_u32_e32 v126, v88, v90
	ds_read_b128 v[92:95], v126
	ds_read_b128 v[96:99], v126 offset:2048
	s_add_i32 s1, s1, 4
	s_min_u32 s1, s1, 63
	v_add_u32_e32 v128, v88, v91
	v_add_u32_e32 v130, v89, v91
	s_lshl_b32 s92, s1, 7
	ds_read_b128 v[118:121], v130 offset:18432
	ds_read_b128 v[122:125], v130 offset:20480
	ds_read_b128 v[132:135], v130 offset:22528
	s_waitcnt lgkmcnt(4)
	v_mfma_f32_16x16x32_bf16 v[76:79], v[100:103], v[92:95], v[76:79]
	v_lshl_add_u64 v[48:49], v[80:81], 0, s[92:93]
	v_add_co_u32_e32 v50, vcc, s7, v48
	v_mfma_f32_16x16x32_bf16 v[56:59], v[106:109], v[92:95], v[56:59]
	s_nop 0
	v_addc_co_u32_e32 v51, vcc, 0, v49, vcc
	v_mfma_f32_16x16x32_bf16 v[44:47], v[110:113], v[92:95], v[44:47]
	v_mfma_f32_16x16x32_bf16 v[24:27], v[114:117], v[92:95], v[24:27]
	s_waitcnt lgkmcnt(3)
	v_mfma_f32_16x16x32_bf16 v[92:95], v[100:103], v[96:99], v[12:15]
	s_nop 2
	ds_read_b128 v[12:15], v128
	v_mfma_f32_16x16x32_bf16 v[100:103], v[106:109], v[96:99], v[8:11]
	v_mfma_f32_16x16x32_bf16 v[106:109], v[110:113], v[96:99], v[4:7]
	ds_read_b128 v[110:113], v128 offset:2048
	v_mfma_f32_16x16x32_bf16 v[96:99], v[114:117], v[96:99], v[0:3]
	ds_read_b128 v[114:117], v130 offset:16384
	s_waitcnt vmcnt(0)
	ds_write_b128 v87, v[16:19] offset:53248
	v_add_co_u32_e32 v50, vcc, s52, v48
	s_waitcnt vmcnt(1)
	ds_write_b128 v87, v[20:23] offset:49152
	s_nop 0
	v_addc_co_u32_e32 v51, vcc, 0, v49, vcc
	v_add_co_u32_e32 v48, vcc, s34, v48
	s_nop 0
	s_nop 0
	v_addc_co_u32_e32 v49, vcc, 0, v49, vcc
	s_waitcnt vmcnt(2)
	ds_write_b128 v87, v[28:31] offset:45056
	v_lshl_add_u64 v[48:49], v[82:83], 0, s[92:93]
	s_waitcnt vmcnt(5)
	ds_write_b128 v87, v[36:39] offset:32768
	s_waitcnt lgkmcnt(4)
	v_mfma_f32_16x16x32_bf16 v[0:3], v[114:117], v[12:15], v[76:79]
	v_mfma_f32_16x16x32_bf16 v[4:7], v[118:121], v[12:15], v[56:59]
	v_add_co_u32_e32 v48, vcc, s7, v48
	s_waitcnt vmcnt(4)
	ds_write_b128 v87, v[40:43] offset:36864
	s_nop 0
	v_addc_co_u32_e32 v49, vcc, 0, v49, vcc
	v_mfma_f32_16x16x32_bf16 v[8:11], v[122:125], v[12:15], v[44:47]
	v_mfma_f32_16x16x32_bf16 v[12:15], v[132:135], v[12:15], v[24:27]
	s_waitcnt vmcnt(3)
	ds_write_b128 v87, v[32:35] offset:40960
	v_mfma_f32_16x16x32_bf16 v[24:27], v[114:117], v[110:113], v[92:95]
	v_mfma_f32_16x16x32_bf16 v[44:47], v[118:121], v[110:113], v[100:103]
	v_mfma_f32_16x16x32_bf16 v[56:59], v[122:125], v[110:113], v[106:109]
	v_mfma_f32_16x16x32_bf16 v[76:79], v[132:135], v[110:113], v[96:99]
	s_waitcnt lgkmcnt(0)
	s_barrier
	ds_read_b128 v[100:103], v127 offset:49152
	ds_read_b128 v[106:109], v127 offset:51200
	ds_read_b128 v[110:113], v127 offset:53248
	ds_read_b128 v[114:117], v127 offset:55296
	ds_read_b128 v[92:95], v126 offset:32768
	ds_read_b128 v[96:99], v126 offset:34816
	s_min_u32 s1, s0, 60
	s_lshl_b32 s92, s1, 7
	ds_read_b128 v[118:121], v130 offset:51200
	ds_read_b128 v[122:125], v130 offset:53248
	ds_read_b128 v[132:135], v130 offset:55296
	s_waitcnt lgkmcnt(4)
	v_mfma_f32_16x16x32_bf16 v[0:3], v[100:103], v[92:95], v[0:3]
	v_lshl_add_u64 v[16:17], v[80:81], 0, s[92:93]
	v_add_co_u32_e32 v18, vcc, s7, v16
	v_mfma_f32_16x16x32_bf16 v[4:7], v[106:109], v[92:95], v[4:7]
	s_nop 0
	v_addc_co_u32_e32 v19, vcc, 0, v17, vcc
	v_mfma_f32_16x16x32_bf16 v[8:11], v[110:113], v[92:95], v[8:11]
	v_mfma_f32_16x16x32_bf16 v[12:15], v[114:117], v[92:95], v[12:15]
	s_waitcnt lgkmcnt(3)
	v_mfma_f32_16x16x32_bf16 v[92:95], v[100:103], v[96:99], v[24:27]
	s_nop 2
	ds_read_b128 v[24:27], v128 offset:32768
	v_mfma_f32_16x16x32_bf16 v[100:103], v[106:109], v[96:99], v[44:47]
	v_mfma_f32_16x16x32_bf16 v[106:109], v[110:113], v[96:99], v[56:59]
	ds_read_b128 v[110:113], v128 offset:34816
	v_mfma_f32_16x16x32_bf16 v[96:99], v[114:117], v[96:99], v[76:79]
	ds_read_b128 v[114:117], v130 offset:49152
	v_add_co_u32_e32 v18, vcc, s52, v16
	s_nop 0
	s_nop 0
	v_addc_co_u32_e32 v19, vcc, 0, v17, vcc
	v_add_co_u32_e32 v16, vcc, s34, v16
	s_nop 0
	s_nop 0
	v_addc_co_u32_e32 v17, vcc, 0, v17, vcc
	v_lshl_add_u64 v[16:17], v[82:83], 0, s[92:93]
	s_waitcnt lgkmcnt(0)
	v_mfma_f32_16x16x32_bf16 v[76:79], v[114:117], v[24:27], v[0:3]
	v_mfma_f32_16x16x32_bf16 v[56:59], v[118:121], v[24:27], v[4:7]
	v_add_co_u32_e32 v16, vcc, s7, v16
	s_nop 0
	s_nop 0
	v_addc_co_u32_e32 v17, vcc, 0, v17, vcc
	v_mfma_f32_16x16x32_bf16 v[44:47], v[122:125], v[24:27], v[8:11]
	v_mfma_f32_16x16x32_bf16 v[24:27], v[132:135], v[24:27], v[12:15]
	v_mfma_f32_16x16x32_bf16 v[12:15], v[114:117], v[110:113], v[92:95]
	v_mfma_f32_16x16x32_bf16 v[8:11], v[118:121], v[110:113], v[100:103]
	v_mfma_f32_16x16x32_bf16 v[4:7], v[122:125], v[110:113], v[106:109]
	v_mfma_f32_16x16x32_bf16 v[0:3], v[132:135], v[110:113], v[96:99]
	s_mov_b32 s1, s0
	s_waitcnt lgkmcnt(0)
	v_readlane_b32 s0, v251, 18
	s_nop 1
	v_add_u32_e32 v48, s0, v86
	v_readlane_b32 s0, v251, 19
	s_waitcnt vmcnt(0)
	v_add_u32_e32 v16, 0xffffe000, v48
	v_or_b32_e32 v34, v48, v85
	v_lshl_or_b32 v32, v84, 2, s0
	v_lshrrev_b32_e32 v16, 10, v16
	s_movk_i32 s0, 0x1800
	v_mad_u32_u24 v16, v16, s0, s0
	v_cmp_lt_i32_e32 vcc, s13, v34
	v_ashrrev_i32_e32 v35, 31, v34
	v_lshlrev_b32_e32 v128, 2, v32
	v_cndmask_b32_e32 v28, 0, v16, vcc
	v_ashrrev_i32_e32 v29, 31, v28
	v_lshl_add_u64 v[16:17], v[28:29], 2, s[40:41]
	v_readlane_b32 s0, v250, 15
	v_lshl_add_u64 v[40:41], v[16:17], 0, v[128:129]
	v_lshlrev_b64 v[16:17], 12, v[34:35]
	v_readlane_b32 s1, v250, 16
	v_lshlrev_b64 v[30:31], 10, v[34:35]
	s_and_b64 vcc, exec, s[36:37]
	v_lshl_add_u64 v[16:17], s[0:1], 0, v[16:17]
	v_lshl_add_u64 v[38:39], v[16:17], 0, v[128:129]
	global_load_dwordx4 v[60:63], v[40:41], off
	global_load_dwordx4 v[72:75], v[40:41], off offset:64
	global_load_dwordx4 v[80:83], v[40:41], off offset:128
	global_load_dwordx4 v[88:91], v[40:41], off offset:192
	global_load_dwordx4 v[190:193], v[38:39], off
	global_load_dwordx4 v[194:197], v[38:39], off offset:64
	global_load_dwordx4 v[198:201], v[38:39], off offset:128
	global_load_dwordx4 v[202:205], v[38:39], off offset:192
	v_add_co_u32_e32 v54, vcc, 0x10000, v38
	s_nop 1
	v_addc_co_u32_e32 v55, vcc, 0, v39, vcc
	global_load_dwordx4 v[206:209], v[54:55], off
	global_load_dwordx4 v[210:213], v[54:55], off offset:64
	global_load_dwordx4 v[214:217], v[54:55], off offset:128
	global_load_dwordx4 v[218:221], v[54:55], off offset:192
	v_readlane_b32 s0, v250, 21
	v_readlane_b32 s1, v250, 22
	v_lshl_add_u64 v[42:43], v[28:29], 2, s[42:43]
	v_lshlrev_b32_e32 v32, 1, v32
	v_lshl_add_u64 v[36:37], v[30:31], 1, s[0:1]
	s_waitcnt vmcnt(4)
	v_pk_fma_f32 v[18:19], v[78:79], v[62:63], v[192:193]
	v_pk_fma_f32 v[16:17], v[76:77], v[60:61], v[190:191]
	global_store_dwordx4 v[38:39], v[16:19], off
	s_cbranch_vccnz .LBB0_330
	v_lshl_add_u64 v[28:29], v[42:43], 0, v[128:129]
	global_load_dwordx4 v[136:139], v128, s[26:27]
	global_load_dwordx4 v[140:143], v128, s[26:27] offset:64
	global_load_dwordx4 v[144:147], v128, s[26:27] offset:128
	global_load_dwordx4 v[148:151], v128, s[26:27] offset:192
	v_mov_b32_e32 v33, v129
	global_load_dwordx4 v[152:155], v[28:29], off
	global_load_dwordx4 v[156:159], v[28:29], off offset:64
	global_load_dwordx4 v[160:163], v[28:29], off offset:128
	global_load_dwordx4 v[180:183], v[28:29], off offset:192
	s_waitcnt vmcnt(0)
	v_pk_mul_f32 v[22:23], v[18:19], v[138:139]
	v_pk_mul_f32 v[20:21], v[16:17], v[136:137]
	s_waitcnt vmcnt(0)
	v_pk_add_f32 v[30:31], v[154:155], 1.0 op_sel_hi:[1,0]
	v_pk_add_f32 v[28:29], v[152:153], 1.0 op_sel_hi:[1,0]
	v_pk_mul_f32 v[22:23], v[22:23], v[30:31]
	v_pk_mul_f32 v[20:21], v[20:21], v[28:29]
	v_and_b32_sdwa v31, v20, v170 dst_sel:DWORD dst_unused:UNUSED_PAD src0_sel:WORD_1 src1_sel:DWORD
	v_add3_u32 v20, v20, v31, s56
	v_and_b32_sdwa v31, v21, v170 dst_sel:DWORD dst_unused:UNUSED_PAD src0_sel:WORD_1 src1_sel:DWORD
	v_add3_u32 v21, v21, v31, s56
	v_and_b32_e32 v30, 0xffff0000, v21
	v_lshl_add_u64 v[28:29], v[36:37], 0, v[32:33]
	v_cvt_pk_bf16_f32 v21, v22, v23
	v_or_b32_sdwa v20, v30, v20 dst_sel:DWORD dst_unused:UNUSED_PAD src0_sel:DWORD src1_sel:WORD_1
	global_store_dwordx2 v[28:29], v[20:21], off

.Ltail359:
	s_add_i32 s27, s28, 2
	v_add_u32_e32 v181, v144, v145
	ds_read_b128 v[80:83], v181 offset:16384
	ds_read_b128 v[84:87], v181 offset:18432
	ds_read_b128 v[88:91], v181 offset:20480
	ds_read_b128 v[92:95], v181 offset:22528
	v_add_u32_e32 v180, v143, v145
	ds_read_b128 v[64:67], v180
	s_add_i32 s28, s28, 4
	ds_read_b128 v[68:71], v180 offset:2048
	s_min_u32 s28, s28, 15
	s_lshl_b32 s92, s28, 7
	ds_read_b128 v[72:75], v180 offset:4096
	ds_read_b128 v[76:79], v180 offset:6144
	v_add_u32_e32 v182, v143, v146
	v_add_u32_e32 v186, v144, v146
	v_lshl_add_u64 v[224:225], v[138:139], 0, s[92:93]
	ds_read_b128 v[192:195], v182
	ds_read_b128 v[196:199], v182 offset:2048
	ds_read_b128 v[200:203], v182 offset:4096
	ds_read_b128 v[204:207], v182 offset:6144
	ds_read_b128 v[208:211], v186 offset:16384
	ds_read_b128 v[212:215], v186 offset:18432
	ds_read_b128 v[216:219], v186 offset:20480
	ds_read_b128 v[220:223], v186 offset:22528
	s_waitcnt lgkmcnt(11)
	v_mfma_f32_16x16x32_bf16 v[60:63], v[80:83], v[64:67], v[60:63]
	v_mfma_f32_16x16x32_bf16 v[56:59], v[84:87], v[64:67], v[56:59]
	v_mfma_f32_16x16x32_bf16 v[52:55], v[88:91], v[64:67], v[52:55]
	v_mfma_f32_16x16x32_bf16 v[48:51], v[92:95], v[64:67], v[48:51]
	s_waitcnt vmcnt(7)
	ds_write_b128 v156, v[96:99] offset:32768
	v_add_co_u32_e32 v96, vcc, s11, v224
	s_waitcnt lgkmcnt(11)
	v_mfma_f32_16x16x32_bf16 v[44:47], v[80:83], v[68:71], v[44:47]
	v_addc_co_u32_e32 v97, vcc, 0, v225, vcc
	v_mfma_f32_16x16x32_bf16 v[40:43], v[84:87], v[68:71], v[40:43]
	v_mfma_f32_16x16x32_bf16 v[36:39], v[88:91], v[68:71], v[36:39]
	v_mfma_f32_16x16x32_bf16 v[32:35], v[92:95], v[68:71], v[32:35]
	v_add_co_u32_e32 v96, vcc, s33, v224
	s_waitcnt vmcnt(6)
	ds_write_b128 v156, v[100:103] offset:36864
	s_nop 0
	v_addc_co_u32_e32 v97, vcc, 0, v225, vcc
	s_waitcnt lgkmcnt(11)
	v_mfma_f32_16x16x32_bf16 v[28:31], v[80:83], v[72:75], v[28:31]
	v_mfma_f32_16x16x32_bf16 v[24:27], v[84:87], v[72:75], v[24:27]
	v_mfma_f32_16x16x32_bf16 v[20:23], v[88:91], v[72:75], v[20:23]
	v_mfma_f32_16x16x32_bf16 v[16:19], v[92:95], v[72:75], v[16:19]
	s_waitcnt vmcnt(5)
	ds_write_b128 v156, v[104:107] offset:40960
	s_waitcnt lgkmcnt(11)
	v_mfma_f32_16x16x32_bf16 v[12:15], v[80:83], v[76:79], v[12:15]
	v_add_co_u32_e32 v80, vcc, s59, v224
	v_mfma_f32_16x16x32_bf16 v[0:3], v[92:95], v[76:79], v[0:3]
	s_nop 0
	v_addc_co_u32_e32 v81, vcc, 0, v225, vcc
	v_lshl_add_u64 v[92:93], v[140:141], 0, s[92:93]
	v_mfma_f32_16x16x32_bf16 v[8:11], v[84:87], v[76:79], v[8:11]
	v_add_co_u32_e32 v84, vcc, s11, v92
	s_nop 1
	v_addc_co_u32_e32 v85, vcc, 0, v93, vcc
	v_mfma_f32_16x16x32_bf16 v[4:7], v[88:91], v[76:79], v[4:7]
	v_add_co_u32_e32 v88, vcc, s33, v92
	s_nop 0
	s_nop 0
	v_addc_co_u32_e32 v89, vcc, 0, v93, vcc
	s_waitcnt vmcnt(4)
	ds_write_b128 v156, v[112:115] offset:45056
	s_waitcnt lgkmcnt(7)
	v_mfma_f32_16x16x32_bf16 v[60:63], v[208:211], v[192:195], v[60:63]
	s_waitcnt lgkmcnt(6)
	v_mfma_f32_16x16x32_bf16 v[56:59], v[212:215], v[192:195], v[56:59]
	s_waitcnt lgkmcnt(5)
	v_mfma_f32_16x16x32_bf16 v[52:55], v[216:219], v[192:195], v[52:55]
	s_waitcnt lgkmcnt(4)
	v_mfma_f32_16x16x32_bf16 v[48:51], v[220:223], v[192:195], v[48:51]
	v_add_co_u32_e32 v92, vcc, s59, v92
	s_waitcnt vmcnt(3)
	ds_write_b128 v156, v[108:111] offset:49152
	s_nop 0
	v_addc_co_u32_e32 v93, vcc, 0, v93, vcc
	v_mfma_f32_16x16x32_bf16 v[44:47], v[208:211], v[196:199], v[44:47]
	v_mfma_f32_16x16x32_bf16 v[40:43], v[212:215], v[196:199], v[40:43]
	v_mfma_f32_16x16x32_bf16 v[36:39], v[216:219], v[196:199], v[36:39]
	v_mfma_f32_16x16x32_bf16 v[32:35], v[220:223], v[196:199], v[32:35]
	s_waitcnt vmcnt(2)
	ds_write_b128 v156, v[116:119] offset:53248
	v_mfma_f32_16x16x32_bf16 v[28:31], v[208:211], v[200:203], v[28:31]
	v_mfma_f32_16x16x32_bf16 v[24:27], v[212:215], v[200:203], v[24:27]
	v_mfma_f32_16x16x32_bf16 v[20:23], v[216:219], v[200:203], v[20:23]
	v_mfma_f32_16x16x32_bf16 v[16:19], v[220:223], v[200:203], v[16:19]
	s_waitcnt vmcnt(1)
	ds_write_b128 v156, v[120:123] offset:57344
	v_mfma_f32_16x16x32_bf16 v[12:15], v[208:211], v[204:207], v[12:15]
	v_mfma_f32_16x16x32_bf16 v[8:11], v[212:215], v[204:207], v[8:11]
	v_mfma_f32_16x16x32_bf16 v[4:7], v[216:219], v[204:207], v[4:7]
	v_mfma_f32_16x16x32_bf16 v[0:3], v[220:223], v[204:207], v[0:3]
	s_waitcnt vmcnt(0)
	ds_write_b128 v156, v[124:127] offset:61440
	s_waitcnt lgkmcnt(0)
	s_barrier
	ds_read_b128 v[112:115], v181 offset:49152
	ds_read_b128 v[116:119], v181 offset:51200
	ds_read_b128 v[120:123], v181 offset:53248
	ds_read_b128 v[124:127], v181 offset:55296
	ds_read_b128 v[96:99], v180 offset:32768
	ds_read_b128 v[100:103], v180 offset:34816
	s_min_u32 s28, s27, 12
	s_lshl_b32 s92, s28, 7
	ds_read_b128 v[104:107], v180 offset:36864
	v_lshl_add_u64 v[224:225], v[138:139], 0, s[92:93]
	ds_read_b128 v[108:111], v180 offset:38912
	ds_read_b128 v[192:195], v182 offset:32768
	ds_read_b128 v[196:199], v182 offset:34816
	ds_read_b128 v[200:203], v182 offset:36864
	ds_read_b128 v[204:207], v182 offset:38912
	ds_read_b128 v[208:211], v186 offset:49152
	ds_read_b128 v[212:215], v186 offset:51200
	ds_read_b128 v[216:219], v186 offset:53248
	ds_read_b128 v[220:223], v186 offset:55296
	s_waitcnt lgkmcnt(11)
	v_mfma_f32_16x16x32_bf16 v[60:63], v[112:115], v[96:99], v[60:63]
	v_mfma_f32_16x16x32_bf16 v[56:59], v[116:119], v[96:99], v[56:59]
	v_mfma_f32_16x16x32_bf16 v[52:55], v[120:123], v[96:99], v[52:55]
	v_mfma_f32_16x16x32_bf16 v[48:51], v[124:127], v[96:99], v[48:51]
	v_add_co_u32_e32 v64, vcc, s11, v224
	s_waitcnt lgkmcnt(10)
	v_mfma_f32_16x16x32_bf16 v[44:47], v[112:115], v[100:103], v[44:47]
	v_addc_co_u32_e32 v65, vcc, 0, v225, vcc
	v_mfma_f32_16x16x32_bf16 v[40:43], v[116:119], v[100:103], v[40:43]
	v_mfma_f32_16x16x32_bf16 v[36:39], v[120:123], v[100:103], v[36:39]
	v_mfma_f32_16x16x32_bf16 v[32:35], v[124:127], v[100:103], v[32:35]
	v_add_co_u32_e32 v64, vcc, s33, v224
	s_nop 1
	v_addc_co_u32_e32 v65, vcc, 0, v225, vcc
	s_waitcnt lgkmcnt(9)
	v_mfma_f32_16x16x32_bf16 v[28:31], v[112:115], v[104:107], v[28:31]
	v_mfma_f32_16x16x32_bf16 v[24:27], v[116:119], v[104:107], v[24:27]
	v_mfma_f32_16x16x32_bf16 v[20:23], v[120:123], v[104:107], v[20:23]
	v_mfma_f32_16x16x32_bf16 v[16:19], v[124:127], v[104:107], v[16:19]
	v_add_co_u32_e32 v64, vcc, s59, v224
	s_nop 1
	v_addc_co_u32_e32 v65, vcc, 0, v225, vcc
	s_waitcnt lgkmcnt(8)
	v_mfma_f32_16x16x32_bf16 v[12:15], v[112:115], v[108:111], v[12:15]
	v_mfma_f32_16x16x32_bf16 v[8:11], v[116:119], v[108:111], v[8:11]
	v_mfma_f32_16x16x32_bf16 v[4:7], v[120:123], v[108:111], v[4:7]
	v_mfma_f32_16x16x32_bf16 v[0:3], v[124:127], v[108:111], v[0:3]
	v_lshl_add_u64 v[64:65], v[140:141], 0, s[92:93]
	v_add_co_u32_e32 v66, vcc, s11, v64
	s_nop 1
	v_addc_co_u32_e32 v67, vcc, 0, v65, vcc
	s_waitcnt lgkmcnt(3)
	v_mfma_f32_16x16x32_bf16 v[60:63], v[208:211], v[192:195], v[60:63]
	s_waitcnt lgkmcnt(2)
	v_mfma_f32_16x16x32_bf16 v[56:59], v[212:215], v[192:195], v[56:59]
	s_waitcnt lgkmcnt(1)
	v_mfma_f32_16x16x32_bf16 v[52:55], v[216:219], v[192:195], v[52:55]
	s_waitcnt lgkmcnt(0)
	v_mfma_f32_16x16x32_bf16 v[48:51], v[220:223], v[192:195], v[48:51]
	v_mfma_f32_16x16x32_bf16 v[44:47], v[208:211], v[196:199], v[44:47]
	v_mfma_f32_16x16x32_bf16 v[40:43], v[212:215], v[196:199], v[40:43]
	v_mfma_f32_16x16x32_bf16 v[36:39], v[216:219], v[196:199], v[36:39]
	v_mfma_f32_16x16x32_bf16 v[32:35], v[220:223], v[196:199], v[32:35]
	v_add_co_u32_e32 v66, vcc, s33, v64
	s_nop 1
	v_addc_co_u32_e32 v67, vcc, 0, v65, vcc
	v_add_co_u32_e32 v64, vcc, s59, v64
	v_mfma_f32_16x16x32_bf16 v[28:31], v[208:211], v[200:203], v[28:31]
	s_nop 0
	v_addc_co_u32_e32 v65, vcc, 0, v65, vcc
	v_mfma_f32_16x16x32_bf16 v[24:27], v[212:215], v[200:203], v[24:27]
	v_mfma_f32_16x16x32_bf16 v[20:23], v[216:219], v[200:203], v[20:23]
	v_mfma_f32_16x16x32_bf16 v[16:19], v[220:223], v[200:203], v[16:19]
	v_mfma_f32_16x16x32_bf16 v[12:15], v[208:211], v[204:207], v[12:15]
	v_mfma_f32_16x16x32_bf16 v[8:11], v[212:215], v[204:207], v[8:11]
	v_mfma_f32_16x16x32_bf16 v[4:7], v[216:219], v[204:207], v[4:7]
	v_mfma_f32_16x16x32_bf16 v[0:3], v[220:223], v[204:207], v[0:3]
	s_mov_b32 s28, s27
	s_waitcnt lgkmcnt(0)
	s_and_saveexec_b64 s[28:29], s[36:37]
	s_cbranch_execz .LBB0_353
	v_add_f32_e32 v64, 0, v128
	v_add_f32_e32 v64, v64, v157
	v_add_f32_e32 v64, v64, v158
	v_add_f32_e32 v64, v64, v159
	v_add_f32_e32 v64, v64, v160
	v_add_f32_e32 v64, v64, v161
	v_add_f32_e32 v64, v64, v162
	v_add_f32_e32 v64, v64, v163
	v_add_f32_e32 v64, v64, v164
	v_add_f32_e32 v64, v64, v165
	v_add_f32_e32 v64, v64, v168
	v_add_f32_e32 v64, v64, v175
	v_add_f32_e32 v64, v64, v179
	v_add_f32_e32 v64, v64, v183
	v_add_f32_e32 v64, v64, v190
	v_add_f32_e32 v64, v64, v191
	v_fmamk_f32 v64, v64, 0x3a800000, v167
	s_mov_b32 s16, 0x800000
	v_mul_f32_e32 v65, 0x4b800000, v64
	v_cmp_gt_f32_e32 vcc, s16, v64
	s_nop 1
	v_cndmask_b32_e32 v64, v64, v65, vcc
	v_rsq_f32_e32 v64, v64
	s_nop 0
	v_mul_f32_e32 v65, 0x45800000, v64
	v_cndmask_b32_e32 v64, v64, v65, vcc
	ds_write_b32 v155, v64
	s_branch .LBB0_353

.Ltail372:
	s_add_i32 s3, s24, 2
	v_add_u32_e32 v180, v142, v144
	ds_read_b128 v[44:47], v180
	ds_read_b128 v[48:51], v180 offset:2048
	v_add_u32_e32 v181, v143, v144
	ds_read_b128 v[52:55], v180 offset:4096
	ds_read_b128 v[56:59], v180 offset:6144
	ds_read_b128 v[60:63], v181 offset:16384
	ds_read_b128 v[68:71], v181 offset:18432
	ds_read_b128 v[72:75], v181 offset:20480
	ds_read_b128 v[76:79], v181 offset:22528
	v_add_u32_e32 v182, v142, v145
	s_add_i32 s24, s24, 4
	ds_read_b128 v[192:195], v182
	s_min_u32 s24, s24, 15
	s_lshl_b32 s92, s24, 7
	v_add_u32_e32 v186, v143, v145
	v_lshl_add_u64 v[224:225], v[138:139], 0, s[92:93]
	ds_read_b128 v[196:199], v182 offset:2048
	ds_read_b128 v[200:203], v182 offset:4096
	ds_read_b128 v[204:207], v182 offset:6144
	ds_read_b128 v[208:211], v186 offset:16384
	ds_read_b128 v[212:215], v186 offset:18432
	ds_read_b128 v[216:219], v186 offset:20480
	ds_read_b128 v[220:223], v186 offset:22528
	s_waitcnt lgkmcnt(11)
	v_mfma_f32_16x16x32_bf16 v[92:95], v[44:47], v[60:63], v[92:95]
	s_waitcnt lgkmcnt(10)
	v_mfma_f32_16x16x32_bf16 v[88:91], v[44:47], v[68:71], v[88:91]
	s_waitcnt lgkmcnt(9)
	v_mfma_f32_16x16x32_bf16 v[84:87], v[44:47], v[72:75], v[84:87]
	s_waitcnt lgkmcnt(8)
	v_mfma_f32_16x16x32_bf16 v[44:47], v[44:47], v[76:79], v[80:83]
	s_nop 2
	s_waitcnt vmcnt(7)
	ds_write_b128 v156, v[96:99] offset:32768
	v_add_co_u32_e32 v96, vcc, s11, v224
	v_mfma_f32_16x16x32_bf16 v[64:67], v[48:51], v[60:63], v[64:67]
	s_nop 0
	v_addc_co_u32_e32 v97, vcc, 0, v225, vcc
	v_mfma_f32_16x16x32_bf16 v[40:43], v[48:51], v[68:71], v[40:43]
	v_mfma_f32_16x16x32_bf16 v[36:39], v[48:51], v[72:75], v[36:39]
	v_mfma_f32_16x16x32_bf16 v[32:35], v[48:51], v[76:79], v[32:35]
	v_add_co_u32_e32 v96, vcc, s33, v224
	s_waitcnt vmcnt(6)
	ds_write_b128 v156, v[100:103] offset:36864
	s_nop 0
	v_addc_co_u32_e32 v97, vcc, 0, v225, vcc
	v_mfma_f32_16x16x32_bf16 v[28:31], v[52:55], v[60:63], v[28:31]
	v_mfma_f32_16x16x32_bf16 v[24:27], v[52:55], v[68:71], v[24:27]
	v_mfma_f32_16x16x32_bf16 v[20:23], v[52:55], v[72:75], v[20:23]
	v_mfma_f32_16x16x32_bf16 v[16:19], v[52:55], v[76:79], v[16:19]
	s_waitcnt vmcnt(5)
	ds_write_b128 v156, v[104:107] offset:40960
	v_mfma_f32_16x16x32_bf16 v[12:15], v[56:59], v[60:63], v[12:15]
	v_add_co_u32_e32 v60, vcc, s59, v224
	s_nop 1
	v_addc_co_u32_e32 v61, vcc, 0, v225, vcc
	v_mfma_f32_16x16x32_bf16 v[8:11], v[56:59], v[68:71], v[8:11]
	v_mfma_f32_16x16x32_bf16 v[4:7], v[56:59], v[72:75], v[4:7]
	v_mfma_f32_16x16x32_bf16 v[0:3], v[56:59], v[76:79], v[0:3]
	s_waitcnt vmcnt(4)
	ds_write_b128 v156, v[112:115] offset:45056
	s_waitcnt lgkmcnt(5)
	v_mfma_f32_16x16x32_bf16 v[72:75], v[192:195], v[216:219], v[84:87]
	s_nop 2
	v_lshl_add_u64 v[84:85], v[140:141], 0, s[92:93]
	v_add_co_u32_e32 v86, vcc, s11, v84
	v_mfma_f32_16x16x32_bf16 v[60:63], v[192:195], v[208:211], v[92:95]
	s_nop 0
	v_addc_co_u32_e32 v87, vcc, 0, v85, vcc
	v_mfma_f32_16x16x32_bf16 v[68:71], v[192:195], v[212:215], v[88:91]
	s_waitcnt lgkmcnt(4)
	v_mfma_f32_16x16x32_bf16 v[44:47], v[192:195], v[220:223], v[44:47]
	s_waitcnt vmcnt(3)
	ds_write_b128 v156, v[108:111] offset:49152
	v_mfma_f32_16x16x32_bf16 v[64:67], v[196:199], v[208:211], v[64:67]
	v_mfma_f32_16x16x32_bf16 v[40:43], v[196:199], v[212:215], v[40:43]
	v_mfma_f32_16x16x32_bf16 v[36:39], v[196:199], v[216:219], v[36:39]
	v_mfma_f32_16x16x32_bf16 v[32:35], v[196:199], v[220:223], v[32:35]
	v_add_co_u32_e32 v86, vcc, s33, v84
	s_waitcnt vmcnt(2)
	ds_write_b128 v156, v[116:119] offset:53248
	v_addc_co_u32_e32 v87, vcc, 0, v85, vcc
	v_add_co_u32_e32 v84, vcc, s59, v84
	v_mfma_f32_16x16x32_bf16 v[28:31], v[200:203], v[208:211], v[28:31]
	s_nop 0
	v_addc_co_u32_e32 v85, vcc, 0, v85, vcc
	v_mfma_f32_16x16x32_bf16 v[24:27], v[200:203], v[212:215], v[24:27]
	v_mfma_f32_16x16x32_bf16 v[20:23], v[200:203], v[216:219], v[20:23]
	v_mfma_f32_16x16x32_bf16 v[16:19], v[200:203], v[220:223], v[16:19]
	s_waitcnt vmcnt(1)
	ds_write_b128 v156, v[120:123] offset:57344
	v_mfma_f32_16x16x32_bf16 v[12:15], v[204:207], v[208:211], v[12:15]
	v_mfma_f32_16x16x32_bf16 v[8:11], v[204:207], v[212:215], v[8:11]
	v_mfma_f32_16x16x32_bf16 v[4:7], v[204:207], v[216:219], v[4:7]
	v_mfma_f32_16x16x32_bf16 v[0:3], v[204:207], v[220:223], v[0:3]
	s_waitcnt vmcnt(0)
	ds_write_b128 v156, v[124:127] offset:61440
	s_waitcnt lgkmcnt(0)
	s_barrier
	ds_read_b128 v[84:87], v180 offset:32768
	ds_read_b128 v[88:91], v180 offset:34816
	ds_read_b128 v[112:115], v181 offset:49152
	ds_read_b128 v[116:119], v181 offset:51200
	ds_read_b128 v[120:123], v181 offset:53248
	ds_read_b128 v[124:127], v181 offset:55296
	ds_read_b128 v[92:95], v180 offset:36864
	ds_read_b128 v[108:111], v180 offset:38912
	ds_read_b128 v[204:207], v182 offset:32768
	s_min_u32 s24, s3, 12
	s_lshl_b32 s92, s24, 7
	ds_read_b128 v[208:211], v182 offset:34816
	ds_read_b128 v[212:215], v182 offset:36864
	ds_read_b128 v[216:219], v182 offset:38912
	ds_read_b128 v[220:223], v186 offset:49152
	ds_read_b128 v[224:227], v186 offset:51200
	ds_read_b128 v[228:231], v186 offset:53248
	ds_read_b128 v[232:235], v186 offset:55296
	s_waitcnt lgkmcnt(13)
	v_mfma_f32_16x16x32_bf16 v[60:63], v[84:87], v[112:115], v[60:63]
	s_waitcnt lgkmcnt(12)
	v_mfma_f32_16x16x32_bf16 v[68:71], v[84:87], v[116:119], v[68:71]
	s_waitcnt lgkmcnt(11)
	v_mfma_f32_16x16x32_bf16 v[72:75], v[84:87], v[120:123], v[72:75]
	s_waitcnt lgkmcnt(10)
	v_mfma_f32_16x16x32_bf16 v[44:47], v[84:87], v[124:127], v[44:47]
	v_lshl_add_u64 v[84:85], v[138:139], 0, s[92:93]
	v_add_co_u32_e32 v80, vcc, s11, v84
	v_mfma_f32_16x16x32_bf16 v[64:67], v[88:91], v[112:115], v[64:67]
	s_nop 0
	v_addc_co_u32_e32 v81, vcc, 0, v85, vcc
	v_mfma_f32_16x16x32_bf16 v[40:43], v[88:91], v[116:119], v[40:43]
	v_mfma_f32_16x16x32_bf16 v[36:39], v[88:91], v[120:123], v[36:39]
	v_mfma_f32_16x16x32_bf16 v[32:35], v[88:91], v[124:127], v[32:35]
	v_add_co_u32_e32 v48, vcc, s33, v84
	s_waitcnt lgkmcnt(9)
	v_mfma_f32_16x16x32_bf16 v[28:31], v[92:95], v[112:115], v[28:31]
	v_addc_co_u32_e32 v49, vcc, 0, v85, vcc
	v_mfma_f32_16x16x32_bf16 v[24:27], v[92:95], v[116:119], v[24:27]
	v_mfma_f32_16x16x32_bf16 v[20:23], v[92:95], v[120:123], v[20:23]
	v_mfma_f32_16x16x32_bf16 v[16:19], v[92:95], v[124:127], v[16:19]
	v_add_co_u32_e32 v48, vcc, s59, v84
	s_nop 1
	v_addc_co_u32_e32 v49, vcc, 0, v85, vcc
	s_waitcnt lgkmcnt(8)
	v_mfma_f32_16x16x32_bf16 v[12:15], v[108:111], v[112:115], v[12:15]
	v_mfma_f32_16x16x32_bf16 v[8:11], v[108:111], v[116:119], v[8:11]
	v_mfma_f32_16x16x32_bf16 v[4:7], v[108:111], v[120:123], v[4:7]
	v_mfma_f32_16x16x32_bf16 v[0:3], v[108:111], v[124:127], v[0:3]
	s_waitcnt lgkmcnt(0)
	v_mfma_f32_16x16x32_bf16 v[80:83], v[204:207], v[232:235], v[44:47]
	s_nop 2
	v_lshl_add_u64 v[44:45], v[140:141], 0, s[92:93]
	v_add_co_u32_e32 v46, vcc, s11, v44
	v_mfma_f32_16x16x32_bf16 v[92:95], v[204:207], v[220:223], v[60:63]
	s_nop 0
	v_addc_co_u32_e32 v47, vcc, 0, v45, vcc
	v_mfma_f32_16x16x32_bf16 v[88:91], v[204:207], v[224:227], v[68:71]
	v_mfma_f32_16x16x32_bf16 v[84:87], v[204:207], v[228:231], v[72:75]
	v_mfma_f32_16x16x32_bf16 v[64:67], v[208:211], v[220:223], v[64:67]
	v_mfma_f32_16x16x32_bf16 v[40:43], v[208:211], v[224:227], v[40:43]
	v_mfma_f32_16x16x32_bf16 v[36:39], v[208:211], v[228:231], v[36:39]
	v_mfma_f32_16x16x32_bf16 v[32:35], v[208:211], v[232:235], v[32:35]
	v_add_co_u32_e32 v46, vcc, s33, v44
	s_nop 1
	v_addc_co_u32_e32 v47, vcc, 0, v45, vcc
	v_add_co_u32_e32 v44, vcc, s59, v44
	v_mfma_f32_16x16x32_bf16 v[28:31], v[212:215], v[220:223], v[28:31]
	s_nop 0
	v_addc_co_u32_e32 v45, vcc, 0, v45, vcc
	v_mfma_f32_16x16x32_bf16 v[24:27], v[212:215], v[224:227], v[24:27]
	v_mfma_f32_16x16x32_bf16 v[20:23], v[212:215], v[228:231], v[20:23]
	v_mfma_f32_16x16x32_bf16 v[16:19], v[212:215], v[232:235], v[16:19]
	v_mfma_f32_16x16x32_bf16 v[12:15], v[216:219], v[220:223], v[12:15]
	v_mfma_f32_16x16x32_bf16 v[8:11], v[216:219], v[224:227], v[8:11]
	v_mfma_f32_16x16x32_bf16 v[4:7], v[216:219], v[228:231], v[4:7]
	v_mfma_f32_16x16x32_bf16 v[0:3], v[216:219], v[232:235], v[0:3]
	s_mov_b32 s24, s3
	s_waitcnt lgkmcnt(0)
	s_and_saveexec_b64 s[24:25], s[36:37]
	s_cbranch_execz .LBB0_366
	v_add_f32_e32 v44, 0, v128
	v_add_f32_e32 v44, v44, v157
	v_add_f32_e32 v44, v44, v158
	v_add_f32_e32 v44, v44, v159
	v_add_f32_e32 v44, v44, v160
	v_add_f32_e32 v44, v44, v161
	v_add_f32_e32 v44, v44, v162
	v_add_f32_e32 v44, v44, v163
	v_add_f32_e32 v44, v44, v164
	v_add_f32_e32 v44, v44, v165
	v_add_f32_e32 v44, v44, v168
	v_add_f32_e32 v44, v44, v175
	v_add_f32_e32 v44, v44, v179
	v_add_f32_e32 v44, v44, v183
	v_add_f32_e32 v44, v44, v190
	v_add_f32_e32 v44, v44, v191
	v_fmamk_f32 v44, v44, 0x3a800000, v167
	s_mov_b32 s3, 0x800000
	v_mul_f32_e32 v45, 0x4b800000, v44
	v_cmp_gt_f32_e32 vcc, s3, v44
	s_nop 1
	v_cndmask_b32_e32 v44, v44, v45, vcc
	v_rsq_f32_e32 v44, v44
	s_nop 0
	v_mul_f32_e32 v45, 0x45800000, v44
	v_cndmask_b32_e32 v44, v44, v45, vcc
	ds_write_b32 v155, v44
	s_branch .LBB0_366

.Ltail392:
	s_add_i32 s0, s1, 2
	v_add_u32_e32 v111, v104, v105
	ds_read_b128 v[136:139], v111 offset:16384
	ds_read_b128 v[140:143], v111 offset:18432
	ds_read_b128 v[144:147], v111 offset:20480
	ds_read_b128 v[148:151], v111 offset:22528
	v_add_u32_e32 v110, v103, v105
	ds_read_b128 v[116:119], v110
	s_add_i32 s1, s1, 4
	ds_read_b128 v[120:123], v110 offset:2048
	s_min_u32 s1, s1, 15
	v_add_u32_e32 v113, v104, v114
	s_lshl_b32 s92, s1, 7
	ds_read_b128 v[124:127], v110 offset:4096
	v_add_u32_e32 v112, v103, v114
	ds_read_b128 v[194:197], v113 offset:16384
	ds_read_b128 v[198:201], v113 offset:18432
	ds_read_b128 v[202:205], v113 offset:20480
	ds_read_b128 v[206:209], v113 offset:22528
	v_lshl_add_u64 v[164:165], v[98:99], 0, s[92:93]
	ds_read_b128 v[132:135], v110 offset:6144
	ds_read_b128 v[152:155], v112
	ds_read_b128 v[156:159], v112 offset:2048
	ds_read_b128 v[160:163], v112 offset:4096
	ds_read_b128 v[190:193], v112 offset:6144
	s_waitcnt lgkmcnt(11)
	v_mfma_f32_16x16x32_bf16 v[92:95], v[136:139], v[116:119], v[92:95]
	v_mfma_f32_16x16x32_bf16 v[88:91], v[140:143], v[116:119], v[88:91]
	v_mfma_f32_16x16x32_bf16 v[52:55], v[144:147], v[116:119], v[52:55]
	v_mfma_f32_16x16x32_bf16 v[48:51], v[148:151], v[116:119], v[48:51]
	s_waitcnt vmcnt(7)
	ds_write_b128 v109, v[56:59] offset:32768
	v_add_co_u32_e32 v56, vcc, s11, v164
	s_waitcnt lgkmcnt(11)
	v_mfma_f32_16x16x32_bf16 v[44:47], v[136:139], v[120:123], v[44:47]
	v_addc_co_u32_e32 v57, vcc, 0, v165, vcc
	v_mfma_f32_16x16x32_bf16 v[40:43], v[140:143], v[120:123], v[40:43]
	v_mfma_f32_16x16x32_bf16 v[36:39], v[144:147], v[120:123], v[36:39]
	v_mfma_f32_16x16x32_bf16 v[32:35], v[148:151], v[120:123], v[32:35]
	v_add_co_u32_e32 v56, vcc, s33, v164
	s_waitcnt vmcnt(6)
	ds_write_b128 v109, v[60:63] offset:36864
	s_nop 0
	v_addc_co_u32_e32 v57, vcc, 0, v165, vcc
	s_waitcnt lgkmcnt(11)
	v_mfma_f32_16x16x32_bf16 v[28:31], v[136:139], v[124:127], v[28:31]
	v_mfma_f32_16x16x32_bf16 v[24:27], v[140:143], v[124:127], v[24:27]
	v_mfma_f32_16x16x32_bf16 v[20:23], v[144:147], v[124:127], v[20:23]
	v_mfma_f32_16x16x32_bf16 v[16:19], v[148:151], v[124:127], v[16:19]
	v_add_co_u32_e32 v56, vcc, s59, v164
	s_waitcnt vmcnt(5)
	ds_write_b128 v109, v[64:67] offset:40960
	s_nop 0
	v_addc_co_u32_e32 v57, vcc, 0, v165, vcc
	v_lshl_add_u64 v[64:65], v[100:101], 0, s[92:93]
	v_add_co_u32_e32 v66, vcc, s11, v64
	s_waitcnt lgkmcnt(7)
	v_mfma_f32_16x16x32_bf16 v[12:15], v[136:139], v[132:135], v[12:15]
	v_addc_co_u32_e32 v67, vcc, 0, v65, vcc
	v_mfma_f32_16x16x32_bf16 v[8:11], v[140:143], v[132:135], v[8:11]
	v_mfma_f32_16x16x32_bf16 v[4:7], v[144:147], v[132:135], v[4:7]
	v_mfma_f32_16x16x32_bf16 v[0:3], v[148:151], v[132:135], v[0:3]
	s_waitcnt vmcnt(4)
	ds_write_b128 v109, v[72:75] offset:45056
	s_waitcnt lgkmcnt(7)
	v_mfma_f32_16x16x32_bf16 v[56:59], v[194:197], v[152:155], v[92:95]
	v_mfma_f32_16x16x32_bf16 v[60:63], v[198:201], v[152:155], v[88:91]
	v_mfma_f32_16x16x32_bf16 v[52:55], v[202:205], v[152:155], v[52:55]
	v_mfma_f32_16x16x32_bf16 v[48:51], v[206:209], v[152:155], v[48:51]
	s_waitcnt vmcnt(3)
	ds_write_b128 v109, v[68:71] offset:49152
	s_waitcnt lgkmcnt(7)
	v_mfma_f32_16x16x32_bf16 v[44:47], v[194:197], v[156:159], v[44:47]
	v_mfma_f32_16x16x32_bf16 v[40:43], v[198:201], v[156:159], v[40:43]
	v_mfma_f32_16x16x32_bf16 v[36:39], v[202:205], v[156:159], v[36:39]
	v_mfma_f32_16x16x32_bf16 v[32:35], v[206:209], v[156:159], v[32:35]
	v_add_co_u32_e32 v66, vcc, s33, v64
	s_waitcnt vmcnt(2)
	ds_write_b128 v109, v[76:79] offset:53248
	v_addc_co_u32_e32 v67, vcc, 0, v65, vcc
	v_add_co_u32_e32 v64, vcc, s59, v64
	s_waitcnt lgkmcnt(7)
	v_mfma_f32_16x16x32_bf16 v[28:31], v[194:197], v[160:163], v[28:31]
	v_addc_co_u32_e32 v65, vcc, 0, v65, vcc
	v_mfma_f32_16x16x32_bf16 v[24:27], v[198:201], v[160:163], v[24:27]
	v_mfma_f32_16x16x32_bf16 v[20:23], v[202:205], v[160:163], v[20:23]
	v_mfma_f32_16x16x32_bf16 v[16:19], v[206:209], v[160:163], v[16:19]
	s_waitcnt vmcnt(1)
	ds_write_b128 v109, v[80:83] offset:57344
	s_waitcnt lgkmcnt(7)
	v_mfma_f32_16x16x32_bf16 v[12:15], v[194:197], v[190:193], v[12:15]
	v_mfma_f32_16x16x32_bf16 v[8:11], v[198:201], v[190:193], v[8:11]
	v_mfma_f32_16x16x32_bf16 v[4:7], v[202:205], v[190:193], v[4:7]
	v_mfma_f32_16x16x32_bf16 v[0:3], v[206:209], v[190:193], v[0:3]
	s_waitcnt vmcnt(0)
	ds_write_b128 v109, v[84:87] offset:61440
	s_waitcnt lgkmcnt(0)
	s_barrier
	ds_read_b128 v[84:87], v111 offset:51200
	ds_read_b128 v[80:83], v111 offset:49152
	ds_read_b128 v[88:91], v111 offset:53248
	ds_read_b128 v[92:95], v111 offset:55296
	ds_read_b128 v[64:67], v110 offset:32768
	s_min_u32 s1, s0, 12
	s_lshl_b32 s92, s1, 7
	ds_read_b128 v[68:71], v110 offset:34816
	v_lshl_add_u64 v[164:165], v[98:99], 0, s[92:93]
	ds_read_b128 v[72:75], v110 offset:36864
	ds_read_b128 v[76:79], v110 offset:38912
	ds_read_b128 v[152:155], v112 offset:32768
	ds_read_b128 v[156:159], v112 offset:34816
	ds_read_b128 v[160:163], v112 offset:36864
	ds_read_b128 v[190:193], v112 offset:38912
	ds_read_b128 v[194:197], v113 offset:49152
	ds_read_b128 v[198:201], v113 offset:51200
	ds_read_b128 v[202:205], v113 offset:53248
	ds_read_b128 v[206:209], v113 offset:55296
	s_waitcnt lgkmcnt(11)
	v_mfma_f32_16x16x32_bf16 v[214:217], v[84:87], v[64:67], v[60:63]
	v_mfma_f32_16x16x32_bf16 v[210:213], v[80:83], v[64:67], v[56:59]
	s_nop 1
	v_add_co_u32_e32 v60, vcc, s11, v164
	s_nop 1
	v_addc_co_u32_e32 v61, vcc, 0, v165, vcc
	v_mfma_f32_16x16x32_bf16 v[52:55], v[88:91], v[64:67], v[52:55]
	v_mfma_f32_16x16x32_bf16 v[48:51], v[92:95], v[64:67], v[48:51]
	v_add_co_u32_e32 v64, vcc, s33, v164
	s_nop 0
	s_nop 0
	v_addc_co_u32_e32 v65, vcc, 0, v165, vcc
	s_waitcnt lgkmcnt(10)
	v_mfma_f32_16x16x32_bf16 v[44:47], v[80:83], v[68:71], v[44:47]
	v_mfma_f32_16x16x32_bf16 v[40:43], v[84:87], v[68:71], v[40:43]
	v_mfma_f32_16x16x32_bf16 v[36:39], v[88:91], v[68:71], v[36:39]
	v_mfma_f32_16x16x32_bf16 v[32:35], v[92:95], v[68:71], v[32:35]
	v_add_co_u32_e32 v68, vcc, s59, v164
	s_waitcnt lgkmcnt(9)
	v_mfma_f32_16x16x32_bf16 v[28:31], v[80:83], v[72:75], v[28:31]
	v_addc_co_u32_e32 v69, vcc, 0, v165, vcc
	v_mfma_f32_16x16x32_bf16 v[24:27], v[84:87], v[72:75], v[24:27]
	v_mfma_f32_16x16x32_bf16 v[20:23], v[88:91], v[72:75], v[20:23]
	v_mfma_f32_16x16x32_bf16 v[16:19], v[92:95], v[72:75], v[16:19]
	s_waitcnt lgkmcnt(8)
	v_mfma_f32_16x16x32_bf16 v[8:11], v[84:87], v[76:79], v[8:11]
	v_lshl_add_u64 v[84:85], v[100:101], 0, s[92:93]
	v_mfma_f32_16x16x32_bf16 v[12:15], v[80:83], v[76:79], v[12:15]
	v_mfma_f32_16x16x32_bf16 v[4:7], v[88:91], v[76:79], v[4:7]
	v_mfma_f32_16x16x32_bf16 v[0:3], v[92:95], v[76:79], v[0:3]
	v_add_co_u32_e32 v76, vcc, s11, v84
	s_nop 0
	s_nop 0
	v_addc_co_u32_e32 v77, vcc, 0, v85, vcc
	v_add_co_u32_e32 v80, vcc, s33, v84
	s_nop 1
	v_addc_co_u32_e32 v81, vcc, 0, v85, vcc
	s_waitcnt lgkmcnt(3)
	v_mfma_f32_16x16x32_bf16 v[92:95], v[194:197], v[152:155], v[210:213]
	s_waitcnt lgkmcnt(2)
	v_mfma_f32_16x16x32_bf16 v[88:91], v[198:201], v[152:155], v[214:217]
	s_waitcnt lgkmcnt(1)
	v_mfma_f32_16x16x32_bf16 v[52:55], v[202:205], v[152:155], v[52:55]
	s_waitcnt lgkmcnt(0)
	v_mfma_f32_16x16x32_bf16 v[48:51], v[206:209], v[152:155], v[48:51]
	v_add_co_u32_e32 v84, vcc, s59, v84
	s_nop 1
	v_addc_co_u32_e32 v85, vcc, 0, v85, vcc
	v_mfma_f32_16x16x32_bf16 v[44:47], v[194:197], v[156:159], v[44:47]
	v_mfma_f32_16x16x32_bf16 v[40:43], v[198:201], v[156:159], v[40:43]
	v_mfma_f32_16x16x32_bf16 v[36:39], v[202:205], v[156:159], v[36:39]
	v_mfma_f32_16x16x32_bf16 v[32:35], v[206:209], v[156:159], v[32:35]
	v_mfma_f32_16x16x32_bf16 v[28:31], v[194:197], v[160:163], v[28:31]
	v_mfma_f32_16x16x32_bf16 v[24:27], v[198:201], v[160:163], v[24:27]
	v_mfma_f32_16x16x32_bf16 v[20:23], v[202:205], v[160:163], v[20:23]
	v_mfma_f32_16x16x32_bf16 v[16:19], v[206:209], v[160:163], v[16:19]
	v_mfma_f32_16x16x32_bf16 v[12:15], v[194:197], v[190:193], v[12:15]
	v_mfma_f32_16x16x32_bf16 v[8:11], v[198:201], v[190:193], v[8:11]
	v_mfma_f32_16x16x32_bf16 v[4:7], v[202:205], v[190:193], v[4:7]
	v_mfma_f32_16x16x32_bf16 v[0:3], v[206:209], v[190:193], v[0:3]
	s_mov_b32 s1, s0
	s_waitcnt lgkmcnt(0)
	s_mul_i32 s0, s69, 0x12000
	v_readlane_b32 s16, v250, 25
	s_add_u32 s24, s16, s0
	v_readlane_b32 s0, v251, 5
	v_lshlrev_b32_e32 v114, 6, v102
	v_readlane_b32 s17, v250, 26
	s_waitcnt vmcnt(5)
	v_add_u32_e32 v64, s0, v108
	v_readlane_b32 s0, v251, 6
	v_add_u32_e32 v56, 0xffffe000, v64
	v_or_b32_e32 v62, v64, v107
	v_or_b32_e32 v65, s0, v114
	v_lshrrev_b32_e32 v56, 10, v56
	s_movk_i32 s0, 0x1800
	v_mad_u32_u24 v56, v56, s0, s0
	v_cmp_lt_i32_e32 vcc, s13, v62
	s_addc_u32 s25, s17, 0
	v_lshlrev_b32_e32 v115, 2, v97
	v_cndmask_b32_e32 v56, 0, v56, vcc
	s_add_u32 s40, s24, 0x2000
	v_or_b32_e32 v58, v65, v115
	v_ashrrev_i32_e32 v57, 31, v56
	s_addc_u32 s41, s25, 0
	s_waitcnt vmcnt(4)
	v_lshlrev_b64 v[74:75], 2, v[56:57]
	v_ashrrev_i32_e32 v59, 31, v58
	v_ashrrev_i32_e32 v63, 31, v62
	v_lshl_add_u64 v[56:57], s[40:41], 0, v[74:75]
	v_lshlrev_b64 v[60:61], 2, v[58:59]
	v_readlane_b32 s0, v250, 15
	s_waitcnt vmcnt(1)
	v_lshl_add_u64 v[82:83], v[56:57], 0, v[60:61]
	v_lshlrev_b64 v[56:57], 12, v[62:63]
	v_readlane_b32 s1, v250, 16
	v_readlane_b32 s16, v250, 21
	v_lshlrev_b64 v[78:79], 11, v[62:63]
	v_lshl_add_u64 v[56:57], s[0:1], 0, v[56:57]
	s_waitcnt vmcnt(0)
	v_lshl_add_u64 v[84:85], v[56:57], 0, v[60:61]
	global_load_dwordx4 v[116:119], v[82:83], off
	global_load_dwordx4 v[120:123], v[82:83], off offset:64
	global_load_dwordx4 v[124:127], v[82:83], off offset:128
	global_load_dwordx4 v[132:135], v[82:83], off offset:192
	global_load_dwordx4 v[190:193], v[84:85], off
	global_load_dwordx4 v[194:197], v[84:85], off offset:64
	global_load_dwordx4 v[198:201], v[84:85], off offset:128
	global_load_dwordx4 v[202:205], v[84:85], off offset:192
	v_add_co_u32_e32 v164, vcc, 0x10000, v84
	s_nop 1
	v_addc_co_u32_e32 v165, vcc, 0, v85, vcc
	v_add_co_u32_e32 v222, vcc, 0x20000, v84
	s_nop 1
	v_addc_co_u32_e32 v223, vcc, 0, v85, vcc
	v_add_co_u32_e32 v224, vcc, 0x30000, v84
	s_nop 1
	v_addc_co_u32_e32 v225, vcc, 0, v85, vcc
	global_load_dwordx4 v[206:209], v[164:165], off
	global_load_dwordx4 v[210:213], v[164:165], off offset:64
	global_load_dwordx4 v[214:217], v[164:165], off offset:128
	global_load_dwordx4 v[218:221], v[164:165], off offset:192
	s_lshl_b32 s0, s69, 12
	v_readlane_b32 s68, v250, 41
	v_readlane_b32 s72, v250, 45
	v_readlane_b32 s73, v250, 46
	s_add_u32 s0, s72, s0
	s_addc_u32 s1, s73, 0
	s_add_u32 s42, s24, 0x4000
	s_addc_u32 s43, s25, 0
	v_lshl_add_u64 v[74:75], s[42:43], 0, v[74:75]
	v_lshl_add_u64 v[56:57], s[0:1], 0, v[60:61]
	v_lshl_add_u64 v[86:87], v[74:75], 0, v[60:61]
	v_readlane_b32 s17, v250, 22
	v_readlane_b32 s69, v250, 42
	v_readlane_b32 s69, v254, 49
	v_lshl_add_u64 v[78:79], s[16:17], 0, v[78:79]
	s_mul_i32 s24, s69, 0x140000
	s_add_u32 s24, s86, s24
	v_lshrrev_b32_e32 v65, 6, v65
	s_mov_b32 s16, 0xa000
	s_addc_u32 s25, s87, 0
	s_add_u32 s38, s24, 0xaf1a000
	s_addc_u32 s39, s25, 0
	v_cmp_eq_u32_e64 s[36:37], 0, v97
	v_readlane_b32 s70, v250, 43
	v_readlane_b32 s71, v250, 44
	v_readlane_b32 s74, v250, 47
	v_readlane_b32 s75, v250, 48
	v_readlane_b32 s76, v250, 49
	v_readlane_b32 s77, v250, 50
	v_readlane_b32 s78, v250, 51
	v_readlane_b32 s79, v250, 52
	v_readlane_b32 s80, v250, 53
	v_readlane_b32 s81, v250, 54
	v_readlane_b32 s82, v250, 55
	v_readlane_b32 s83, v250, 56
	s_waitcnt vmcnt(4)
	v_pk_fma_f32 v[68:69], v[94:95], v[118:119], v[192:193]
	v_pk_fma_f32 v[66:67], v[92:93], v[116:117], v[190:191]
	global_store_dwordx4 v[84:85], v[66:69], off
	global_load_dwordx4 v[136:139], v[56:57], off
	global_load_dwordx4 v[140:143], v[56:57], off offset:64
	global_load_dwordx4 v[144:147], v[56:57], off offset:128
	global_load_dwordx4 v[148:151], v[56:57], off offset:192
	global_load_dwordx4 v[152:155], v[86:87], off
	global_load_dwordx4 v[156:159], v[86:87], off offset:64
	global_load_dwordx4 v[160:163], v[86:87], off offset:128
	global_load_dwordx4 v[180:183], v[86:87], off offset:192
	v_lshl_add_u64 v[92:93], v[58:59], 1, v[78:79]
	s_waitcnt vmcnt(0)
	v_pk_mul_f32 v[72:73], v[68:69], v[138:139]
	v_pk_mul_f32 v[70:71], v[66:67], v[136:137]
	s_waitcnt vmcnt(0)
	v_pk_add_f32 v[76:77], v[154:155], 1.0 op_sel_hi:[1,0]
	v_pk_add_f32 v[74:75], v[152:153], 1.0 op_sel_hi:[1,0]
	v_pk_mul_f32 v[72:73], v[72:73], v[76:77]
	v_pk_mul_f32 v[70:71], v[70:71], v[74:75]
	v_and_b32_sdwa v77, v71, v170 dst_sel:DWORD dst_unused:UNUSED_PAD src0_sel:WORD_1 src1_sel:DWORD
	v_and_b32_sdwa v75, v70, v170 dst_sel:DWORD dst_unused:UNUSED_PAD src0_sel:WORD_1 src1_sel:DWORD
	v_add3_u32 v71, v71, v77, s56
	v_add3_u32 v70, v70, v75, s56
	v_and_b32_e32 v74, 0xffff0000, v71
	v_cvt_pk_bf16_f32 v71, v72, v73
	v_or_b32_sdwa v70, v74, v70 dst_sel:DWORD dst_unused:UNUSED_PAD src0_sel:DWORD src1_sel:WORD_1
	global_store_dwordx2 v[92:93], v[70:71], off
	s_nop 0
	s_waitcnt vmcnt(0)
	v_pk_fma_f32 v[72:73], v[90:91], v[122:123], v[196:197]
	v_pk_fma_f32 v[70:71], v[88:89], v[120:121], v[194:195]
	global_store_dwordx4 v[84:85], v[70:73], off offset:64
	v_pk_mul_f32 v[76:77], v[72:73], v[142:143]
	v_pk_mul_f32 v[74:75], v[70:71], v[140:141]
	v_pk_add_f32 v[80:81], v[158:159], 1.0 op_sel_hi:[1,0]
	v_pk_add_f32 v[78:79], v[156:157], 1.0 op_sel_hi:[1,0]
	v_pk_mul_f32 v[76:77], v[76:77], v[80:81]
	v_pk_mul_f32 v[74:75], v[74:75], v[78:79]
	v_and_b32_sdwa v81, v75, v170 dst_sel:DWORD dst_unused:UNUSED_PAD src0_sel:WORD_1 src1_sel:DWORD
	v_and_b32_sdwa v79, v74, v170 dst_sel:DWORD dst_unused:UNUSED_PAD src0_sel:WORD_1 src1_sel:DWORD
	v_add3_u32 v75, v75, v81, s56
	v_add3_u32 v74, v74, v79, s56
	v_and_b32_e32 v78, 0xffff0000, v75
	v_cvt_pk_bf16_f32 v75, v76, v77
	v_or_b32_sdwa v74, v78, v74 dst_sel:DWORD dst_unused:UNUSED_PAD src0_sel:DWORD src1_sel:WORD_1
	global_store_dwordx2 v[92:93], v[74:75], off offset:32
	s_nop 0
	v_pk_fma_f32 v[54:55], v[54:55], v[126:127], v[200:201]
	v_pk_fma_f32 v[52:53], v[52:53], v[124:125], v[198:199]
	global_store_dwordx4 v[84:85], v[52:55], off offset:128
	v_pk_mul_f32 v[76:77], v[54:55], v[146:147]
	v_pk_mul_f32 v[74:75], v[52:53], v[144:145]
	v_pk_add_f32 v[80:81], v[162:163], 1.0 op_sel_hi:[1,0]
	v_pk_add_f32 v[78:79], v[160:161], 1.0 op_sel_hi:[1,0]
	v_pk_mul_f32 v[76:77], v[76:77], v[80:81]
	v_pk_mul_f32 v[74:75], v[74:75], v[78:79]
	v_and_b32_sdwa v81, v75, v170 dst_sel:DWORD dst_unused:UNUSED_PAD src0_sel:WORD_1 src1_sel:DWORD
	v_and_b32_sdwa v79, v74, v170 dst_sel:DWORD dst_unused:UNUSED_PAD src0_sel:WORD_1 src1_sel:DWORD
	v_add3_u32 v75, v75, v81, s56
	v_add3_u32 v74, v74, v79, s56
	v_and_b32_e32 v78, 0xffff0000, v75
	v_cvt_pk_bf16_f32 v75, v76, v77
	v_or_b32_sdwa v74, v78, v74 dst_sel:DWORD dst_unused:UNUSED_PAD src0_sel:DWORD src1_sel:WORD_1
	global_store_dwordx2 v[92:93], v[74:75], off offset:64
	s_nop 0
	v_pk_fma_f32 v[76:77], v[50:51], v[134:135], v[204:205]
	v_pk_fma_f32 v[74:75], v[48:49], v[132:133], v[202:203]
	global_store_dwordx4 v[84:85], v[74:77], off offset:192
	s_nop 0
	v_mbcnt_lo_u32_b32 v48, -1, 0
	v_mbcnt_hi_u32_b32 v48, -1, v48
	v_and_b32_e32 v50, 64, v48
	v_xor_b32_e32 v49, 16, v48
	v_add_u32_e32 v50, 64, v50
	v_xor_b32_e32 v51, 32, v48
	v_cmp_lt_i32_e32 vcc, v49, v50
	s_nop 1
	v_cndmask_b32_e32 v49, v48, v49, vcc
	v_cmp_lt_i32_e32 vcc, v51, v50
	v_lshlrev_b32_e32 v105, 2, v49
	s_nop 0
	v_cndmask_b32_e32 v50, v48, v51, vcc
	v_lshlrev_b32_e32 v104, 2, v50
	v_mul_f32_e32 v50, v67, v67
	v_mul_f32_e32 v51, v71, v71
	v_fmac_f32_e32 v50, v66, v66
	v_fmac_f32_e32 v51, v70, v70
	v_fmac_f32_e32 v50, v68, v68
	v_fmac_f32_e32 v51, v72, v72
	v_fmac_f32_e32 v50, v69, v69
	v_fmac_f32_e32 v51, v73, v73
	v_add_f32_e32 v50, v50, v51
	v_mul_f32_e32 v51, v53, v53
	v_fmac_f32_e32 v51, v52, v52
	v_fmac_f32_e32 v51, v54, v54
	v_fmac_f32_e32 v51, v55, v55
	v_add_f32_e32 v50, v50, v51
	v_mul_f32_e32 v51, v75, v75
	v_fmac_f32_e32 v51, v74, v74
	v_fmac_f32_e32 v51, v76, v76
	v_fmac_f32_e32 v51, v77, v77
	v_add_f32_e32 v50, v50, v51
	ds_bpermute_b32 v51, v105, v50
	v_mul_lo_u32 v48, v65, s16
	v_ashrrev_i32_e32 v49, 31, v48
	v_lshl_add_u64 v[48:49], s[38:39], 0, v[48:49]
	v_lshl_add_u64 v[48:49], v[62:63], 2, v[48:49]
	s_waitcnt lgkmcnt(0)
	v_add_f32_e32 v50, v50, v51
	ds_bpermute_b32 v51, v104, v50
	v_pk_mul_f32 v[52:53], v[76:77], v[150:151]
	v_pk_mul_f32 v[54:55], v[74:75], v[148:149]
	v_pk_add_f32 v[66:67], v[182:183], 1.0 op_sel_hi:[1,0]
	v_pk_add_f32 v[68:69], v[180:181], 1.0 op_sel_hi:[1,0]
	v_pk_mul_f32 v[52:53], v[52:53], v[66:67]
	v_pk_mul_f32 v[54:55], v[54:55], v[68:69]
	v_cvt_pk_bf16_f32 v53, v52, v53
	v_cvt_pk_bf16_f32 v52, v54, v55
	global_store_dwordx2 v[92:93], v[52:53], off offset:96
	s_and_saveexec_b64 s[24:25], s[36:37]
	s_cbranch_execz .LBB0_395
	s_waitcnt lgkmcnt(0)
	v_add_f32_e32 v50, v50, v51
	global_store_dword v[48:49], v50, off

.Ltail406:
	s_add_i32 s29, s44, 2
	ds_read_b128 v[136:139], v111 offset:16384
	ds_read_b128 v[140:143], v111 offset:18432
	ds_read_b128 v[144:147], v111 offset:20480
	ds_read_b128 v[148:151], v111 offset:22528
	ds_read_b128 v[116:119], v110
	s_add_i32 s44, s44, 4
	ds_read_b128 v[120:123], v110 offset:2048
	s_min_u32 s44, s44, 15
	s_lshl_b32 s92, s44, 7
	ds_read_b128 v[124:127], v110 offset:4096
	ds_read_b128 v[194:197], v113 offset:16384
	ds_read_b128 v[198:201], v113 offset:18432
	ds_read_b128 v[202:205], v113 offset:20480
	ds_read_b128 v[206:209], v113 offset:22528
	v_lshl_add_u64 v[164:165], v[100:101], 0, s[92:93]
	ds_read_b128 v[132:135], v110 offset:6144
	ds_read_b128 v[152:155], v112
	ds_read_b128 v[156:159], v112 offset:2048
	ds_read_b128 v[160:163], v112 offset:4096
	ds_read_b128 v[190:193], v112 offset:6144
	s_waitcnt lgkmcnt(11)
	v_mfma_f32_16x16x32_bf16 v[92:95], v[136:139], v[116:119], v[92:95]
	v_mfma_f32_16x16x32_bf16 v[88:91], v[140:143], v[116:119], v[88:91]
	v_mfma_f32_16x16x32_bf16 v[56:59], v[144:147], v[116:119], v[56:59]
	v_mfma_f32_16x16x32_bf16 v[48:51], v[148:151], v[116:119], v[48:51]
	s_waitcnt vmcnt(7)
	ds_write_b128 v109, v[52:55] offset:32768
	v_add_co_u32_e32 v52, vcc, s11, v164
	s_waitcnt lgkmcnt(11)
	v_mfma_f32_16x16x32_bf16 v[44:47], v[136:139], v[120:123], v[44:47]
	v_addc_co_u32_e32 v53, vcc, 0, v165, vcc
	v_mfma_f32_16x16x32_bf16 v[40:43], v[140:143], v[120:123], v[40:43]
	v_mfma_f32_16x16x32_bf16 v[36:39], v[144:147], v[120:123], v[36:39]
	v_mfma_f32_16x16x32_bf16 v[32:35], v[148:151], v[120:123], v[32:35]
	v_add_co_u32_e32 v52, vcc, s33, v164
	s_waitcnt vmcnt(6)
	ds_write_b128 v109, v[60:63] offset:36864
	s_nop 0
	v_addc_co_u32_e32 v53, vcc, 0, v165, vcc
	s_waitcnt lgkmcnt(11)
	v_mfma_f32_16x16x32_bf16 v[28:31], v[136:139], v[124:127], v[28:31]
	v_mfma_f32_16x16x32_bf16 v[24:27], v[140:143], v[124:127], v[24:27]
	v_mfma_f32_16x16x32_bf16 v[20:23], v[144:147], v[124:127], v[20:23]
	v_mfma_f32_16x16x32_bf16 v[16:19], v[148:151], v[124:127], v[16:19]
	v_add_co_u32_e32 v52, vcc, s59, v164
	s_waitcnt vmcnt(5)
	ds_write_b128 v109, v[64:67] offset:40960
	s_nop 0
	v_addc_co_u32_e32 v53, vcc, 0, v165, vcc
	v_lshl_add_u64 v[64:65], v[102:103], 0, s[92:93]
	v_add_co_u32_e32 v66, vcc, s11, v64
	s_waitcnt lgkmcnt(7)
	v_mfma_f32_16x16x32_bf16 v[12:15], v[136:139], v[132:135], v[12:15]
	v_addc_co_u32_e32 v67, vcc, 0, v65, vcc
	v_mfma_f32_16x16x32_bf16 v[8:11], v[140:143], v[132:135], v[8:11]
	v_mfma_f32_16x16x32_bf16 v[4:7], v[144:147], v[132:135], v[4:7]
	v_mfma_f32_16x16x32_bf16 v[0:3], v[148:151], v[132:135], v[0:3]
	s_waitcnt vmcnt(4)
	ds_write_b128 v109, v[72:75] offset:45056
	s_waitcnt lgkmcnt(7)
	v_mfma_f32_16x16x32_bf16 v[52:55], v[194:197], v[152:155], v[92:95]
	v_mfma_f32_16x16x32_bf16 v[60:63], v[198:201], v[152:155], v[88:91]
	v_mfma_f32_16x16x32_bf16 v[56:59], v[202:205], v[152:155], v[56:59]
	v_mfma_f32_16x16x32_bf16 v[48:51], v[206:209], v[152:155], v[48:51]
	s_waitcnt vmcnt(3)
	ds_write_b128 v109, v[68:71] offset:49152
	s_waitcnt lgkmcnt(7)
	v_mfma_f32_16x16x32_bf16 v[44:47], v[194:197], v[156:159], v[44:47]
	v_mfma_f32_16x16x32_bf16 v[40:43], v[198:201], v[156:159], v[40:43]
	v_mfma_f32_16x16x32_bf16 v[36:39], v[202:205], v[156:159], v[36:39]
	v_mfma_f32_16x16x32_bf16 v[32:35], v[206:209], v[156:159], v[32:35]
	v_add_co_u32_e32 v66, vcc, s33, v64
	s_waitcnt vmcnt(2)
	ds_write_b128 v109, v[76:79] offset:53248
	v_addc_co_u32_e32 v67, vcc, 0, v65, vcc
	v_add_co_u32_e32 v64, vcc, s59, v64
	s_waitcnt lgkmcnt(7)
	v_mfma_f32_16x16x32_bf16 v[28:31], v[194:197], v[160:163], v[28:31]
	v_addc_co_u32_e32 v65, vcc, 0, v65, vcc
	v_mfma_f32_16x16x32_bf16 v[24:27], v[198:201], v[160:163], v[24:27]
	v_mfma_f32_16x16x32_bf16 v[20:23], v[202:205], v[160:163], v[20:23]
	v_mfma_f32_16x16x32_bf16 v[16:19], v[206:209], v[160:163], v[16:19]
	s_waitcnt vmcnt(1)
	ds_write_b128 v109, v[80:83] offset:57344
	s_waitcnt lgkmcnt(7)
	v_mfma_f32_16x16x32_bf16 v[12:15], v[194:197], v[190:193], v[12:15]
	v_mfma_f32_16x16x32_bf16 v[8:11], v[198:201], v[190:193], v[8:11]
	v_mfma_f32_16x16x32_bf16 v[4:7], v[202:205], v[190:193], v[4:7]
	v_mfma_f32_16x16x32_bf16 v[0:3], v[206:209], v[190:193], v[0:3]
	s_waitcnt vmcnt(0)
	ds_write_b128 v109, v[84:87] offset:61440
	s_waitcnt lgkmcnt(0)
	s_barrier
	ds_read_b128 v[84:87], v111 offset:51200
	ds_read_b128 v[80:83], v111 offset:49152
	ds_read_b128 v[88:91], v111 offset:53248
	ds_read_b128 v[92:95], v111 offset:55296
	ds_read_b128 v[64:67], v110 offset:32768
	s_min_u32 s44, s29, 12
	s_lshl_b32 s92, s44, 7
	ds_read_b128 v[68:71], v110 offset:34816
	v_lshl_add_u64 v[164:165], v[100:101], 0, s[92:93]
	ds_read_b128 v[72:75], v110 offset:36864
	ds_read_b128 v[76:79], v110 offset:38912
	ds_read_b128 v[152:155], v112 offset:32768
	ds_read_b128 v[156:159], v112 offset:34816
	ds_read_b128 v[160:163], v112 offset:36864
	ds_read_b128 v[190:193], v112 offset:38912
	ds_read_b128 v[194:197], v113 offset:49152
	ds_read_b128 v[198:201], v113 offset:51200
	ds_read_b128 v[202:205], v113 offset:53248
	ds_read_b128 v[206:209], v113 offset:55296
	s_waitcnt lgkmcnt(11)
	v_mfma_f32_16x16x32_bf16 v[214:217], v[84:87], v[64:67], v[60:63]
	v_mfma_f32_16x16x32_bf16 v[210:213], v[80:83], v[64:67], v[52:55]
	s_nop 1
	v_add_co_u32_e32 v60, vcc, s11, v164
	s_nop 1
	v_addc_co_u32_e32 v61, vcc, 0, v165, vcc
	v_mfma_f32_16x16x32_bf16 v[56:59], v[88:91], v[64:67], v[56:59]
	v_mfma_f32_16x16x32_bf16 v[48:51], v[92:95], v[64:67], v[48:51]
	v_add_co_u32_e32 v64, vcc, s33, v164
	s_nop 0
	s_nop 0
	v_addc_co_u32_e32 v65, vcc, 0, v165, vcc
	s_waitcnt lgkmcnt(10)
	v_mfma_f32_16x16x32_bf16 v[44:47], v[80:83], v[68:71], v[44:47]
	v_mfma_f32_16x16x32_bf16 v[40:43], v[84:87], v[68:71], v[40:43]
	v_mfma_f32_16x16x32_bf16 v[36:39], v[88:91], v[68:71], v[36:39]
	v_mfma_f32_16x16x32_bf16 v[32:35], v[92:95], v[68:71], v[32:35]
	v_add_co_u32_e32 v68, vcc, s59, v164
	s_waitcnt lgkmcnt(9)
	v_mfma_f32_16x16x32_bf16 v[28:31], v[80:83], v[72:75], v[28:31]
	v_addc_co_u32_e32 v69, vcc, 0, v165, vcc
	v_mfma_f32_16x16x32_bf16 v[24:27], v[84:87], v[72:75], v[24:27]
	v_mfma_f32_16x16x32_bf16 v[20:23], v[88:91], v[72:75], v[20:23]
	v_mfma_f32_16x16x32_bf16 v[16:19], v[92:95], v[72:75], v[16:19]
	s_waitcnt lgkmcnt(8)
	v_mfma_f32_16x16x32_bf16 v[8:11], v[84:87], v[76:79], v[8:11]
	v_lshl_add_u64 v[84:85], v[102:103], 0, s[92:93]
	v_mfma_f32_16x16x32_bf16 v[12:15], v[80:83], v[76:79], v[12:15]
	v_mfma_f32_16x16x32_bf16 v[4:7], v[88:91], v[76:79], v[4:7]
	v_mfma_f32_16x16x32_bf16 v[0:3], v[92:95], v[76:79], v[0:3]
	v_add_co_u32_e32 v76, vcc, s11, v84
	s_nop 0
	s_nop 0
	v_addc_co_u32_e32 v77, vcc, 0, v85, vcc
	v_add_co_u32_e32 v80, vcc, s33, v84
	s_nop 1
	v_addc_co_u32_e32 v81, vcc, 0, v85, vcc
	s_waitcnt lgkmcnt(3)
	v_mfma_f32_16x16x32_bf16 v[92:95], v[194:197], v[152:155], v[210:213]
	s_waitcnt lgkmcnt(2)
	v_mfma_f32_16x16x32_bf16 v[88:91], v[198:201], v[152:155], v[214:217]
	s_waitcnt lgkmcnt(1)
	v_mfma_f32_16x16x32_bf16 v[56:59], v[202:205], v[152:155], v[56:59]
	s_waitcnt lgkmcnt(0)
	v_mfma_f32_16x16x32_bf16 v[48:51], v[206:209], v[152:155], v[48:51]
	v_add_co_u32_e32 v84, vcc, s59, v84
	s_nop 1
	v_addc_co_u32_e32 v85, vcc, 0, v85, vcc
	v_mfma_f32_16x16x32_bf16 v[44:47], v[194:197], v[156:159], v[44:47]
	v_mfma_f32_16x16x32_bf16 v[40:43], v[198:201], v[156:159], v[40:43]
	v_mfma_f32_16x16x32_bf16 v[36:39], v[202:205], v[156:159], v[36:39]
	v_mfma_f32_16x16x32_bf16 v[32:35], v[206:209], v[156:159], v[32:35]
	v_mfma_f32_16x16x32_bf16 v[28:31], v[194:197], v[160:163], v[28:31]
	v_mfma_f32_16x16x32_bf16 v[24:27], v[198:201], v[160:163], v[24:27]
	v_mfma_f32_16x16x32_bf16 v[20:23], v[202:205], v[160:163], v[20:23]
	v_mfma_f32_16x16x32_bf16 v[16:19], v[206:209], v[160:163], v[16:19]
	v_mfma_f32_16x16x32_bf16 v[12:15], v[194:197], v[190:193], v[12:15]
	v_mfma_f32_16x16x32_bf16 v[8:11], v[198:201], v[190:193], v[8:11]
	v_mfma_f32_16x16x32_bf16 v[4:7], v[202:205], v[190:193], v[4:7]
	v_mfma_f32_16x16x32_bf16 v[0:3], v[206:209], v[190:193], v[0:3]
	s_mov_b32 s44, s29
	s_waitcnt lgkmcnt(0)
	s_waitcnt vmcnt(5)
	v_add_u32_e32 v64, s24, v108
	v_add_u32_e32 v52, 0xffffe000, v64
	v_or_b32_e32 v62, v64, v107
	v_lshrrev_b32_e32 v52, 10, v52
	s_movk_i32 s16, 0x1800
	v_mad_u32_u24 v52, v52, s16, s16
	v_cmp_lt_i32_e32 vcc, s13, v62
	v_or_b32_e32 v65, s25, v114
	v_or_b32_e32 v54, v65, v115
	v_cndmask_b32_e32 v52, 0, v52, vcc
	v_ashrrev_i32_e32 v53, 31, v52
	s_waitcnt vmcnt(4)
	v_lshlrev_b64 v[74:75], 2, v[52:53]
	v_ashrrev_i32_e32 v55, 31, v54
	v_ashrrev_i32_e32 v63, 31, v62
	v_lshl_add_u64 v[52:53], s[40:41], 0, v[74:75]
	v_lshlrev_b64 v[60:61], 2, v[54:55]
	v_readlane_b32 s16, v250, 15
	s_waitcnt vmcnt(1)
	v_lshl_add_u64 v[82:83], v[52:53], 0, v[60:61]
	v_lshlrev_b64 v[52:53], 12, v[62:63]
	v_readlane_b32 s17, v250, 16
	v_lshl_add_u64 v[74:75], s[42:43], 0, v[74:75]
	s_waitcnt vmcnt(0)
	v_lshl_add_u64 v[86:87], v[74:75], 0, v[60:61]
	v_lshl_add_u64 v[52:53], s[16:17], 0, v[52:53]
	v_lshl_add_u64 v[84:85], v[52:53], 0, v[60:61]
	global_load_dwordx4 v[66:69], v[82:83], off
	global_load_dwordx4 v[70:73], v[84:85], off
	v_lshl_add_u64 v[52:53], s[0:1], 0, v[60:61]
	v_readlane_b32 s16, v250, 21
	v_lshlrev_b64 v[78:79], 11, v[62:63]
	v_readlane_b32 s17, v250, 22
	s_waitcnt vmcnt(0)
	v_pk_fma_f32 v[68:69], v[94:95], v[68:69], v[72:73]
	v_pk_fma_f32 v[66:67], v[92:93], v[66:67], v[70:71]
	global_store_dwordx4 v[84:85], v[66:69], off
	global_load_dwordx4 v[70:73], v[52:53], off
	global_load_dwordx4 v[74:77], v[86:87], off
	v_lshl_add_u64 v[78:79], s[16:17], 0, v[78:79]
	v_lshl_add_u64 v[92:93], v[54:55], 1, v[78:79]
	s_mov_b32 s16, 0xa000
	s_waitcnt vmcnt(1)
	v_pk_mul_f32 v[72:73], v[68:69], v[72:73]
	v_pk_mul_f32 v[70:71], v[66:67], v[70:71]
	s_waitcnt vmcnt(0)
	v_pk_add_f32 v[76:77], v[76:77], 1.0 op_sel_hi:[1,0]
	v_pk_add_f32 v[74:75], v[74:75], 1.0 op_sel_hi:[1,0]
	v_pk_mul_f32 v[72:73], v[72:73], v[76:77]
	v_pk_mul_f32 v[70:71], v[70:71], v[74:75]
	v_and_b32_sdwa v77, v71, v170 dst_sel:DWORD dst_unused:UNUSED_PAD src0_sel:WORD_1 src1_sel:DWORD
	v_and_b32_sdwa v75, v70, v170 dst_sel:DWORD dst_unused:UNUSED_PAD src0_sel:WORD_1 src1_sel:DWORD
	v_add3_u32 v71, v71, v77, s56
	v_add3_u32 v70, v70, v75, s56
	v_and_b32_e32 v74, 0xffff0000, v71
	v_cvt_pk_bf16_f32 v71, v72, v73
	v_or_b32_sdwa v70, v74, v70 dst_sel:DWORD dst_unused:UNUSED_PAD src0_sel:DWORD src1_sel:WORD_1
	global_store_dwordx2 v[92:93], v[70:71], off
	global_load_dwordx4 v[70:73], v[82:83], off offset:64
	s_nop 0
	global_load_dwordx4 v[74:77], v[84:85], off offset:64
	s_waitcnt vmcnt(0)
	v_pk_fma_f32 v[72:73], v[90:91], v[72:73], v[76:77]
	v_pk_fma_f32 v[70:71], v[88:89], v[70:71], v[74:75]
	global_store_dwordx4 v[84:85], v[70:73], off offset:64
	global_load_dwordx4 v[74:77], v[52:53], off offset:64
	global_load_dwordx4 v[78:81], v[86:87], off offset:64
	s_waitcnt vmcnt(1)
	v_pk_mul_f32 v[76:77], v[72:73], v[76:77]
	v_pk_mul_f32 v[74:75], v[70:71], v[74:75]
	s_waitcnt vmcnt(0)
	v_pk_add_f32 v[80:81], v[80:81], 1.0 op_sel_hi:[1,0]
	v_pk_add_f32 v[78:79], v[78:79], 1.0 op_sel_hi:[1,0]
	v_pk_mul_f32 v[76:77], v[76:77], v[80:81]
	v_pk_mul_f32 v[74:75], v[74:75], v[78:79]
	v_and_b32_sdwa v81, v75, v170 dst_sel:DWORD dst_unused:UNUSED_PAD src0_sel:WORD_1 src1_sel:DWORD
	v_and_b32_sdwa v79, v74, v170 dst_sel:DWORD dst_unused:UNUSED_PAD src0_sel:WORD_1 src1_sel:DWORD
	v_add3_u32 v75, v75, v81, s56
	v_add3_u32 v74, v74, v79, s56
	v_and_b32_e32 v78, 0xffff0000, v75
	v_cvt_pk_bf16_f32 v75, v76, v77
	v_or_b32_sdwa v74, v78, v74 dst_sel:DWORD dst_unused:UNUSED_PAD src0_sel:DWORD src1_sel:WORD_1
	global_store_dwordx2 v[92:93], v[74:75], off offset:32
	global_load_dwordx4 v[74:77], v[82:83], off offset:128
	s_nop 0
	global_load_dwordx4 v[78:81], v[84:85], off offset:128
	s_waitcnt vmcnt(0)
	v_pk_fma_f32 v[58:59], v[58:59], v[76:77], v[80:81]
	v_pk_fma_f32 v[56:57], v[56:57], v[74:75], v[78:79]
	global_store_dwordx4 v[84:85], v[56:59], off offset:128
	global_load_dwordx4 v[74:77], v[52:53], off offset:128
	global_load_dwordx4 v[78:81], v[86:87], off offset:128
	s_waitcnt vmcnt(1)
	v_pk_mul_f32 v[76:77], v[58:59], v[76:77]
	v_pk_mul_f32 v[74:75], v[56:57], v[74:75]
	s_waitcnt vmcnt(0)
	v_pk_add_f32 v[80:81], v[80:81], 1.0 op_sel_hi:[1,0]
	v_pk_add_f32 v[78:79], v[78:79], 1.0 op_sel_hi:[1,0]
	v_pk_mul_f32 v[76:77], v[76:77], v[80:81]
	v_pk_mul_f32 v[74:75], v[74:75], v[78:79]
	v_and_b32_sdwa v81, v75, v170 dst_sel:DWORD dst_unused:UNUSED_PAD src0_sel:WORD_1 src1_sel:DWORD
	v_and_b32_sdwa v79, v74, v170 dst_sel:DWORD dst_unused:UNUSED_PAD src0_sel:WORD_1 src1_sel:DWORD
	v_add3_u32 v75, v75, v81, s56
	v_add3_u32 v74, v74, v79, s56
	v_and_b32_e32 v78, 0xffff0000, v75
	v_cvt_pk_bf16_f32 v75, v76, v77
	v_or_b32_sdwa v74, v78, v74 dst_sel:DWORD dst_unused:UNUSED_PAD src0_sel:DWORD src1_sel:WORD_1
	global_store_dwordx2 v[92:93], v[74:75], off offset:64
	global_load_dwordx4 v[74:77], v[82:83], off offset:192
	s_nop 0
	global_load_dwordx4 v[78:81], v[84:85], off offset:192
	s_waitcnt vmcnt(0)
	v_pk_fma_f32 v[76:77], v[50:51], v[76:77], v[80:81]
	v_pk_fma_f32 v[74:75], v[48:49], v[74:75], v[78:79]
	global_store_dwordx4 v[84:85], v[74:77], off offset:192
	global_load_dwordx4 v[78:81], v[52:53], off offset:192
	s_nop 0
	global_load_dwordx4 v[82:85], v[86:87], off offset:192
	v_mul_f32_e32 v48, v67, v67
	v_mul_f32_e32 v49, v71, v71
	v_fmac_f32_e32 v48, v66, v66
	v_fmac_f32_e32 v49, v70, v70
	v_fmac_f32_e32 v48, v68, v68
	v_fmac_f32_e32 v49, v72, v72
	v_fmac_f32_e32 v48, v69, v69
	v_fmac_f32_e32 v49, v73, v73
	v_add_f32_e32 v48, v48, v49
	v_mul_f32_e32 v49, v57, v57
	v_fmac_f32_e32 v49, v56, v56
	v_fmac_f32_e32 v49, v58, v58
	v_fmac_f32_e32 v49, v59, v59
	v_add_f32_e32 v48, v48, v49
	v_mul_f32_e32 v49, v75, v75
	v_fmac_f32_e32 v49, v74, v74
	v_fmac_f32_e32 v49, v76, v76
	v_fmac_f32_e32 v49, v77, v77
	v_add_f32_e32 v50, v48, v49
	ds_bpermute_b32 v51, v105, v50
	v_lshrrev_b32_e32 v48, 6, v65
	v_mul_lo_u32 v48, v48, s16
	v_ashrrev_i32_e32 v49, 31, v48
	v_lshl_add_u64 v[48:49], s[38:39], 0, v[48:49]
	s_waitcnt lgkmcnt(0)
	v_add_f32_e32 v50, v50, v51
	ds_bpermute_b32 v51, v104, v50
	v_lshl_add_u64 v[48:49], v[62:63], 2, v[48:49]
	s_waitcnt vmcnt(1)
	v_pk_mul_f32 v[56:57], v[76:77], v[80:81]
	v_pk_mul_f32 v[58:59], v[74:75], v[78:79]
	s_waitcnt vmcnt(0)
	v_pk_add_f32 v[66:67], v[84:85], 1.0 op_sel_hi:[1,0]
	v_pk_add_f32 v[68:69], v[82:83], 1.0 op_sel_hi:[1,0]
	v_pk_mul_f32 v[56:57], v[56:57], v[66:67]
	v_pk_mul_f32 v[58:59], v[58:59], v[68:69]
	v_cvt_pk_bf16_f32 v57, v56, v57
	v_cvt_pk_bf16_f32 v56, v58, v59
	global_store_dwordx2 v[92:93], v[56:57], off offset:96
	s_and_saveexec_b64 s[24:25], s[36:37]
	s_cbranch_execz .LBB0_409
	s_waitcnt lgkmcnt(0)
	v_add_f32_e32 v50, v50, v51
	global_store_dword v[48:49], v50, off

.Ltail419:
	s_add_i32 s2, s3, 2
	v_add_u32_e32 v127, v89, v90
	ds_read_b128 v[100:103], v127 offset:16384
	ds_read_b128 v[106:109], v127 offset:18432
	ds_read_b128 v[110:113], v127 offset:20480
	ds_read_b128 v[114:117], v127 offset:22528
	v_add_u32_e32 v126, v88, v90
	ds_read_b128 v[92:95], v126
	ds_read_b128 v[96:99], v126 offset:2048
	s_add_i32 s3, s3, 4
	s_min_u32 s3, s3, 15
	v_add_u32_e32 v128, v88, v91
	v_add_u32_e32 v130, v89, v91
	s_lshl_b32 s92, s3, 7
	ds_read_b128 v[118:121], v130 offset:18432
	ds_read_b128 v[122:125], v130 offset:20480
	ds_read_b128 v[132:135], v130 offset:22528
	s_waitcnt lgkmcnt(4)
	v_mfma_f32_16x16x32_bf16 v[76:79], v[100:103], v[92:95], v[76:79]
	v_lshl_add_u64 v[44:45], v[80:81], 0, s[92:93]
	v_add_co_u32_e32 v46, vcc, s11, v44
	v_mfma_f32_16x16x32_bf16 v[68:71], v[106:109], v[92:95], v[68:71]
	s_nop 0
	v_addc_co_u32_e32 v47, vcc, 0, v45, vcc
	v_mfma_f32_16x16x32_bf16 v[52:55], v[110:113], v[92:95], v[52:55]
	v_mfma_f32_16x16x32_bf16 v[40:43], v[114:117], v[92:95], v[40:43]
	s_waitcnt lgkmcnt(3)
	v_mfma_f32_16x16x32_bf16 v[92:95], v[100:103], v[96:99], v[36:39]
	s_nop 2
	ds_read_b128 v[36:39], v128
	v_mfma_f32_16x16x32_bf16 v[100:103], v[106:109], v[96:99], v[8:11]
	v_mfma_f32_16x16x32_bf16 v[106:109], v[110:113], v[96:99], v[4:7]
	ds_read_b128 v[110:113], v128 offset:2048
	v_mfma_f32_16x16x32_bf16 v[96:99], v[114:117], v[96:99], v[0:3]
	ds_read_b128 v[114:117], v130 offset:16384
	s_waitcnt vmcnt(0)
	ds_write_b128 v87, v[12:15] offset:53248
	v_add_co_u32_e32 v46, vcc, s33, v44
	s_waitcnt vmcnt(1)
	ds_write_b128 v87, v[16:19] offset:49152
	s_nop 0
	v_addc_co_u32_e32 v47, vcc, 0, v45, vcc
	v_add_co_u32_e32 v44, vcc, s59, v44
	s_nop 0
	s_nop 0
	v_addc_co_u32_e32 v45, vcc, 0, v45, vcc
	s_waitcnt vmcnt(2)
	ds_write_b128 v87, v[20:23] offset:45056
	v_lshl_add_u64 v[44:45], v[82:83], 0, s[92:93]
	s_waitcnt vmcnt(5)
	ds_write_b128 v87, v[28:31] offset:32768
	s_waitcnt lgkmcnt(4)
	v_mfma_f32_16x16x32_bf16 v[0:3], v[114:117], v[36:39], v[76:79]
	v_mfma_f32_16x16x32_bf16 v[4:7], v[118:121], v[36:39], v[68:71]
	v_add_co_u32_e32 v44, vcc, s11, v44
	s_waitcnt vmcnt(4)
	ds_write_b128 v87, v[32:35] offset:36864
	s_nop 0
	v_addc_co_u32_e32 v45, vcc, 0, v45, vcc
	v_mfma_f32_16x16x32_bf16 v[8:11], v[122:125], v[36:39], v[52:55]
	v_mfma_f32_16x16x32_bf16 v[36:39], v[132:135], v[36:39], v[40:43]
	s_waitcnt vmcnt(3)
	ds_write_b128 v87, v[24:27] offset:40960
	v_mfma_f32_16x16x32_bf16 v[40:43], v[114:117], v[110:113], v[92:95]
	v_mfma_f32_16x16x32_bf16 v[52:55], v[118:121], v[110:113], v[100:103]
	v_mfma_f32_16x16x32_bf16 v[68:71], v[122:125], v[110:113], v[106:109]
	v_mfma_f32_16x16x32_bf16 v[76:79], v[132:135], v[110:113], v[96:99]
	s_waitcnt lgkmcnt(0)
	s_barrier
	ds_read_b128 v[100:103], v127 offset:49152
	ds_read_b128 v[106:109], v127 offset:51200
	ds_read_b128 v[110:113], v127 offset:53248
	ds_read_b128 v[114:117], v127 offset:55296
	ds_read_b128 v[92:95], v126 offset:32768
	ds_read_b128 v[96:99], v126 offset:34816
	s_min_u32 s3, s2, 12
	s_lshl_b32 s92, s3, 7
	ds_read_b128 v[118:121], v130 offset:51200
	ds_read_b128 v[122:125], v130 offset:53248
	ds_read_b128 v[132:135], v130 offset:55296
	s_waitcnt lgkmcnt(4)
	v_mfma_f32_16x16x32_bf16 v[0:3], v[100:103], v[92:95], v[0:3]
	v_lshl_add_u64 v[12:13], v[80:81], 0, s[92:93]
	v_add_co_u32_e32 v14, vcc, s11, v12
	v_mfma_f32_16x16x32_bf16 v[4:7], v[106:109], v[92:95], v[4:7]
	s_nop 0
	v_addc_co_u32_e32 v15, vcc, 0, v13, vcc
	v_mfma_f32_16x16x32_bf16 v[8:11], v[110:113], v[92:95], v[8:11]
	v_mfma_f32_16x16x32_bf16 v[36:39], v[114:117], v[92:95], v[36:39]
	s_waitcnt lgkmcnt(3)
	v_mfma_f32_16x16x32_bf16 v[92:95], v[100:103], v[96:99], v[40:43]
	s_nop 2
	ds_read_b128 v[40:43], v128 offset:32768
	v_mfma_f32_16x16x32_bf16 v[100:103], v[106:109], v[96:99], v[52:55]
	v_mfma_f32_16x16x32_bf16 v[106:109], v[110:113], v[96:99], v[68:71]
	ds_read_b128 v[110:113], v128 offset:34816
	v_mfma_f32_16x16x32_bf16 v[96:99], v[114:117], v[96:99], v[76:79]
	ds_read_b128 v[114:117], v130 offset:49152
	v_add_co_u32_e32 v14, vcc, s33, v12
	s_nop 0
	s_nop 0
	v_addc_co_u32_e32 v15, vcc, 0, v13, vcc
	v_add_co_u32_e32 v12, vcc, s59, v12
	s_nop 0
	s_nop 0
	v_addc_co_u32_e32 v13, vcc, 0, v13, vcc
	v_lshl_add_u64 v[12:13], v[82:83], 0, s[92:93]
	s_waitcnt lgkmcnt(0)
	v_mfma_f32_16x16x32_bf16 v[76:79], v[114:117], v[40:43], v[0:3]
	v_mfma_f32_16x16x32_bf16 v[68:71], v[118:121], v[40:43], v[4:7]
	v_add_co_u32_e32 v12, vcc, s11, v12
	s_nop 0
	s_nop 0
	v_addc_co_u32_e32 v13, vcc, 0, v13, vcc
	v_mfma_f32_16x16x32_bf16 v[52:55], v[122:125], v[40:43], v[8:11]
	v_mfma_f32_16x16x32_bf16 v[40:43], v[132:135], v[40:43], v[36:39]
	v_mfma_f32_16x16x32_bf16 v[36:39], v[114:117], v[110:113], v[92:95]
	v_mfma_f32_16x16x32_bf16 v[8:11], v[118:121], v[110:113], v[100:103]
	v_mfma_f32_16x16x32_bf16 v[4:7], v[122:125], v[110:113], v[106:109]
	v_mfma_f32_16x16x32_bf16 v[0:3], v[132:135], v[110:113], v[96:99]
	s_mov_b32 s3, s2
	s_waitcnt lgkmcnt(0)
	v_readlane_b32 s2, v251, 18
	s_waitcnt vmcnt(1)
	s_nop 0
	v_add_u32_e32 v18, s2, v86
	v_readlane_b32 s2, v251, 19
	s_waitcnt vmcnt(0)
	v_add_u32_e32 v13, 0xffffe000, v18
	v_or_b32_e32 v12, v18, v85
	v_lshl_or_b32 v19, v84, 2, s2
	v_lshrrev_b32_e32 v13, 10, v13
	s_movk_i32 s2, 0x1800
	v_mad_u32_u24 v13, v13, s2, s2
	v_cmp_lt_i32_e32 vcc, s13, v12
	v_lshlrev_b32_e32 v128, 2, v19
	v_readlane_b32 s2, v250, 15
	v_cndmask_b32_e32 v14, 0, v13, vcc
	v_ashrrev_i32_e32 v15, 31, v14
	v_lshlrev_b64 v[24:25], 2, v[14:15]
	v_ashrrev_i32_e32 v13, 31, v12
	v_lshl_add_u64 v[14:15], s[40:41], 0, v[24:25]
	v_lshl_add_u64 v[48:49], v[14:15], 0, v[128:129]
	v_lshlrev_b64 v[14:15], 12, v[12:13]
	v_readlane_b32 s3, v250, 16
	v_lshl_add_u64 v[28:29], s[42:43], 0, v[24:25]
	v_lshlrev_b64 v[32:33], 11, v[12:13]
	v_lshl_add_u64 v[14:15], s[2:3], 0, v[14:15]
	v_lshl_add_u64 v[50:51], v[14:15], 0, v[128:129]
	global_load_dwordx4 v[72:75], v[48:49], off
	global_load_dwordx4 v[80:83], v[48:49], off offset:64
	global_load_dwordx4 v[88:91], v[48:49], off offset:128
	global_load_dwordx4 v[136:139], v[48:49], off offset:192
	global_load_dwordx4 v[194:197], v[50:51], off
	global_load_dwordx4 v[198:201], v[50:51], off offset:64
	global_load_dwordx4 v[202:205], v[50:51], off offset:128
	global_load_dwordx4 v[206:209], v[50:51], off offset:192
	v_add_co_u32_e32 v58, vcc, 0x10000, v50
	s_nop 1
	v_addc_co_u32_e32 v59, vcc, 0, v51, vcc
	global_load_dwordx4 v[210:213], v[58:59], off
	global_load_dwordx4 v[214:217], v[58:59], off offset:64
	global_load_dwordx4 v[218:221], v[58:59], off offset:128
	global_load_dwordx4 v[222:225], v[58:59], off offset:192
	v_readlane_b32 s2, v250, 21
	v_readlane_b32 s3, v250, 22
	v_cmp_eq_u32_e32 vcc, 0, v84
	s_waitcnt vmcnt(4)
	v_pk_fma_f32 v[22:23], v[78:79], v[74:75], v[196:197]
	v_pk_fma_f32 v[20:21], v[76:77], v[72:73], v[194:195]
	global_store_dwordx4 v[50:51], v[20:23], off
	v_lshl_add_u64 v[14:15], v[28:29], 0, v[128:129]
	global_load_dwordx4 v[140:143], v128, s[0:1]
	global_load_dwordx4 v[144:147], v128, s[0:1] offset:64
	global_load_dwordx4 v[148:151], v128, s[0:1] offset:128
	global_load_dwordx4 v[152:155], v128, s[0:1] offset:192
	global_load_dwordx4 v[156:159], v[14:15], off
	global_load_dwordx4 v[160:163], v[14:15], off offset:64
	global_load_dwordx4 v[180:183], v[14:15], off offset:128
	global_load_dwordx4 v[190:193], v[14:15], off offset:192
	v_lshlrev_b32_e32 v16, 1, v19
	v_mov_b32_e32 v17, v129
	v_lshl_add_u64 v[32:33], s[2:3], 0, v[32:33]
	v_lshl_add_u64 v[56:57], v[32:33], 0, v[16:17]
	s_waitcnt vmcnt(0)
	v_pk_mul_f32 v[26:27], v[22:23], v[142:143]
	v_pk_mul_f32 v[24:25], v[20:21], v[140:141]
	s_waitcnt vmcnt(0)
	v_pk_add_f32 v[30:31], v[158:159], 1.0 op_sel_hi:[1,0]
	v_pk_add_f32 v[28:29], v[156:157], 1.0 op_sel_hi:[1,0]
	v_pk_mul_f32 v[26:27], v[26:27], v[30:31]
	v_pk_mul_f32 v[24:25], v[24:25], v[28:29]
	v_and_b32_sdwa v19, v26, v170 dst_sel:DWORD dst_unused:UNUSED_PAD src0_sel:WORD_1 src1_sel:DWORD
	v_and_b32_sdwa v29, v27, v170 dst_sel:DWORD dst_unused:UNUSED_PAD src0_sel:WORD_1 src1_sel:DWORD
	v_and_b32_sdwa v30, v25, v170 dst_sel:DWORD dst_unused:UNUSED_PAD src0_sel:WORD_1 src1_sel:DWORD
	v_and_b32_sdwa v28, v24, v170 dst_sel:DWORD dst_unused:UNUSED_PAD src0_sel:WORD_1 src1_sel:DWORD
	v_add3_u32 v19, v26, v19, s56
	v_add3_u32 v26, v27, v29, s56
	v_add3_u32 v25, v25, v30, s56
	v_add3_u32 v24, v24, v28, s56
	v_and_b32_e32 v26, 0xffff0000, v26
	v_and_b32_e32 v27, 0xffff0000, v25
	v_or_b32_sdwa v25, v26, v19 dst_sel:DWORD dst_unused:UNUSED_PAD src0_sel:DWORD src1_sel:WORD_1
	v_or_b32_sdwa v24, v27, v24 dst_sel:DWORD dst_unused:UNUSED_PAD src0_sel:DWORD src1_sel:WORD_1
	global_store_dwordx2 v[56:57], v[24:25], off
	s_nop 0
	s_waitcnt vmcnt(0)
	v_pk_fma_f32 v[26:27], v[70:71], v[82:83], v[200:201]
	v_pk_fma_f32 v[24:25], v[68:69], v[80:81], v[198:199]
	global_store_dwordx4 v[50:51], v[24:27], off offset:64
	v_pk_mul_f32 v[30:31], v[26:27], v[146:147]
	v_pk_mul_f32 v[28:29], v[24:25], v[144:145]
	v_pk_add_f32 v[34:35], v[162:163], 1.0 op_sel_hi:[1,0]
	v_pk_add_f32 v[32:33], v[160:161], 1.0 op_sel_hi:[1,0]
	v_pk_mul_f32 v[30:31], v[30:31], v[34:35]
	v_pk_mul_f32 v[28:29], v[28:29], v[32:33]
	v_and_b32_sdwa v19, v30, v170 dst_sel:DWORD dst_unused:UNUSED_PAD src0_sel:WORD_1 src1_sel:DWORD
	v_and_b32_sdwa v33, v31, v170 dst_sel:DWORD dst_unused:UNUSED_PAD src0_sel:WORD_1 src1_sel:DWORD
	v_and_b32_sdwa v34, v29, v170 dst_sel:DWORD dst_unused:UNUSED_PAD src0_sel:WORD_1 src1_sel:DWORD
	v_and_b32_sdwa v32, v28, v170 dst_sel:DWORD dst_unused:UNUSED_PAD src0_sel:WORD_1 src1_sel:DWORD
	v_add3_u32 v19, v30, v19, s56
	v_add3_u32 v30, v31, v33, s56
	v_add3_u32 v29, v29, v34, s56
	v_add3_u32 v28, v28, v32, s56
	v_and_b32_e32 v30, 0xffff0000, v30
	v_and_b32_e32 v31, 0xffff0000, v29
	v_or_b32_sdwa v29, v30, v19 dst_sel:DWORD dst_unused:UNUSED_PAD src0_sel:DWORD src1_sel:WORD_1
	v_or_b32_sdwa v28, v31, v28 dst_sel:DWORD dst_unused:UNUSED_PAD src0_sel:DWORD src1_sel:WORD_1
	global_store_dwordx2 v[56:57], v[28:29], off offset:32
	s_nop 0
	v_pk_fma_f32 v[30:31], v[54:55], v[90:91], v[204:205]
	v_pk_fma_f32 v[28:29], v[52:53], v[88:89], v[202:203]
	global_store_dwordx4 v[50:51], v[28:31], off offset:128
	v_pk_mul_f32 v[34:35], v[30:31], v[150:151]
	v_pk_mul_f32 v[32:33], v[28:29], v[148:149]
	v_pk_add_f32 v[46:47], v[182:183], 1.0 op_sel_hi:[1,0]
	v_pk_add_f32 v[44:45], v[180:181], 1.0 op_sel_hi:[1,0]
	v_pk_mul_f32 v[34:35], v[34:35], v[46:47]
	v_pk_mul_f32 v[32:33], v[32:33], v[44:45]
	v_and_b32_sdwa v19, v34, v170 dst_sel:DWORD dst_unused:UNUSED_PAD src0_sel:WORD_1 src1_sel:DWORD
	v_and_b32_sdwa v45, v35, v170 dst_sel:DWORD dst_unused:UNUSED_PAD src0_sel:WORD_1 src1_sel:DWORD
	v_and_b32_sdwa v46, v33, v170 dst_sel:DWORD dst_unused:UNUSED_PAD src0_sel:WORD_1 src1_sel:DWORD
	v_and_b32_sdwa v44, v32, v170 dst_sel:DWORD dst_unused:UNUSED_PAD src0_sel:WORD_1 src1_sel:DWORD
	v_add3_u32 v19, v34, v19, s56
	v_add3_u32 v34, v35, v45, s56
	v_add3_u32 v33, v33, v46, s56
	v_add3_u32 v32, v32, v44, s56
	v_and_b32_e32 v34, 0xffff0000, v34
	v_and_b32_e32 v35, 0xffff0000, v33
	v_or_b32_sdwa v33, v34, v19 dst_sel:DWORD dst_unused:UNUSED_PAD src0_sel:DWORD src1_sel:WORD_1
	v_or_b32_sdwa v32, v35, v32 dst_sel:DWORD dst_unused:UNUSED_PAD src0_sel:DWORD src1_sel:WORD_1
	global_store_dwordx2 v[56:57], v[32:33], off offset:64
	s_nop 0
	v_pk_fma_f32 v[34:35], v[42:43], v[138:139], v[208:209]
	v_pk_fma_f32 v[32:33], v[40:41], v[136:137], v[206:207]
	global_store_dwordx4 v[50:51], v[32:35], off offset:192
	v_mul_f32_e32 v14, v21, v21
	v_mul_f32_e32 v15, v25, v25
	v_fmac_f32_e32 v14, v20, v20
	v_fmac_f32_e32 v15, v24, v24
	v_fmac_f32_e32 v14, v22, v22
	v_fmac_f32_e32 v15, v26, v26
	v_fmac_f32_e32 v14, v23, v23
	v_fmac_f32_e32 v15, v27, v27
	v_add_f32_e32 v14, v14, v15
	v_mul_f32_e32 v15, v29, v29
	v_fmac_f32_e32 v15, v28, v28
	v_fmac_f32_e32 v15, v30, v30
	v_fmac_f32_e32 v15, v31, v31
	v_add_f32_e32 v14, v14, v15
	v_mul_f32_e32 v15, v33, v33
	v_fmac_f32_e32 v15, v32, v32
	v_fmac_f32_e32 v15, v34, v34
	v_fmac_f32_e32 v15, v35, v35
	v_add_f32_e32 v14, v14, v15
	ds_bpermute_b32 v15, v105, v14
	s_waitcnt lgkmcnt(0)
	v_add_f32_e32 v14, v14, v15
	ds_bpermute_b32 v15, v104, v14
	v_pk_mul_f32 v[20:21], v[34:35], v[154:155]
	v_pk_mul_f32 v[22:23], v[32:33], v[152:153]
	v_pk_add_f32 v[24:25], v[192:193], 1.0 op_sel_hi:[1,0]
	v_pk_add_f32 v[26:27], v[190:191], 1.0 op_sel_hi:[1,0]
	v_pk_mul_f32 v[20:21], v[20:21], v[24:25]
	v_pk_mul_f32 v[22:23], v[22:23], v[26:27]
	v_and_b32_sdwa v19, v20, v170 dst_sel:DWORD dst_unused:UNUSED_PAD src0_sel:WORD_1 src1_sel:DWORD
	v_and_b32_sdwa v25, v21, v170 dst_sel:DWORD dst_unused:UNUSED_PAD src0_sel:WORD_1 src1_sel:DWORD
	v_and_b32_sdwa v26, v23, v170 dst_sel:DWORD dst_unused:UNUSED_PAD src0_sel:WORD_1 src1_sel:DWORD
	v_and_b32_sdwa v24, v22, v170 dst_sel:DWORD dst_unused:UNUSED_PAD src0_sel:WORD_1 src1_sel:DWORD
	v_add3_u32 v19, v20, v19, s56
	v_add3_u32 v20, v21, v25, s56
	v_add3_u32 v21, v23, v26, s56
	v_add3_u32 v22, v22, v24, s56
	v_and_b32_e32 v20, 0xffff0000, v20
	v_and_b32_e32 v23, 0xffff0000, v21
	v_or_b32_sdwa v21, v20, v19 dst_sel:DWORD dst_unused:UNUSED_PAD src0_sel:DWORD src1_sel:WORD_1
	v_or_b32_sdwa v20, v23, v22 dst_sel:DWORD dst_unused:UNUSED_PAD src0_sel:DWORD src1_sel:WORD_1
	global_store_dwordx2 v[56:57], v[20:21], off offset:96
	s_and_saveexec_b64 s[2:3], vcc
	s_cbranch_execz .LBB0_422
	v_readlane_b32 s16, v253, 20
	s_add_u32 s24, s38, s16
	s_addc_u32 s25, s39, 0
	v_lshl_add_u64 v[20:21], v[12:13], 2, s[24:25]
	s_waitcnt lgkmcnt(0)
	v_add_f32_e32 v13, v14, v15
	global_store_dword v[20:21], v13, off

.Ltail582:
	s_add_i32 s0, s1, 2
	v_add_u32_e32 v111, v104, v105
	ds_read_b128 v[136:139], v111 offset:16384
	ds_read_b128 v[140:143], v111 offset:18432
	ds_read_b128 v[144:147], v111 offset:20480
	ds_read_b128 v[148:151], v111 offset:22528
	v_add_u32_e32 v110, v103, v105
	ds_read_b128 v[116:119], v110
	s_add_i32 s1, s1, 4
	ds_read_b128 v[120:123], v110 offset:2048
	s_min_u32 s1, s1, 63
	v_add_u32_e32 v113, v104, v114
	s_lshl_b32 s92, s1, 7
	ds_read_b128 v[124:127], v110 offset:4096
	v_add_u32_e32 v112, v103, v114
	ds_read_b128 v[194:197], v113 offset:16384
	ds_read_b128 v[198:201], v113 offset:18432
	ds_read_b128 v[202:205], v113 offset:20480
	ds_read_b128 v[206:209], v113 offset:22528
	v_lshl_add_u64 v[164:165], v[98:99], 0, s[92:93]
	ds_read_b128 v[132:135], v110 offset:6144
	ds_read_b128 v[152:155], v112
	ds_read_b128 v[156:159], v112 offset:2048
	ds_read_b128 v[160:163], v112 offset:4096
	ds_read_b128 v[190:193], v112 offset:6144
	s_waitcnt lgkmcnt(11)
	v_mfma_f32_16x16x32_bf16 v[92:95], v[136:139], v[116:119], v[92:95]
	v_mfma_f32_16x16x32_bf16 v[88:91], v[140:143], v[116:119], v[88:91]
	v_mfma_f32_16x16x32_bf16 v[52:55], v[144:147], v[116:119], v[52:55]
	v_mfma_f32_16x16x32_bf16 v[48:51], v[148:151], v[116:119], v[48:51]
	s_waitcnt vmcnt(7)
	ds_write_b128 v109, v[56:59] offset:32768
	v_add_co_u32_e32 v56, vcc, s7, v164
	s_waitcnt lgkmcnt(11)
	v_mfma_f32_16x16x32_bf16 v[44:47], v[136:139], v[120:123], v[44:47]
	v_addc_co_u32_e32 v57, vcc, 0, v165, vcc
	v_mfma_f32_16x16x32_bf16 v[40:43], v[140:143], v[120:123], v[40:43]
	v_mfma_f32_16x16x32_bf16 v[36:39], v[144:147], v[120:123], v[36:39]
	v_mfma_f32_16x16x32_bf16 v[32:35], v[148:151], v[120:123], v[32:35]
	v_add_co_u32_e32 v56, vcc, s52, v164
	s_waitcnt vmcnt(6)
	ds_write_b128 v109, v[60:63] offset:36864
	s_nop 0
	v_addc_co_u32_e32 v57, vcc, 0, v165, vcc
	s_waitcnt lgkmcnt(11)
	v_mfma_f32_16x16x32_bf16 v[28:31], v[136:139], v[124:127], v[28:31]
	v_mfma_f32_16x16x32_bf16 v[24:27], v[140:143], v[124:127], v[24:27]
	v_mfma_f32_16x16x32_bf16 v[20:23], v[144:147], v[124:127], v[20:23]
	v_mfma_f32_16x16x32_bf16 v[16:19], v[148:151], v[124:127], v[16:19]
	v_add_co_u32_e32 v56, vcc, s34, v164
	s_waitcnt vmcnt(5)
	ds_write_b128 v109, v[64:67] offset:40960
	s_nop 0
	v_addc_co_u32_e32 v57, vcc, 0, v165, vcc
	v_lshl_add_u64 v[64:65], v[100:101], 0, s[92:93]
	v_add_co_u32_e32 v66, vcc, s7, v64
	s_waitcnt lgkmcnt(7)
	v_mfma_f32_16x16x32_bf16 v[12:15], v[136:139], v[132:135], v[12:15]
	v_addc_co_u32_e32 v67, vcc, 0, v65, vcc
	v_mfma_f32_16x16x32_bf16 v[8:11], v[140:143], v[132:135], v[8:11]
	v_mfma_f32_16x16x32_bf16 v[4:7], v[144:147], v[132:135], v[4:7]
	v_mfma_f32_16x16x32_bf16 v[0:3], v[148:151], v[132:135], v[0:3]
	s_waitcnt vmcnt(4)
	ds_write_b128 v109, v[72:75] offset:45056
	s_waitcnt lgkmcnt(7)
	v_mfma_f32_16x16x32_bf16 v[56:59], v[194:197], v[152:155], v[92:95]
	v_mfma_f32_16x16x32_bf16 v[60:63], v[198:201], v[152:155], v[88:91]
	v_mfma_f32_16x16x32_bf16 v[52:55], v[202:205], v[152:155], v[52:55]
	v_mfma_f32_16x16x32_bf16 v[48:51], v[206:209], v[152:155], v[48:51]
	s_waitcnt vmcnt(3)
	ds_write_b128 v109, v[68:71] offset:49152
	s_waitcnt lgkmcnt(7)
	v_mfma_f32_16x16x32_bf16 v[44:47], v[194:197], v[156:159], v[44:47]
	v_mfma_f32_16x16x32_bf16 v[40:43], v[198:201], v[156:159], v[40:43]
	v_mfma_f32_16x16x32_bf16 v[36:39], v[202:205], v[156:159], v[36:39]
	v_mfma_f32_16x16x32_bf16 v[32:35], v[206:209], v[156:159], v[32:35]
	v_add_co_u32_e32 v66, vcc, s52, v64
	s_waitcnt vmcnt(2)
	ds_write_b128 v109, v[76:79] offset:53248
	v_addc_co_u32_e32 v67, vcc, 0, v65, vcc
	v_add_co_u32_e32 v64, vcc, s34, v64
	s_waitcnt lgkmcnt(7)
	v_mfma_f32_16x16x32_bf16 v[28:31], v[194:197], v[160:163], v[28:31]
	v_addc_co_u32_e32 v65, vcc, 0, v65, vcc
	v_mfma_f32_16x16x32_bf16 v[24:27], v[198:201], v[160:163], v[24:27]
	v_mfma_f32_16x16x32_bf16 v[20:23], v[202:205], v[160:163], v[20:23]
	v_mfma_f32_16x16x32_bf16 v[16:19], v[206:209], v[160:163], v[16:19]
	s_waitcnt vmcnt(1)
	ds_write_b128 v109, v[80:83] offset:57344
	s_waitcnt lgkmcnt(7)
	v_mfma_f32_16x16x32_bf16 v[12:15], v[194:197], v[190:193], v[12:15]
	v_mfma_f32_16x16x32_bf16 v[8:11], v[198:201], v[190:193], v[8:11]
	v_mfma_f32_16x16x32_bf16 v[4:7], v[202:205], v[190:193], v[4:7]
	v_mfma_f32_16x16x32_bf16 v[0:3], v[206:209], v[190:193], v[0:3]
	s_waitcnt vmcnt(0)
	ds_write_b128 v109, v[84:87] offset:61440
	s_waitcnt lgkmcnt(0)
	s_barrier
	ds_read_b128 v[84:87], v111 offset:51200
	ds_read_b128 v[80:83], v111 offset:49152
	ds_read_b128 v[88:91], v111 offset:53248
	ds_read_b128 v[92:95], v111 offset:55296
	ds_read_b128 v[64:67], v110 offset:32768
	s_min_u32 s1, s0, 60
	s_lshl_b32 s92, s1, 7
	ds_read_b128 v[68:71], v110 offset:34816
	v_lshl_add_u64 v[164:165], v[98:99], 0, s[92:93]
	ds_read_b128 v[72:75], v110 offset:36864
	ds_read_b128 v[76:79], v110 offset:38912
	ds_read_b128 v[152:155], v112 offset:32768
	ds_read_b128 v[156:159], v112 offset:34816
	ds_read_b128 v[160:163], v112 offset:36864
	ds_read_b128 v[190:193], v112 offset:38912
	ds_read_b128 v[194:197], v113 offset:49152
	ds_read_b128 v[198:201], v113 offset:51200
	ds_read_b128 v[202:205], v113 offset:53248
	ds_read_b128 v[206:209], v113 offset:55296
	s_waitcnt lgkmcnt(11)
	v_mfma_f32_16x16x32_bf16 v[214:217], v[84:87], v[64:67], v[60:63]
	v_mfma_f32_16x16x32_bf16 v[210:213], v[80:83], v[64:67], v[56:59]
	s_nop 1
	v_add_co_u32_e32 v60, vcc, s7, v164
	s_nop 1
	v_addc_co_u32_e32 v61, vcc, 0, v165, vcc
	v_mfma_f32_16x16x32_bf16 v[52:55], v[88:91], v[64:67], v[52:55]
	v_mfma_f32_16x16x32_bf16 v[48:51], v[92:95], v[64:67], v[48:51]
	v_add_co_u32_e32 v64, vcc, s52, v164
	s_nop 0
	s_nop 0
	v_addc_co_u32_e32 v65, vcc, 0, v165, vcc
	s_waitcnt lgkmcnt(10)
	v_mfma_f32_16x16x32_bf16 v[44:47], v[80:83], v[68:71], v[44:47]
	v_mfma_f32_16x16x32_bf16 v[40:43], v[84:87], v[68:71], v[40:43]
	v_mfma_f32_16x16x32_bf16 v[36:39], v[88:91], v[68:71], v[36:39]
	v_mfma_f32_16x16x32_bf16 v[32:35], v[92:95], v[68:71], v[32:35]
	v_add_co_u32_e32 v68, vcc, s34, v164
	s_waitcnt lgkmcnt(9)
	v_mfma_f32_16x16x32_bf16 v[28:31], v[80:83], v[72:75], v[28:31]
	v_addc_co_u32_e32 v69, vcc, 0, v165, vcc
	v_mfma_f32_16x16x32_bf16 v[24:27], v[84:87], v[72:75], v[24:27]
	v_mfma_f32_16x16x32_bf16 v[20:23], v[88:91], v[72:75], v[20:23]
	v_mfma_f32_16x16x32_bf16 v[16:19], v[92:95], v[72:75], v[16:19]
	s_waitcnt lgkmcnt(8)
	v_mfma_f32_16x16x32_bf16 v[8:11], v[84:87], v[76:79], v[8:11]
	v_lshl_add_u64 v[84:85], v[100:101], 0, s[92:93]
	v_mfma_f32_16x16x32_bf16 v[12:15], v[80:83], v[76:79], v[12:15]
	v_mfma_f32_16x16x32_bf16 v[4:7], v[88:91], v[76:79], v[4:7]
	v_mfma_f32_16x16x32_bf16 v[0:3], v[92:95], v[76:79], v[0:3]
	v_add_co_u32_e32 v76, vcc, s7, v84
	s_nop 0
	s_nop 0
	v_addc_co_u32_e32 v77, vcc, 0, v85, vcc
	v_add_co_u32_e32 v80, vcc, s52, v84
	s_nop 1
	v_addc_co_u32_e32 v81, vcc, 0, v85, vcc
	s_waitcnt lgkmcnt(3)
	v_mfma_f32_16x16x32_bf16 v[92:95], v[194:197], v[152:155], v[210:213]
	s_waitcnt lgkmcnt(2)
	v_mfma_f32_16x16x32_bf16 v[88:91], v[198:201], v[152:155], v[214:217]
	s_waitcnt lgkmcnt(1)
	v_mfma_f32_16x16x32_bf16 v[52:55], v[202:205], v[152:155], v[52:55]
	s_waitcnt lgkmcnt(0)
	v_mfma_f32_16x16x32_bf16 v[48:51], v[206:209], v[152:155], v[48:51]
	v_add_co_u32_e32 v84, vcc, s34, v84
	s_nop 1
	v_addc_co_u32_e32 v85, vcc, 0, v85, vcc
	v_mfma_f32_16x16x32_bf16 v[44:47], v[194:197], v[156:159], v[44:47]
	v_mfma_f32_16x16x32_bf16 v[40:43], v[198:201], v[156:159], v[40:43]
	v_mfma_f32_16x16x32_bf16 v[36:39], v[202:205], v[156:159], v[36:39]
	v_mfma_f32_16x16x32_bf16 v[32:35], v[206:209], v[156:159], v[32:35]
	v_mfma_f32_16x16x32_bf16 v[28:31], v[194:197], v[160:163], v[28:31]
	v_mfma_f32_16x16x32_bf16 v[24:27], v[198:201], v[160:163], v[24:27]
	v_mfma_f32_16x16x32_bf16 v[20:23], v[202:205], v[160:163], v[20:23]
	v_mfma_f32_16x16x32_bf16 v[16:19], v[206:209], v[160:163], v[16:19]
	v_mfma_f32_16x16x32_bf16 v[12:15], v[194:197], v[190:193], v[12:15]
	v_mfma_f32_16x16x32_bf16 v[8:11], v[198:201], v[190:193], v[8:11]
	v_mfma_f32_16x16x32_bf16 v[4:7], v[202:205], v[190:193], v[4:7]
	v_mfma_f32_16x16x32_bf16 v[0:3], v[206:209], v[190:193], v[0:3]
	s_mov_b32 s1, s0
	s_waitcnt lgkmcnt(0)
	s_or_b32 s0, s69, 1
	s_mul_i32 s1, s69, 0x12000
	v_readlane_b32 s26, v250, 25
	v_readlane_b32 s27, v250, 26
	s_add_u32 s1, s26, s1
	s_addc_u32 s24, s27, 0
	s_add_u32 s38, s1, 0x5000
	v_readlane_b32 s1, v251, 5
	v_lshlrev_b32_e32 v114, 6, v102
	v_lshlrev_b32_e32 v115, 2, v97
	s_waitcnt vmcnt(5)
	v_add_u32_e32 v64, s1, v108
	v_readlane_b32 s1, v251, 6
	v_add_u32_e32 v56, 0xffffe000, v64
	v_or_b32_e32 v62, v64, v107
	v_or_b32_e32 v65, s1, v114
	v_lshrrev_b32_e32 v56, 10, v56
	s_movk_i32 s1, 0x1800
	v_mad_u32_u24 v56, v56, s1, s1
	v_cmp_lt_i32_e32 vcc, s13, v62
	v_or_b32_e32 v58, v65, v115
	s_addc_u32 s39, s24, 0
	v_cndmask_b32_e32 v56, 0, v56, vcc
	v_ashrrev_i32_e32 v57, 31, v56
	s_waitcnt vmcnt(4)
	v_lshlrev_b64 v[74:75], 2, v[56:57]
	v_ashrrev_i32_e32 v59, 31, v58
	v_ashrrev_i32_e32 v63, 31, v62
	v_lshl_add_u64 v[56:57], s[38:39], 0, v[74:75]
	v_lshlrev_b64 v[60:61], 2, v[58:59]
	v_readlane_b32 s16, v250, 15
	s_waitcnt vmcnt(1)
	v_lshl_add_u64 v[82:83], v[56:57], 0, v[60:61]
	v_lshlrev_b64 v[56:57], 12, v[62:63]
	v_readlane_b32 s17, v250, 16
	v_readlane_b32 s68, v250, 41
	s_mul_i32 s24, s0, 0x12000
	v_lshl_add_u64 v[56:57], s[16:17], 0, v[56:57]
	s_waitcnt vmcnt(0)
	v_lshl_add_u64 v[84:85], v[56:57], 0, v[60:61]
	global_load_dwordx4 v[116:119], v[82:83], off
	global_load_dwordx4 v[120:123], v[82:83], off offset:64
	global_load_dwordx4 v[124:127], v[82:83], off offset:128
	global_load_dwordx4 v[132:135], v[82:83], off offset:192
	global_load_dwordx4 v[190:193], v[84:85], off
	global_load_dwordx4 v[194:197], v[84:85], off offset:64
	global_load_dwordx4 v[198:201], v[84:85], off offset:128
	global_load_dwordx4 v[202:205], v[84:85], off offset:192
	v_add_co_u32_e32 v164, vcc, 0x10000, v84
	s_nop 1
	v_addc_co_u32_e32 v165, vcc, 0, v85, vcc
	v_add_co_u32_e32 v222, vcc, 0x20000, v84
	s_nop 1
	v_addc_co_u32_e32 v223, vcc, 0, v85, vcc
	v_add_co_u32_e32 v224, vcc, 0x30000, v84
	s_nop 1
	v_addc_co_u32_e32 v225, vcc, 0, v85, vcc
	global_load_dwordx4 v[206:209], v[164:165], off
	global_load_dwordx4 v[210:213], v[164:165], off offset:64
	global_load_dwordx4 v[214:217], v[164:165], off offset:128
	global_load_dwordx4 v[218:221], v[164:165], off offset:192
	s_lshl_b32 s0, s0, 12
	v_readlane_b32 s70, v250, 43
	v_readlane_b32 s71, v250, 44
	s_add_u32 s0, s70, s0
	s_addc_u32 s1, s71, 0
	s_add_u32 s24, s26, s24
	s_addc_u32 s25, s27, 0
	s_add_u32 s40, s24, 0x1000
	s_addc_u32 s41, s25, 0
	v_lshl_add_u64 v[74:75], s[40:41], 0, v[74:75]
	v_lshl_add_u64 v[56:57], s[0:1], 0, v[60:61]
	v_lshl_add_u64 v[86:87], v[74:75], 0, v[60:61]
	v_readlane_b32 s16, v250, 21
	v_lshlrev_b64 v[78:79], 11, v[62:63]
	v_readlane_b32 s17, v250, 22
	v_readlane_b32 s69, v250, 42
	v_readlane_b32 s69, v254, 49
	v_lshl_add_u64 v[78:79], s[16:17], 0, v[78:79]
	s_mul_i32 s24, s69, 0x140000
	s_add_u32 s24, s86, s24
	s_mov_b32 s16, 0xa000
	s_addc_u32 s25, s87, 0
	s_add_u32 s26, s24, 0xafba000
	s_addc_u32 s27, s25, 0
	v_cmp_eq_u32_e64 s[36:37], 0, v97
	v_readlane_b32 s72, v250, 45
	v_readlane_b32 s73, v250, 46
	v_readlane_b32 s74, v250, 47
	v_readlane_b32 s75, v250, 48
	v_readlane_b32 s76, v250, 49
	v_readlane_b32 s77, v250, 50
	v_readlane_b32 s78, v250, 51
	v_readlane_b32 s79, v250, 52
	v_readlane_b32 s80, v250, 53
	v_readlane_b32 s81, v250, 54
	v_readlane_b32 s82, v250, 55
	v_readlane_b32 s83, v250, 56
	s_waitcnt vmcnt(4)
	v_pk_fma_f32 v[68:69], v[94:95], v[118:119], v[192:193]
	v_pk_fma_f32 v[66:67], v[92:93], v[116:117], v[190:191]
	global_store_dwordx4 v[84:85], v[66:69], off
	global_load_dwordx4 v[136:139], v[56:57], off
	global_load_dwordx4 v[140:143], v[56:57], off offset:64
	global_load_dwordx4 v[144:147], v[56:57], off offset:128
	global_load_dwordx4 v[148:151], v[56:57], off offset:192
	global_load_dwordx4 v[152:155], v[86:87], off
	global_load_dwordx4 v[156:159], v[86:87], off offset:64
	global_load_dwordx4 v[160:163], v[86:87], off offset:128
	global_load_dwordx4 v[180:183], v[86:87], off offset:192
	v_lshl_add_u64 v[92:93], v[58:59], 1, v[78:79]
	s_waitcnt vmcnt(0)
	v_pk_mul_f32 v[72:73], v[68:69], v[138:139]
	v_pk_mul_f32 v[70:71], v[66:67], v[136:137]
	s_waitcnt vmcnt(0)
	v_pk_add_f32 v[76:77], v[154:155], 1.0 op_sel_hi:[1,0]
	v_pk_add_f32 v[74:75], v[152:153], 1.0 op_sel_hi:[1,0]
	v_pk_mul_f32 v[72:73], v[72:73], v[76:77]
	v_pk_mul_f32 v[70:71], v[70:71], v[74:75]
	v_and_b32_sdwa v77, v71, v170 dst_sel:DWORD dst_unused:UNUSED_PAD src0_sel:WORD_1 src1_sel:DWORD
	v_and_b32_sdwa v75, v70, v170 dst_sel:DWORD dst_unused:UNUSED_PAD src0_sel:WORD_1 src1_sel:DWORD
	v_add3_u32 v71, v71, v77, s56
	v_add3_u32 v70, v70, v75, s56
	v_and_b32_e32 v74, 0xffff0000, v71
	v_cvt_pk_bf16_f32 v71, v72, v73
	v_or_b32_sdwa v70, v74, v70 dst_sel:DWORD dst_unused:UNUSED_PAD src0_sel:DWORD src1_sel:WORD_1
	global_store_dwordx2 v[92:93], v[70:71], off
	s_nop 0
	s_waitcnt vmcnt(0)
	v_pk_fma_f32 v[72:73], v[90:91], v[122:123], v[196:197]
	v_pk_fma_f32 v[70:71], v[88:89], v[120:121], v[194:195]
	global_store_dwordx4 v[84:85], v[70:73], off offset:64
	v_pk_mul_f32 v[76:77], v[72:73], v[142:143]
	v_pk_mul_f32 v[74:75], v[70:71], v[140:141]
	v_pk_add_f32 v[80:81], v[158:159], 1.0 op_sel_hi:[1,0]
	v_pk_add_f32 v[78:79], v[156:157], 1.0 op_sel_hi:[1,0]
	v_pk_mul_f32 v[76:77], v[76:77], v[80:81]
	v_pk_mul_f32 v[74:75], v[74:75], v[78:79]
	v_and_b32_sdwa v81, v75, v170 dst_sel:DWORD dst_unused:UNUSED_PAD src0_sel:WORD_1 src1_sel:DWORD
	v_and_b32_sdwa v79, v74, v170 dst_sel:DWORD dst_unused:UNUSED_PAD src0_sel:WORD_1 src1_sel:DWORD
	v_add3_u32 v75, v75, v81, s56
	v_add3_u32 v74, v74, v79, s56
	v_and_b32_e32 v78, 0xffff0000, v75
	v_cvt_pk_bf16_f32 v75, v76, v77
	v_or_b32_sdwa v74, v78, v74 dst_sel:DWORD dst_unused:UNUSED_PAD src0_sel:DWORD src1_sel:WORD_1
	global_store_dwordx2 v[92:93], v[74:75], off offset:32
	s_nop 0
	v_pk_fma_f32 v[54:55], v[54:55], v[126:127], v[200:201]
	v_pk_fma_f32 v[52:53], v[52:53], v[124:125], v[198:199]
	global_store_dwordx4 v[84:85], v[52:55], off offset:128
	v_pk_mul_f32 v[76:77], v[54:55], v[146:147]
	v_pk_mul_f32 v[74:75], v[52:53], v[144:145]
	v_pk_add_f32 v[80:81], v[162:163], 1.0 op_sel_hi:[1,0]
	v_pk_add_f32 v[78:79], v[160:161], 1.0 op_sel_hi:[1,0]
	v_pk_mul_f32 v[76:77], v[76:77], v[80:81]
	v_pk_mul_f32 v[74:75], v[74:75], v[78:79]
	v_and_b32_sdwa v81, v75, v170 dst_sel:DWORD dst_unused:UNUSED_PAD src0_sel:WORD_1 src1_sel:DWORD
	v_and_b32_sdwa v79, v74, v170 dst_sel:DWORD dst_unused:UNUSED_PAD src0_sel:WORD_1 src1_sel:DWORD
	v_add3_u32 v75, v75, v81, s56
	v_add3_u32 v74, v74, v79, s56
	v_and_b32_e32 v78, 0xffff0000, v75
	v_cvt_pk_bf16_f32 v75, v76, v77
	v_or_b32_sdwa v74, v78, v74 dst_sel:DWORD dst_unused:UNUSED_PAD src0_sel:DWORD src1_sel:WORD_1
	global_store_dwordx2 v[92:93], v[74:75], off offset:64
	s_nop 0
	v_pk_fma_f32 v[76:77], v[50:51], v[134:135], v[204:205]
	v_pk_fma_f32 v[74:75], v[48:49], v[132:133], v[202:203]
	global_store_dwordx4 v[84:85], v[74:77], off offset:192
	s_nop 0
	v_mul_f32_e32 v50, v67, v67
	v_mul_f32_e32 v51, v71, v71
	v_fmac_f32_e32 v50, v66, v66
	v_fmac_f32_e32 v51, v70, v70
	v_fmac_f32_e32 v50, v68, v68
	v_fmac_f32_e32 v51, v72, v72
	v_fmac_f32_e32 v50, v69, v69
	v_fmac_f32_e32 v51, v73, v73
	v_add_f32_e32 v50, v50, v51
	v_mul_f32_e32 v51, v53, v53
	v_fmac_f32_e32 v51, v52, v52
	v_fmac_f32_e32 v51, v54, v54
	v_fmac_f32_e32 v51, v55, v55
	v_add_f32_e32 v50, v50, v51
	v_mul_f32_e32 v51, v75, v75
	v_xor_b32_e32 v48, 16, v176
	v_fmac_f32_e32 v51, v74, v74
	v_cmp_lt_i32_e32 vcc, v48, v177
	v_fmac_f32_e32 v51, v76, v76
	v_fmac_f32_e32 v51, v77, v77
	v_cndmask_b32_e32 v48, v176, v48, vcc
	v_lshlrev_b32_e32 v105, 2, v48
	v_add_f32_e32 v50, v50, v51
	ds_bpermute_b32 v51, v105, v50
	v_xor_b32_e32 v49, 32, v176
	v_cmp_lt_i32_e32 vcc, v49, v177
	v_lshrrev_b32_e32 v48, 6, v65
	v_mul_lo_u32 v48, v48, s16
	v_cndmask_b32_e32 v49, v176, v49, vcc
	v_lshlrev_b32_e32 v104, 2, v49
	s_waitcnt lgkmcnt(0)
	v_add_f32_e32 v50, v50, v51
	ds_bpermute_b32 v51, v104, v50
	v_ashrrev_i32_e32 v49, 31, v48
	v_lshl_add_u64 v[48:49], s[26:27], 0, v[48:49]
	v_lshl_add_u64 v[48:49], v[62:63], 2, v[48:49]
	v_pk_mul_f32 v[52:53], v[76:77], v[150:151]
	v_pk_mul_f32 v[54:55], v[74:75], v[148:149]
	v_pk_add_f32 v[66:67], v[182:183], 1.0 op_sel_hi:[1,0]
	v_pk_add_f32 v[68:69], v[180:181], 1.0 op_sel_hi:[1,0]
	v_pk_mul_f32 v[52:53], v[52:53], v[66:67]
	v_pk_mul_f32 v[54:55], v[54:55], v[68:69]
	v_cvt_pk_bf16_f32 v53, v52, v53
	v_cvt_pk_bf16_f32 v52, v54, v55
	global_store_dwordx2 v[92:93], v[52:53], off offset:96
	s_and_saveexec_b64 s[24:25], s[36:37]
	s_cbranch_execz .LBB0_585
	s_waitcnt lgkmcnt(0)
	v_add_f32_e32 v50, v50, v51
	global_store_dword v[48:49], v50, off

.Ltail596:
	s_add_i32 s29, s42, 2
	ds_read_b128 v[136:139], v111 offset:16384
	ds_read_b128 v[140:143], v111 offset:18432
	ds_read_b128 v[144:147], v111 offset:20480
	ds_read_b128 v[148:151], v111 offset:22528
	ds_read_b128 v[116:119], v110
	s_add_i32 s42, s42, 4
	ds_read_b128 v[120:123], v110 offset:2048
	s_min_u32 s42, s42, 63
	s_lshl_b32 s92, s42, 7
	ds_read_b128 v[124:127], v110 offset:4096
	ds_read_b128 v[194:197], v113 offset:16384
	ds_read_b128 v[198:201], v113 offset:18432
	ds_read_b128 v[202:205], v113 offset:20480
	ds_read_b128 v[206:209], v113 offset:22528
	v_lshl_add_u64 v[164:165], v[100:101], 0, s[92:93]
	ds_read_b128 v[132:135], v110 offset:6144
	ds_read_b128 v[152:155], v112
	ds_read_b128 v[156:159], v112 offset:2048
	ds_read_b128 v[160:163], v112 offset:4096
	ds_read_b128 v[190:193], v112 offset:6144
	s_waitcnt lgkmcnt(11)
	v_mfma_f32_16x16x32_bf16 v[92:95], v[136:139], v[116:119], v[92:95]
	v_mfma_f32_16x16x32_bf16 v[88:91], v[140:143], v[116:119], v[88:91]
	v_mfma_f32_16x16x32_bf16 v[56:59], v[144:147], v[116:119], v[56:59]
	v_mfma_f32_16x16x32_bf16 v[48:51], v[148:151], v[116:119], v[48:51]
	s_waitcnt vmcnt(7)
	ds_write_b128 v109, v[52:55] offset:32768
	v_add_co_u32_e32 v52, vcc, s7, v164
	s_waitcnt lgkmcnt(11)
	v_mfma_f32_16x16x32_bf16 v[44:47], v[136:139], v[120:123], v[44:47]
	v_addc_co_u32_e32 v53, vcc, 0, v165, vcc
	v_mfma_f32_16x16x32_bf16 v[40:43], v[140:143], v[120:123], v[40:43]
	v_mfma_f32_16x16x32_bf16 v[36:39], v[144:147], v[120:123], v[36:39]
	v_mfma_f32_16x16x32_bf16 v[32:35], v[148:151], v[120:123], v[32:35]
	v_add_co_u32_e32 v52, vcc, s52, v164
	s_waitcnt vmcnt(6)
	ds_write_b128 v109, v[60:63] offset:36864
	s_nop 0
	v_addc_co_u32_e32 v53, vcc, 0, v165, vcc
	s_waitcnt lgkmcnt(11)
	v_mfma_f32_16x16x32_bf16 v[28:31], v[136:139], v[124:127], v[28:31]
	v_mfma_f32_16x16x32_bf16 v[24:27], v[140:143], v[124:127], v[24:27]
	v_mfma_f32_16x16x32_bf16 v[20:23], v[144:147], v[124:127], v[20:23]
	v_mfma_f32_16x16x32_bf16 v[16:19], v[148:151], v[124:127], v[16:19]
	v_add_co_u32_e32 v52, vcc, s34, v164
	s_waitcnt vmcnt(5)
	ds_write_b128 v109, v[64:67] offset:40960
	s_nop 0
	v_addc_co_u32_e32 v53, vcc, 0, v165, vcc
	v_lshl_add_u64 v[64:65], v[102:103], 0, s[92:93]
	v_add_co_u32_e32 v66, vcc, s7, v64
	s_waitcnt lgkmcnt(7)
	v_mfma_f32_16x16x32_bf16 v[12:15], v[136:139], v[132:135], v[12:15]
	v_addc_co_u32_e32 v67, vcc, 0, v65, vcc
	v_mfma_f32_16x16x32_bf16 v[8:11], v[140:143], v[132:135], v[8:11]
	v_mfma_f32_16x16x32_bf16 v[4:7], v[144:147], v[132:135], v[4:7]
	v_mfma_f32_16x16x32_bf16 v[0:3], v[148:151], v[132:135], v[0:3]
	s_waitcnt vmcnt(4)
	ds_write_b128 v109, v[72:75] offset:45056
	s_waitcnt lgkmcnt(7)
	v_mfma_f32_16x16x32_bf16 v[52:55], v[194:197], v[152:155], v[92:95]
	v_mfma_f32_16x16x32_bf16 v[60:63], v[198:201], v[152:155], v[88:91]
	v_mfma_f32_16x16x32_bf16 v[56:59], v[202:205], v[152:155], v[56:59]
	v_mfma_f32_16x16x32_bf16 v[48:51], v[206:209], v[152:155], v[48:51]
	s_waitcnt vmcnt(3)
	ds_write_b128 v109, v[68:71] offset:49152
	s_waitcnt lgkmcnt(7)
	v_mfma_f32_16x16x32_bf16 v[44:47], v[194:197], v[156:159], v[44:47]
	v_mfma_f32_16x16x32_bf16 v[40:43], v[198:201], v[156:159], v[40:43]
	v_mfma_f32_16x16x32_bf16 v[36:39], v[202:205], v[156:159], v[36:39]
	v_mfma_f32_16x16x32_bf16 v[32:35], v[206:209], v[156:159], v[32:35]
	v_add_co_u32_e32 v66, vcc, s52, v64
	s_waitcnt vmcnt(2)
	ds_write_b128 v109, v[76:79] offset:53248
	v_addc_co_u32_e32 v67, vcc, 0, v65, vcc
	v_add_co_u32_e32 v64, vcc, s34, v64
	s_waitcnt lgkmcnt(7)
	v_mfma_f32_16x16x32_bf16 v[28:31], v[194:197], v[160:163], v[28:31]
	v_addc_co_u32_e32 v65, vcc, 0, v65, vcc
	v_mfma_f32_16x16x32_bf16 v[24:27], v[198:201], v[160:163], v[24:27]
	v_mfma_f32_16x16x32_bf16 v[20:23], v[202:205], v[160:163], v[20:23]
	v_mfma_f32_16x16x32_bf16 v[16:19], v[206:209], v[160:163], v[16:19]
	s_waitcnt vmcnt(1)
	ds_write_b128 v109, v[80:83] offset:57344
	s_waitcnt lgkmcnt(7)
	v_mfma_f32_16x16x32_bf16 v[12:15], v[194:197], v[190:193], v[12:15]
	v_mfma_f32_16x16x32_bf16 v[8:11], v[198:201], v[190:193], v[8:11]
	v_mfma_f32_16x16x32_bf16 v[4:7], v[202:205], v[190:193], v[4:7]
	v_mfma_f32_16x16x32_bf16 v[0:3], v[206:209], v[190:193], v[0:3]
	s_waitcnt vmcnt(0)
	ds_write_b128 v109, v[84:87] offset:61440
	s_waitcnt lgkmcnt(0)
	s_barrier
	ds_read_b128 v[84:87], v111 offset:51200
	ds_read_b128 v[80:83], v111 offset:49152
	ds_read_b128 v[88:91], v111 offset:53248
	ds_read_b128 v[92:95], v111 offset:55296
	ds_read_b128 v[64:67], v110 offset:32768
	s_min_u32 s42, s29, 60
	s_lshl_b32 s92, s42, 7
	ds_read_b128 v[68:71], v110 offset:34816
	v_lshl_add_u64 v[164:165], v[100:101], 0, s[92:93]
	ds_read_b128 v[72:75], v110 offset:36864
	ds_read_b128 v[76:79], v110 offset:38912
	ds_read_b128 v[152:155], v112 offset:32768
	ds_read_b128 v[156:159], v112 offset:34816
	ds_read_b128 v[160:163], v112 offset:36864
	ds_read_b128 v[190:193], v112 offset:38912
	ds_read_b128 v[194:197], v113 offset:49152
	ds_read_b128 v[198:201], v113 offset:51200
	ds_read_b128 v[202:205], v113 offset:53248
	ds_read_b128 v[206:209], v113 offset:55296
	s_waitcnt lgkmcnt(11)
	v_mfma_f32_16x16x32_bf16 v[214:217], v[84:87], v[64:67], v[60:63]
	v_mfma_f32_16x16x32_bf16 v[210:213], v[80:83], v[64:67], v[52:55]
	s_nop 1
	v_add_co_u32_e32 v60, vcc, s7, v164
	s_nop 1
	v_addc_co_u32_e32 v61, vcc, 0, v165, vcc
	v_mfma_f32_16x16x32_bf16 v[56:59], v[88:91], v[64:67], v[56:59]
	v_mfma_f32_16x16x32_bf16 v[48:51], v[92:95], v[64:67], v[48:51]
	v_add_co_u32_e32 v64, vcc, s52, v164
	s_nop 0
	s_nop 0
	v_addc_co_u32_e32 v65, vcc, 0, v165, vcc
	s_waitcnt lgkmcnt(10)
	v_mfma_f32_16x16x32_bf16 v[44:47], v[80:83], v[68:71], v[44:47]
	v_mfma_f32_16x16x32_bf16 v[40:43], v[84:87], v[68:71], v[40:43]
	v_mfma_f32_16x16x32_bf16 v[36:39], v[88:91], v[68:71], v[36:39]
	v_mfma_f32_16x16x32_bf16 v[32:35], v[92:95], v[68:71], v[32:35]
	v_add_co_u32_e32 v68, vcc, s34, v164
	s_waitcnt lgkmcnt(9)
	v_mfma_f32_16x16x32_bf16 v[28:31], v[80:83], v[72:75], v[28:31]
	v_addc_co_u32_e32 v69, vcc, 0, v165, vcc
	v_mfma_f32_16x16x32_bf16 v[24:27], v[84:87], v[72:75], v[24:27]
	v_mfma_f32_16x16x32_bf16 v[20:23], v[88:91], v[72:75], v[20:23]
	v_mfma_f32_16x16x32_bf16 v[16:19], v[92:95], v[72:75], v[16:19]
	s_waitcnt lgkmcnt(8)
	v_mfma_f32_16x16x32_bf16 v[8:11], v[84:87], v[76:79], v[8:11]
	v_lshl_add_u64 v[84:85], v[102:103], 0, s[92:93]
	v_mfma_f32_16x16x32_bf16 v[12:15], v[80:83], v[76:79], v[12:15]
	v_mfma_f32_16x16x32_bf16 v[4:7], v[88:91], v[76:79], v[4:7]
	v_mfma_f32_16x16x32_bf16 v[0:3], v[92:95], v[76:79], v[0:3]
	v_add_co_u32_e32 v76, vcc, s7, v84
	s_nop 0
	s_nop 0
	v_addc_co_u32_e32 v77, vcc, 0, v85, vcc
	v_add_co_u32_e32 v80, vcc, s52, v84
	s_nop 1
	v_addc_co_u32_e32 v81, vcc, 0, v85, vcc
	s_waitcnt lgkmcnt(3)
	v_mfma_f32_16x16x32_bf16 v[92:95], v[194:197], v[152:155], v[210:213]
	s_waitcnt lgkmcnt(2)
	v_mfma_f32_16x16x32_bf16 v[88:91], v[198:201], v[152:155], v[214:217]
	s_waitcnt lgkmcnt(1)
	v_mfma_f32_16x16x32_bf16 v[56:59], v[202:205], v[152:155], v[56:59]
	s_waitcnt lgkmcnt(0)
	v_mfma_f32_16x16x32_bf16 v[48:51], v[206:209], v[152:155], v[48:51]
	v_add_co_u32_e32 v84, vcc, s34, v84
	s_nop 1
	v_addc_co_u32_e32 v85, vcc, 0, v85, vcc
	v_mfma_f32_16x16x32_bf16 v[44:47], v[194:197], v[156:159], v[44:47]
	v_mfma_f32_16x16x32_bf16 v[40:43], v[198:201], v[156:159], v[40:43]
	v_mfma_f32_16x16x32_bf16 v[36:39], v[202:205], v[156:159], v[36:39]
	v_mfma_f32_16x16x32_bf16 v[32:35], v[206:209], v[156:159], v[32:35]
	v_mfma_f32_16x16x32_bf16 v[28:31], v[194:197], v[160:163], v[28:31]
	v_mfma_f32_16x16x32_bf16 v[24:27], v[198:201], v[160:163], v[24:27]
	v_mfma_f32_16x16x32_bf16 v[20:23], v[202:205], v[160:163], v[20:23]
	v_mfma_f32_16x16x32_bf16 v[16:19], v[206:209], v[160:163], v[16:19]
	v_mfma_f32_16x16x32_bf16 v[12:15], v[194:197], v[190:193], v[12:15]
	v_mfma_f32_16x16x32_bf16 v[8:11], v[198:201], v[190:193], v[8:11]
	v_mfma_f32_16x16x32_bf16 v[4:7], v[202:205], v[190:193], v[4:7]
	v_mfma_f32_16x16x32_bf16 v[0:3], v[206:209], v[190:193], v[0:3]
	s_mov_b32 s42, s29
	s_waitcnt lgkmcnt(0)
	s_waitcnt vmcnt(5)
	v_add_u32_e32 v64, s24, v108
	v_add_u32_e32 v52, 0xffffe000, v64
	v_or_b32_e32 v62, v64, v107
	v_lshrrev_b32_e32 v52, 10, v52
	s_movk_i32 s16, 0x1800
	v_mad_u32_u24 v52, v52, s16, s16
	v_cmp_lt_i32_e32 vcc, s13, v62
	v_or_b32_e32 v65, s25, v114
	v_or_b32_e32 v54, v65, v115
	v_cndmask_b32_e32 v52, 0, v52, vcc
	v_ashrrev_i32_e32 v53, 31, v52
	s_waitcnt vmcnt(4)
	v_lshlrev_b64 v[74:75], 2, v[52:53]
	v_ashrrev_i32_e32 v55, 31, v54
	v_ashrrev_i32_e32 v63, 31, v62
	v_lshl_add_u64 v[52:53], s[38:39], 0, v[74:75]
	v_lshlrev_b64 v[60:61], 2, v[54:55]
	v_readlane_b32 s16, v250, 15
	s_waitcnt vmcnt(1)
	v_lshl_add_u64 v[82:83], v[52:53], 0, v[60:61]
	v_lshlrev_b64 v[52:53], 12, v[62:63]
	v_readlane_b32 s17, v250, 16
	v_lshl_add_u64 v[74:75], s[40:41], 0, v[74:75]
	s_waitcnt vmcnt(0)
	v_lshl_add_u64 v[86:87], v[74:75], 0, v[60:61]
	v_lshl_add_u64 v[52:53], s[16:17], 0, v[52:53]
	v_lshl_add_u64 v[84:85], v[52:53], 0, v[60:61]
	global_load_dwordx4 v[66:69], v[82:83], off
	global_load_dwordx4 v[70:73], v[84:85], off
	v_lshl_add_u64 v[52:53], s[0:1], 0, v[60:61]
	v_readlane_b32 s16, v250, 21
	v_lshlrev_b64 v[78:79], 11, v[62:63]
	v_readlane_b32 s17, v250, 22
	s_waitcnt vmcnt(0)
	v_pk_fma_f32 v[68:69], v[94:95], v[68:69], v[72:73]
	v_pk_fma_f32 v[66:67], v[92:93], v[66:67], v[70:71]
	global_store_dwordx4 v[84:85], v[66:69], off
	global_load_dwordx4 v[70:73], v[52:53], off
	global_load_dwordx4 v[74:77], v[86:87], off
	v_lshl_add_u64 v[78:79], s[16:17], 0, v[78:79]
	v_lshl_add_u64 v[92:93], v[54:55], 1, v[78:79]
	s_mov_b32 s16, 0xa000
	s_waitcnt vmcnt(1)
	v_pk_mul_f32 v[72:73], v[68:69], v[72:73]
	v_pk_mul_f32 v[70:71], v[66:67], v[70:71]
	s_waitcnt vmcnt(0)
	v_pk_add_f32 v[76:77], v[76:77], 1.0 op_sel_hi:[1,0]
	v_pk_add_f32 v[74:75], v[74:75], 1.0 op_sel_hi:[1,0]
	v_pk_mul_f32 v[72:73], v[72:73], v[76:77]
	v_pk_mul_f32 v[70:71], v[70:71], v[74:75]
	v_and_b32_sdwa v77, v71, v170 dst_sel:DWORD dst_unused:UNUSED_PAD src0_sel:WORD_1 src1_sel:DWORD
	v_and_b32_sdwa v75, v70, v170 dst_sel:DWORD dst_unused:UNUSED_PAD src0_sel:WORD_1 src1_sel:DWORD
	v_add3_u32 v71, v71, v77, s56
	v_add3_u32 v70, v70, v75, s56
	v_and_b32_e32 v74, 0xffff0000, v71
	v_cvt_pk_bf16_f32 v71, v72, v73
	v_or_b32_sdwa v70, v74, v70 dst_sel:DWORD dst_unused:UNUSED_PAD src0_sel:DWORD src1_sel:WORD_1
	global_store_dwordx2 v[92:93], v[70:71], off
	global_load_dwordx4 v[70:73], v[82:83], off offset:64
	s_nop 0
	global_load_dwordx4 v[74:77], v[84:85], off offset:64
	s_waitcnt vmcnt(0)
	v_pk_fma_f32 v[72:73], v[90:91], v[72:73], v[76:77]
	v_pk_fma_f32 v[70:71], v[88:89], v[70:71], v[74:75]
	global_store_dwordx4 v[84:85], v[70:73], off offset:64
	global_load_dwordx4 v[74:77], v[52:53], off offset:64
	global_load_dwordx4 v[78:81], v[86:87], off offset:64
	s_waitcnt vmcnt(1)
	v_pk_mul_f32 v[76:77], v[72:73], v[76:77]
	v_pk_mul_f32 v[74:75], v[70:71], v[74:75]
	s_waitcnt vmcnt(0)
	v_pk_add_f32 v[80:81], v[80:81], 1.0 op_sel_hi:[1,0]
	v_pk_add_f32 v[78:79], v[78:79], 1.0 op_sel_hi:[1,0]
	v_pk_mul_f32 v[76:77], v[76:77], v[80:81]
	v_pk_mul_f32 v[74:75], v[74:75], v[78:79]
	v_and_b32_sdwa v81, v75, v170 dst_sel:DWORD dst_unused:UNUSED_PAD src0_sel:WORD_1 src1_sel:DWORD
	v_and_b32_sdwa v79, v74, v170 dst_sel:DWORD dst_unused:UNUSED_PAD src0_sel:WORD_1 src1_sel:DWORD
	v_add3_u32 v75, v75, v81, s56
	v_add3_u32 v74, v74, v79, s56
	v_and_b32_e32 v78, 0xffff0000, v75
	v_cvt_pk_bf16_f32 v75, v76, v77
	v_or_b32_sdwa v74, v78, v74 dst_sel:DWORD dst_unused:UNUSED_PAD src0_sel:DWORD src1_sel:WORD_1
	global_store_dwordx2 v[92:93], v[74:75], off offset:32
	global_load_dwordx4 v[74:77], v[82:83], off offset:128
	s_nop 0
	global_load_dwordx4 v[78:81], v[84:85], off offset:128
	s_waitcnt vmcnt(0)
	v_pk_fma_f32 v[58:59], v[58:59], v[76:77], v[80:81]
	v_pk_fma_f32 v[56:57], v[56:57], v[74:75], v[78:79]
	global_store_dwordx4 v[84:85], v[56:59], off offset:128
	global_load_dwordx4 v[74:77], v[52:53], off offset:128
	global_load_dwordx4 v[78:81], v[86:87], off offset:128
	s_waitcnt vmcnt(1)
	v_pk_mul_f32 v[76:77], v[58:59], v[76:77]
	v_pk_mul_f32 v[74:75], v[56:57], v[74:75]
	s_waitcnt vmcnt(0)
	v_pk_add_f32 v[80:81], v[80:81], 1.0 op_sel_hi:[1,0]
	v_pk_add_f32 v[78:79], v[78:79], 1.0 op_sel_hi:[1,0]
	v_pk_mul_f32 v[76:77], v[76:77], v[80:81]
	v_pk_mul_f32 v[74:75], v[74:75], v[78:79]
	v_and_b32_sdwa v81, v75, v170 dst_sel:DWORD dst_unused:UNUSED_PAD src0_sel:WORD_1 src1_sel:DWORD
	v_and_b32_sdwa v79, v74, v170 dst_sel:DWORD dst_unused:UNUSED_PAD src0_sel:WORD_1 src1_sel:DWORD
	v_add3_u32 v75, v75, v81, s56
	v_add3_u32 v74, v74, v79, s56
	v_and_b32_e32 v78, 0xffff0000, v75
	v_cvt_pk_bf16_f32 v75, v76, v77
	v_or_b32_sdwa v74, v78, v74 dst_sel:DWORD dst_unused:UNUSED_PAD src0_sel:DWORD src1_sel:WORD_1
	global_store_dwordx2 v[92:93], v[74:75], off offset:64
	global_load_dwordx4 v[74:77], v[82:83], off offset:192
	s_nop 0
	global_load_dwordx4 v[78:81], v[84:85], off offset:192
	s_waitcnt vmcnt(0)
	v_pk_fma_f32 v[76:77], v[50:51], v[76:77], v[80:81]
	v_pk_fma_f32 v[74:75], v[48:49], v[74:75], v[78:79]
	global_store_dwordx4 v[84:85], v[74:77], off offset:192
	global_load_dwordx4 v[78:81], v[52:53], off offset:192
	s_nop 0
	global_load_dwordx4 v[82:85], v[86:87], off offset:192
	v_mul_f32_e32 v48, v67, v67
	v_mul_f32_e32 v49, v71, v71
	v_fmac_f32_e32 v48, v66, v66
	v_fmac_f32_e32 v49, v70, v70
	v_fmac_f32_e32 v48, v68, v68
	v_fmac_f32_e32 v49, v72, v72
	v_fmac_f32_e32 v48, v69, v69
	v_fmac_f32_e32 v49, v73, v73
	v_add_f32_e32 v48, v48, v49
	v_mul_f32_e32 v49, v57, v57
	v_fmac_f32_e32 v49, v56, v56
	v_fmac_f32_e32 v49, v58, v58
	v_fmac_f32_e32 v49, v59, v59
	v_add_f32_e32 v48, v48, v49
	v_mul_f32_e32 v49, v75, v75
	v_fmac_f32_e32 v49, v74, v74
	v_fmac_f32_e32 v49, v76, v76
	v_fmac_f32_e32 v49, v77, v77
	v_add_f32_e32 v50, v48, v49
	ds_bpermute_b32 v51, v105, v50
	v_lshrrev_b32_e32 v48, 6, v65
	v_mul_lo_u32 v48, v48, s16
	v_ashrrev_i32_e32 v49, 31, v48
	v_lshl_add_u64 v[48:49], s[26:27], 0, v[48:49]
	s_waitcnt lgkmcnt(0)
	v_add_f32_e32 v50, v50, v51
	ds_bpermute_b32 v51, v104, v50
	v_lshl_add_u64 v[48:49], v[62:63], 2, v[48:49]
	s_waitcnt vmcnt(1)
	v_pk_mul_f32 v[56:57], v[76:77], v[80:81]
	v_pk_mul_f32 v[58:59], v[74:75], v[78:79]
	s_waitcnt vmcnt(0)
	v_pk_add_f32 v[66:67], v[84:85], 1.0 op_sel_hi:[1,0]
	v_pk_add_f32 v[68:69], v[82:83], 1.0 op_sel_hi:[1,0]
	v_pk_mul_f32 v[56:57], v[56:57], v[66:67]
	v_pk_mul_f32 v[58:59], v[58:59], v[68:69]
	v_cvt_pk_bf16_f32 v57, v56, v57
	v_cvt_pk_bf16_f32 v56, v58, v59
	global_store_dwordx2 v[92:93], v[56:57], off offset:96
	s_and_saveexec_b64 s[24:25], s[36:37]
	s_cbranch_execz .LBB0_599
	s_waitcnt lgkmcnt(0)
	v_add_f32_e32 v50, v50, v51
	global_store_dword v[48:49], v50, off

.Ltail609:
	s_add_i32 s2, s3, 2
	v_add_u32_e32 v127, v89, v90
	ds_read_b128 v[100:103], v127 offset:16384
	ds_read_b128 v[106:109], v127 offset:18432
	ds_read_b128 v[110:113], v127 offset:20480
	ds_read_b128 v[114:117], v127 offset:22528
	v_add_u32_e32 v126, v88, v90
	ds_read_b128 v[92:95], v126
	ds_read_b128 v[96:99], v126 offset:2048
	s_add_i32 s3, s3, 4
	s_min_u32 s3, s3, 63
	v_add_u32_e32 v128, v88, v91
	v_add_u32_e32 v130, v89, v91
	s_lshl_b32 s92, s3, 7
	ds_read_b128 v[118:121], v130 offset:18432
	ds_read_b128 v[122:125], v130 offset:20480
	ds_read_b128 v[132:135], v130 offset:22528
	s_waitcnt lgkmcnt(4)
	v_mfma_f32_16x16x32_bf16 v[76:79], v[100:103], v[92:95], v[76:79]
	v_lshl_add_u64 v[44:45], v[80:81], 0, s[92:93]
	v_add_co_u32_e32 v46, vcc, s7, v44
	v_mfma_f32_16x16x32_bf16 v[68:71], v[106:109], v[92:95], v[68:71]
	s_nop 0
	v_addc_co_u32_e32 v47, vcc, 0, v45, vcc
	v_mfma_f32_16x16x32_bf16 v[52:55], v[110:113], v[92:95], v[52:55]
	v_mfma_f32_16x16x32_bf16 v[40:43], v[114:117], v[92:95], v[40:43]
	s_waitcnt lgkmcnt(3)
	v_mfma_f32_16x16x32_bf16 v[92:95], v[100:103], v[96:99], v[36:39]
	s_nop 2
	ds_read_b128 v[36:39], v128
	v_mfma_f32_16x16x32_bf16 v[100:103], v[106:109], v[96:99], v[8:11]
	v_mfma_f32_16x16x32_bf16 v[106:109], v[110:113], v[96:99], v[4:7]
	ds_read_b128 v[110:113], v128 offset:2048
	v_mfma_f32_16x16x32_bf16 v[96:99], v[114:117], v[96:99], v[0:3]
	ds_read_b128 v[114:117], v130 offset:16384
	s_waitcnt vmcnt(0)
	ds_write_b128 v87, v[12:15] offset:53248
	v_add_co_u32_e32 v46, vcc, s52, v44
	s_waitcnt vmcnt(1)
	ds_write_b128 v87, v[16:19] offset:49152
	s_nop 0
	v_addc_co_u32_e32 v47, vcc, 0, v45, vcc
	v_add_co_u32_e32 v44, vcc, s34, v44
	s_nop 0
	s_nop 0
	v_addc_co_u32_e32 v45, vcc, 0, v45, vcc
	s_waitcnt vmcnt(2)
	ds_write_b128 v87, v[20:23] offset:45056
	v_lshl_add_u64 v[44:45], v[82:83], 0, s[92:93]
	s_waitcnt vmcnt(5)
	ds_write_b128 v87, v[28:31] offset:32768
	s_waitcnt lgkmcnt(4)
	v_mfma_f32_16x16x32_bf16 v[0:3], v[114:117], v[36:39], v[76:79]
	v_mfma_f32_16x16x32_bf16 v[4:7], v[118:121], v[36:39], v[68:71]
	v_add_co_u32_e32 v44, vcc, s7, v44
	s_waitcnt vmcnt(4)
	ds_write_b128 v87, v[32:35] offset:36864
	s_nop 0
	v_addc_co_u32_e32 v45, vcc, 0, v45, vcc
	v_mfma_f32_16x16x32_bf16 v[8:11], v[122:125], v[36:39], v[52:55]
	v_mfma_f32_16x16x32_bf16 v[36:39], v[132:135], v[36:39], v[40:43]
	s_waitcnt vmcnt(3)
	ds_write_b128 v87, v[24:27] offset:40960
	v_mfma_f32_16x16x32_bf16 v[40:43], v[114:117], v[110:113], v[92:95]
	v_mfma_f32_16x16x32_bf16 v[52:55], v[118:121], v[110:113], v[100:103]
	v_mfma_f32_16x16x32_bf16 v[68:71], v[122:125], v[110:113], v[106:109]
	v_mfma_f32_16x16x32_bf16 v[76:79], v[132:135], v[110:113], v[96:99]
	s_waitcnt lgkmcnt(0)
	s_barrier
	ds_read_b128 v[100:103], v127 offset:49152
	ds_read_b128 v[106:109], v127 offset:51200
	ds_read_b128 v[110:113], v127 offset:53248
	ds_read_b128 v[114:117], v127 offset:55296
	ds_read_b128 v[92:95], v126 offset:32768
	ds_read_b128 v[96:99], v126 offset:34816
	s_min_u32 s3, s2, 60
	s_lshl_b32 s92, s3, 7
	ds_read_b128 v[118:121], v130 offset:51200
	ds_read_b128 v[122:125], v130 offset:53248
	ds_read_b128 v[132:135], v130 offset:55296
	s_waitcnt lgkmcnt(4)
	v_mfma_f32_16x16x32_bf16 v[0:3], v[100:103], v[92:95], v[0:3]
	v_lshl_add_u64 v[12:13], v[80:81], 0, s[92:93]
	v_add_co_u32_e32 v14, vcc, s7, v12
	v_mfma_f32_16x16x32_bf16 v[4:7], v[106:109], v[92:95], v[4:7]
	s_nop 0
	v_addc_co_u32_e32 v15, vcc, 0, v13, vcc
	v_mfma_f32_16x16x32_bf16 v[8:11], v[110:113], v[92:95], v[8:11]
	v_mfma_f32_16x16x32_bf16 v[36:39], v[114:117], v[92:95], v[36:39]
	s_waitcnt lgkmcnt(3)
	v_mfma_f32_16x16x32_bf16 v[92:95], v[100:103], v[96:99], v[40:43]
	s_nop 2
	ds_read_b128 v[40:43], v128 offset:32768
	v_mfma_f32_16x16x32_bf16 v[100:103], v[106:109], v[96:99], v[52:55]
	v_mfma_f32_16x16x32_bf16 v[106:109], v[110:113], v[96:99], v[68:71]
	ds_read_b128 v[110:113], v128 offset:34816
	v_mfma_f32_16x16x32_bf16 v[96:99], v[114:117], v[96:99], v[76:79]
	ds_read_b128 v[114:117], v130 offset:49152
	v_add_co_u32_e32 v14, vcc, s52, v12
	s_nop 0
	s_nop 0
	v_addc_co_u32_e32 v15, vcc, 0, v13, vcc
	v_add_co_u32_e32 v12, vcc, s34, v12
	s_nop 0
	s_nop 0
	v_addc_co_u32_e32 v13, vcc, 0, v13, vcc
	v_lshl_add_u64 v[12:13], v[82:83], 0, s[92:93]
	s_waitcnt lgkmcnt(0)
	v_mfma_f32_16x16x32_bf16 v[76:79], v[114:117], v[40:43], v[0:3]
	v_mfma_f32_16x16x32_bf16 v[68:71], v[118:121], v[40:43], v[4:7]
	v_add_co_u32_e32 v12, vcc, s7, v12
	s_nop 0
	s_nop 0
	v_addc_co_u32_e32 v13, vcc, 0, v13, vcc
	v_mfma_f32_16x16x32_bf16 v[52:55], v[122:125], v[40:43], v[8:11]
	v_mfma_f32_16x16x32_bf16 v[40:43], v[132:135], v[40:43], v[36:39]
	v_mfma_f32_16x16x32_bf16 v[36:39], v[114:117], v[110:113], v[92:95]
	v_mfma_f32_16x16x32_bf16 v[8:11], v[118:121], v[110:113], v[100:103]
	v_mfma_f32_16x16x32_bf16 v[4:7], v[122:125], v[110:113], v[106:109]
	v_mfma_f32_16x16x32_bf16 v[0:3], v[132:135], v[110:113], v[96:99]
	s_mov_b32 s3, s2
	s_waitcnt lgkmcnt(0)
	v_readlane_b32 s2, v251, 18
	s_waitcnt vmcnt(1)
	s_nop 0
	v_add_u32_e32 v18, s2, v86
	v_readlane_b32 s2, v251, 19
	s_waitcnt vmcnt(0)
	v_add_u32_e32 v13, 0xffffe000, v18
	v_or_b32_e32 v12, v18, v85
	v_lshl_or_b32 v19, v84, 2, s2
	v_lshrrev_b32_e32 v13, 10, v13
	s_movk_i32 s2, 0x1800
	v_mad_u32_u24 v13, v13, s2, s2
	v_cmp_lt_i32_e32 vcc, s13, v12
	v_lshlrev_b32_e32 v128, 2, v19
	v_readlane_b32 s2, v250, 15
	v_cndmask_b32_e32 v14, 0, v13, vcc
	v_ashrrev_i32_e32 v15, 31, v14
	v_lshlrev_b64 v[24:25], 2, v[14:15]
	v_ashrrev_i32_e32 v13, 31, v12
	v_lshl_add_u64 v[14:15], s[38:39], 0, v[24:25]
	v_lshl_add_u64 v[48:49], v[14:15], 0, v[128:129]
	v_lshlrev_b64 v[14:15], 12, v[12:13]
	v_readlane_b32 s3, v250, 16
	v_lshl_add_u64 v[28:29], s[40:41], 0, v[24:25]
	v_lshlrev_b64 v[32:33], 11, v[12:13]
	v_lshl_add_u64 v[14:15], s[2:3], 0, v[14:15]
	v_lshl_add_u64 v[50:51], v[14:15], 0, v[128:129]
	global_load_dwordx4 v[72:75], v[48:49], off
	global_load_dwordx4 v[80:83], v[48:49], off offset:64
	global_load_dwordx4 v[88:91], v[48:49], off offset:128
	global_load_dwordx4 v[136:139], v[48:49], off offset:192
	global_load_dwordx4 v[194:197], v[50:51], off
	global_load_dwordx4 v[198:201], v[50:51], off offset:64
	global_load_dwordx4 v[202:205], v[50:51], off offset:128
	global_load_dwordx4 v[206:209], v[50:51], off offset:192
	v_add_co_u32_e32 v58, vcc, 0x10000, v50
	s_nop 1
	v_addc_co_u32_e32 v59, vcc, 0, v51, vcc
	global_load_dwordx4 v[210:213], v[58:59], off
	global_load_dwordx4 v[214:217], v[58:59], off offset:64
	global_load_dwordx4 v[218:221], v[58:59], off offset:128
	global_load_dwordx4 v[222:225], v[58:59], off offset:192
	v_readlane_b32 s2, v250, 21
	v_readlane_b32 s3, v250, 22
	v_cmp_eq_u32_e32 vcc, 0, v84
	s_waitcnt vmcnt(4)
	v_pk_fma_f32 v[22:23], v[78:79], v[74:75], v[196:197]
	v_pk_fma_f32 v[20:21], v[76:77], v[72:73], v[194:195]
	global_store_dwordx4 v[50:51], v[20:23], off
	v_lshl_add_u64 v[14:15], v[28:29], 0, v[128:129]
	global_load_dwordx4 v[140:143], v128, s[0:1]
	global_load_dwordx4 v[144:147], v128, s[0:1] offset:64
	global_load_dwordx4 v[148:151], v128, s[0:1] offset:128
	global_load_dwordx4 v[152:155], v128, s[0:1] offset:192
	global_load_dwordx4 v[156:159], v[14:15], off
	global_load_dwordx4 v[160:163], v[14:15], off offset:64
	global_load_dwordx4 v[180:183], v[14:15], off offset:128
	global_load_dwordx4 v[190:193], v[14:15], off offset:192
	v_lshlrev_b32_e32 v16, 1, v19
	v_mov_b32_e32 v17, v129
	v_lshl_add_u64 v[32:33], s[2:3], 0, v[32:33]
	v_lshl_add_u64 v[56:57], v[32:33], 0, v[16:17]
	s_waitcnt vmcnt(0)
	v_pk_mul_f32 v[26:27], v[22:23], v[142:143]
	v_pk_mul_f32 v[24:25], v[20:21], v[140:141]
	s_waitcnt vmcnt(0)
	v_pk_add_f32 v[30:31], v[158:159], 1.0 op_sel_hi:[1,0]
	v_pk_add_f32 v[28:29], v[156:157], 1.0 op_sel_hi:[1,0]
	v_pk_mul_f32 v[26:27], v[26:27], v[30:31]
	v_pk_mul_f32 v[24:25], v[24:25], v[28:29]
	v_and_b32_sdwa v19, v26, v170 dst_sel:DWORD dst_unused:UNUSED_PAD src0_sel:WORD_1 src1_sel:DWORD
	v_and_b32_sdwa v29, v27, v170 dst_sel:DWORD dst_unused:UNUSED_PAD src0_sel:WORD_1 src1_sel:DWORD
	v_and_b32_sdwa v30, v25, v170 dst_sel:DWORD dst_unused:UNUSED_PAD src0_sel:WORD_1 src1_sel:DWORD
	v_and_b32_sdwa v28, v24, v170 dst_sel:DWORD dst_unused:UNUSED_PAD src0_sel:WORD_1 src1_sel:DWORD
	v_add3_u32 v19, v26, v19, s56
	v_add3_u32 v26, v27, v29, s56
	v_add3_u32 v25, v25, v30, s56
	v_add3_u32 v24, v24, v28, s56
	v_and_b32_e32 v26, 0xffff0000, v26
	v_and_b32_e32 v27, 0xffff0000, v25
	v_or_b32_sdwa v25, v26, v19 dst_sel:DWORD dst_unused:UNUSED_PAD src0_sel:DWORD src1_sel:WORD_1
	v_or_b32_sdwa v24, v27, v24 dst_sel:DWORD dst_unused:UNUSED_PAD src0_sel:DWORD src1_sel:WORD_1
	global_store_dwordx2 v[56:57], v[24:25], off
	s_nop 0
	s_waitcnt vmcnt(0)
	v_pk_fma_f32 v[26:27], v[70:71], v[82:83], v[200:201]
	v_pk_fma_f32 v[24:25], v[68:69], v[80:81], v[198:199]
	global_store_dwordx4 v[50:51], v[24:27], off offset:64
	v_pk_mul_f32 v[30:31], v[26:27], v[146:147]
	v_pk_mul_f32 v[28:29], v[24:25], v[144:145]
	v_pk_add_f32 v[34:35], v[162:163], 1.0 op_sel_hi:[1,0]
	v_pk_add_f32 v[32:33], v[160:161], 1.0 op_sel_hi:[1,0]
	v_pk_mul_f32 v[30:31], v[30:31], v[34:35]
	v_pk_mul_f32 v[28:29], v[28:29], v[32:33]
	v_and_b32_sdwa v19, v30, v170 dst_sel:DWORD dst_unused:UNUSED_PAD src0_sel:WORD_1 src1_sel:DWORD
	v_and_b32_sdwa v33, v31, v170 dst_sel:DWORD dst_unused:UNUSED_PAD src0_sel:WORD_1 src1_sel:DWORD
	v_and_b32_sdwa v34, v29, v170 dst_sel:DWORD dst_unused:UNUSED_PAD src0_sel:WORD_1 src1_sel:DWORD
	v_and_b32_sdwa v32, v28, v170 dst_sel:DWORD dst_unused:UNUSED_PAD src0_sel:WORD_1 src1_sel:DWORD
	v_add3_u32 v19, v30, v19, s56
	v_add3_u32 v30, v31, v33, s56
	v_add3_u32 v29, v29, v34, s56
	v_add3_u32 v28, v28, v32, s56
	v_and_b32_e32 v30, 0xffff0000, v30
	v_and_b32_e32 v31, 0xffff0000, v29
	v_or_b32_sdwa v29, v30, v19 dst_sel:DWORD dst_unused:UNUSED_PAD src0_sel:DWORD src1_sel:WORD_1
	v_or_b32_sdwa v28, v31, v28 dst_sel:DWORD dst_unused:UNUSED_PAD src0_sel:DWORD src1_sel:WORD_1
	global_store_dwordx2 v[56:57], v[28:29], off offset:32
	s_nop 0
	v_pk_fma_f32 v[30:31], v[54:55], v[90:91], v[204:205]
	v_pk_fma_f32 v[28:29], v[52:53], v[88:89], v[202:203]
	global_store_dwordx4 v[50:51], v[28:31], off offset:128
	v_pk_mul_f32 v[34:35], v[30:31], v[150:151]
	v_pk_mul_f32 v[32:33], v[28:29], v[148:149]
	v_pk_add_f32 v[46:47], v[182:183], 1.0 op_sel_hi:[1,0]
	v_pk_add_f32 v[44:45], v[180:181], 1.0 op_sel_hi:[1,0]
	v_pk_mul_f32 v[34:35], v[34:35], v[46:47]
	v_pk_mul_f32 v[32:33], v[32:33], v[44:45]
	v_and_b32_sdwa v19, v34, v170 dst_sel:DWORD dst_unused:UNUSED_PAD src0_sel:WORD_1 src1_sel:DWORD
	v_and_b32_sdwa v45, v35, v170 dst_sel:DWORD dst_unused:UNUSED_PAD src0_sel:WORD_1 src1_sel:DWORD
	v_and_b32_sdwa v46, v33, v170 dst_sel:DWORD dst_unused:UNUSED_PAD src0_sel:WORD_1 src1_sel:DWORD
	v_and_b32_sdwa v44, v32, v170 dst_sel:DWORD dst_unused:UNUSED_PAD src0_sel:WORD_1 src1_sel:DWORD
	v_add3_u32 v19, v34, v19, s56
	v_add3_u32 v34, v35, v45, s56
	v_add3_u32 v33, v33, v46, s56
	v_add3_u32 v32, v32, v44, s56
	v_and_b32_e32 v34, 0xffff0000, v34
	v_and_b32_e32 v35, 0xffff0000, v33
	v_or_b32_sdwa v33, v34, v19 dst_sel:DWORD dst_unused:UNUSED_PAD src0_sel:DWORD src1_sel:WORD_1
	v_or_b32_sdwa v32, v35, v32 dst_sel:DWORD dst_unused:UNUSED_PAD src0_sel:DWORD src1_sel:WORD_1
	global_store_dwordx2 v[56:57], v[32:33], off offset:64
	s_nop 0
	v_pk_fma_f32 v[34:35], v[42:43], v[138:139], v[208:209]
	v_pk_fma_f32 v[32:33], v[40:41], v[136:137], v[206:207]
	global_store_dwordx4 v[50:51], v[32:35], off offset:192
	v_mul_f32_e32 v14, v21, v21
	v_mul_f32_e32 v15, v25, v25
	v_fmac_f32_e32 v14, v20, v20
	v_fmac_f32_e32 v15, v24, v24
	v_fmac_f32_e32 v14, v22, v22
	v_fmac_f32_e32 v15, v26, v26
	v_fmac_f32_e32 v14, v23, v23
	v_fmac_f32_e32 v15, v27, v27
	v_add_f32_e32 v14, v14, v15
	v_mul_f32_e32 v15, v29, v29
	v_fmac_f32_e32 v15, v28, v28
	v_fmac_f32_e32 v15, v30, v30
	v_fmac_f32_e32 v15, v31, v31
	v_add_f32_e32 v14, v14, v15
	v_mul_f32_e32 v15, v33, v33
	v_fmac_f32_e32 v15, v32, v32
	v_fmac_f32_e32 v15, v34, v34
	v_fmac_f32_e32 v15, v35, v35
	v_add_f32_e32 v14, v14, v15
	ds_bpermute_b32 v15, v105, v14
	s_waitcnt lgkmcnt(0)
	v_add_f32_e32 v14, v14, v15
	ds_bpermute_b32 v15, v104, v14
	v_pk_mul_f32 v[20:21], v[34:35], v[154:155]
	v_pk_mul_f32 v[22:23], v[32:33], v[152:153]
	v_pk_add_f32 v[24:25], v[192:193], 1.0 op_sel_hi:[1,0]
	v_pk_add_f32 v[26:27], v[190:191], 1.0 op_sel_hi:[1,0]
	v_pk_mul_f32 v[20:21], v[20:21], v[24:25]
	v_pk_mul_f32 v[22:23], v[22:23], v[26:27]
	v_and_b32_sdwa v19, v20, v170 dst_sel:DWORD dst_unused:UNUSED_PAD src0_sel:WORD_1 src1_sel:DWORD
	v_and_b32_sdwa v25, v21, v170 dst_sel:DWORD dst_unused:UNUSED_PAD src0_sel:WORD_1 src1_sel:DWORD
	v_and_b32_sdwa v26, v23, v170 dst_sel:DWORD dst_unused:UNUSED_PAD src0_sel:WORD_1 src1_sel:DWORD
	v_and_b32_sdwa v24, v22, v170 dst_sel:DWORD dst_unused:UNUSED_PAD src0_sel:WORD_1 src1_sel:DWORD
	v_add3_u32 v19, v20, v19, s56
	v_add3_u32 v20, v21, v25, s56
	v_add3_u32 v21, v23, v26, s56
	v_add3_u32 v22, v22, v24, s56
	v_and_b32_e32 v20, 0xffff0000, v20
	v_and_b32_e32 v23, 0xffff0000, v21
	v_or_b32_sdwa v21, v20, v19 dst_sel:DWORD dst_unused:UNUSED_PAD src0_sel:DWORD src1_sel:WORD_1
	v_or_b32_sdwa v20, v23, v22 dst_sel:DWORD dst_unused:UNUSED_PAD src0_sel:DWORD src1_sel:WORD_1
	global_store_dwordx2 v[56:57], v[20:21], off offset:96
	s_and_saveexec_b64 s[2:3], vcc
	s_cbranch_execz .LBB0_612
	v_readlane_b32 s16, v253, 20
	s_add_u32 s24, s26, s16
	s_addc_u32 s25, s27, 0
	v_lshl_add_u64 v[20:21], v[12:13], 2, s[24:25]
	s_waitcnt lgkmcnt(0)
	v_add_f32_e32 v13, v14, v15
	global_store_dword v[20:21], v13, off

.Ltail628:
	s_add_i32 s3, s24, 2
	v_add_u32_e32 v227, v144, v145
	ds_read_b128 v[36:39], v227 offset:16384
	ds_read_b128 v[40:43], v227 offset:18432
	ds_read_b128 v[44:47], v227 offset:20480
	ds_read_b128 v[48:51], v227 offset:22528
	v_add_u32_e32 v226, v143, v145
	ds_read_b128 v[16:19], v226
	v_add_u32_e32 v232, v144, v146
	s_add_i32 s24, s24, 4
	ds_read_b128 v[20:23], v226 offset:2048
	ds_read_b128 v[216:219], v232 offset:20480
	s_min_u32 s24, s24, 15
	s_lshl_b32 s92, s24, 7
	ds_read_b128 v[28:31], v226 offset:4096
	ds_read_b128 v[32:35], v226 offset:6144
	v_add_u32_e32 v228, v143, v146
	v_lshl_add_u64 v[224:225], v[138:139], 0, s[92:93]
	ds_read_b128 v[192:195], v228
	ds_read_b128 v[196:199], v228 offset:2048
	ds_read_b128 v[200:203], v228 offset:4096
	ds_read_b128 v[204:207], v228 offset:6144
	ds_read_b128 v[208:211], v232 offset:16384
	ds_read_b128 v[212:215], v232 offset:18432
	ds_read_b128 v[220:223], v232 offset:22528
	s_waitcnt lgkmcnt(11)
	v_mfma_f32_16x16x32_bf16 v[92:95], v[36:39], v[16:19], v[92:95]
	v_mfma_f32_16x16x32_bf16 v[88:91], v[40:43], v[16:19], v[88:91]
	v_mfma_f32_16x16x32_bf16 v[84:87], v[44:47], v[16:19], v[84:87]
	v_mfma_f32_16x16x32_bf16 v[16:19], v[48:51], v[16:19], v[80:83]
	s_nop 2
	s_waitcnt vmcnt(7)
	ds_write_b128 v156, v[96:99] offset:32768
	v_add_co_u32_e32 v96, vcc, s11, v224
	s_waitcnt lgkmcnt(11)
	v_mfma_f32_16x16x32_bf16 v[76:79], v[36:39], v[20:23], v[76:79]
	v_addc_co_u32_e32 v97, vcc, 0, v225, vcc
	v_mfma_f32_16x16x32_bf16 v[72:75], v[40:43], v[20:23], v[72:75]
	v_mfma_f32_16x16x32_bf16 v[68:71], v[44:47], v[20:23], v[68:71]
	v_mfma_f32_16x16x32_bf16 v[20:23], v[48:51], v[20:23], v[64:67]
	s_nop 2
	v_add_co_u32_e32 v96, vcc, s33, v224
	s_waitcnt vmcnt(6)
	ds_write_b128 v156, v[100:103] offset:36864
	s_nop 0
	v_addc_co_u32_e32 v97, vcc, 0, v225, vcc
	s_waitcnt lgkmcnt(10)
	v_mfma_f32_16x16x32_bf16 v[60:63], v[36:39], v[28:31], v[60:63]
	v_mfma_f32_16x16x32_bf16 v[56:59], v[40:43], v[28:31], v[56:59]
	v_mfma_f32_16x16x32_bf16 v[52:55], v[44:47], v[28:31], v[52:55]
	v_mfma_f32_16x16x32_bf16 v[24:27], v[48:51], v[28:31], v[24:27]
	s_waitcnt vmcnt(5)
	ds_write_b128 v156, v[104:107] offset:40960
	s_waitcnt lgkmcnt(10)
	v_mfma_f32_16x16x32_bf16 v[12:15], v[36:39], v[32:35], v[12:15]
	v_add_co_u32_e32 v36, vcc, s59, v224
	s_nop 1
	v_addc_co_u32_e32 v37, vcc, 0, v225, vcc
	v_mfma_f32_16x16x32_bf16 v[8:11], v[40:43], v[32:35], v[8:11]
	v_mfma_f32_16x16x32_bf16 v[4:7], v[44:47], v[32:35], v[4:7]
	v_mfma_f32_16x16x32_bf16 v[0:3], v[48:51], v[32:35], v[0:3]
	s_waitcnt vmcnt(4)
	ds_write_b128 v156, v[112:115] offset:45056
	s_waitcnt lgkmcnt(10)
	v_mfma_f32_16x16x32_bf16 v[44:47], v[216:219], v[192:195], v[84:87]
	s_nop 2
	v_lshl_add_u64 v[84:85], v[140:141], 0, s[92:93]
	v_add_co_u32_e32 v86, vcc, s11, v84
	s_waitcnt lgkmcnt(6)
	v_mfma_f32_16x16x32_bf16 v[36:39], v[208:211], v[192:195], v[92:95]
	v_addc_co_u32_e32 v87, vcc, 0, v85, vcc
	s_waitcnt lgkmcnt(5)
	v_mfma_f32_16x16x32_bf16 v[40:43], v[212:215], v[192:195], v[88:91]
	s_waitcnt lgkmcnt(4)
	v_mfma_f32_16x16x32_bf16 v[16:19], v[220:223], v[192:195], v[16:19]
	s_waitcnt vmcnt(3)
	ds_write_b128 v156, v[108:111] offset:49152
	v_mfma_f32_16x16x32_bf16 v[76:79], v[208:211], v[196:199], v[76:79]
	v_mfma_f32_16x16x32_bf16 v[72:75], v[212:215], v[196:199], v[72:75]
	v_mfma_f32_16x16x32_bf16 v[68:71], v[216:219], v[196:199], v[68:71]
	v_mfma_f32_16x16x32_bf16 v[20:23], v[220:223], v[196:199], v[20:23]
	v_add_co_u32_e32 v86, vcc, s33, v84
	s_waitcnt vmcnt(2)
	ds_write_b128 v156, v[116:119] offset:53248
	v_addc_co_u32_e32 v87, vcc, 0, v85, vcc
	v_add_co_u32_e32 v84, vcc, s59, v84
	v_mfma_f32_16x16x32_bf16 v[60:63], v[208:211], v[200:203], v[60:63]
	s_nop 0
	v_addc_co_u32_e32 v85, vcc, 0, v85, vcc
	v_mfma_f32_16x16x32_bf16 v[56:59], v[212:215], v[200:203], v[56:59]
	v_mfma_f32_16x16x32_bf16 v[52:55], v[216:219], v[200:203], v[52:55]
	v_mfma_f32_16x16x32_bf16 v[24:27], v[220:223], v[200:203], v[24:27]
	s_waitcnt vmcnt(1)
	ds_write_b128 v156, v[120:123] offset:57344
	v_mfma_f32_16x16x32_bf16 v[12:15], v[208:211], v[204:207], v[12:15]
	v_mfma_f32_16x16x32_bf16 v[8:11], v[212:215], v[204:207], v[8:11]
	v_mfma_f32_16x16x32_bf16 v[4:7], v[216:219], v[204:207], v[4:7]
	v_mfma_f32_16x16x32_bf16 v[0:3], v[220:223], v[204:207], v[0:3]
	s_waitcnt vmcnt(0)
	ds_write_b128 v156, v[124:127] offset:61440
	s_waitcnt lgkmcnt(0)
	s_barrier
	ds_read_b128 v[112:115], v227 offset:49152
	ds_read_b128 v[116:119], v227 offset:51200
	ds_read_b128 v[120:123], v227 offset:53248
	ds_read_b128 v[124:127], v227 offset:55296
	ds_read_b128 v[84:87], v226 offset:32768
	ds_read_b128 v[88:91], v226 offset:34816
	ds_read_b128 v[92:95], v226 offset:36864
	ds_read_b128 v[108:111], v226 offset:38912
	ds_read_b128 v[204:207], v228 offset:32768
	ds_read_b128 v[208:211], v228 offset:34816
	ds_read_b128 v[212:215], v228 offset:36864
	ds_read_b128 v[216:219], v228 offset:38912
	ds_read_b128 v[220:223], v232 offset:49152
	ds_read_b128 v[224:227], v232 offset:51200
	ds_read_b128 v[228:231], v232 offset:53248
	ds_read_b128 v[232:235], v232 offset:55296
	s_min_u32 s24, s3, 12
	s_lshl_b32 s92, s24, 7
	s_waitcnt lgkmcnt(11)
	v_mfma_f32_16x16x32_bf16 v[36:39], v[112:115], v[84:87], v[36:39]
	v_mfma_f32_16x16x32_bf16 v[40:43], v[116:119], v[84:87], v[40:43]
	v_mfma_f32_16x16x32_bf16 v[44:47], v[120:123], v[84:87], v[44:47]
	v_mfma_f32_16x16x32_bf16 v[16:19], v[124:127], v[84:87], v[16:19]
	v_lshl_add_u64 v[84:85], v[138:139], 0, s[92:93]
	v_add_co_u32_e32 v80, vcc, s11, v84
	s_waitcnt lgkmcnt(10)
	v_mfma_f32_16x16x32_bf16 v[76:79], v[112:115], v[88:91], v[76:79]
	v_addc_co_u32_e32 v81, vcc, 0, v85, vcc
	v_mfma_f32_16x16x32_bf16 v[72:75], v[116:119], v[88:91], v[72:75]
	v_mfma_f32_16x16x32_bf16 v[68:71], v[120:123], v[88:91], v[68:71]
	v_mfma_f32_16x16x32_bf16 v[20:23], v[124:127], v[88:91], v[20:23]
	v_add_co_u32_e32 v64, vcc, s33, v84
	s_waitcnt lgkmcnt(9)
	v_mfma_f32_16x16x32_bf16 v[60:63], v[112:115], v[92:95], v[60:63]
	v_addc_co_u32_e32 v65, vcc, 0, v85, vcc
	v_mfma_f32_16x16x32_bf16 v[56:59], v[116:119], v[92:95], v[56:59]
	v_mfma_f32_16x16x32_bf16 v[52:55], v[120:123], v[92:95], v[52:55]
	v_mfma_f32_16x16x32_bf16 v[24:27], v[124:127], v[92:95], v[24:27]
	v_add_co_u32_e32 v28, vcc, s59, v84
	s_waitcnt lgkmcnt(8)
	v_mfma_f32_16x16x32_bf16 v[12:15], v[112:115], v[108:111], v[12:15]
	v_addc_co_u32_e32 v29, vcc, 0, v85, vcc
	v_mfma_f32_16x16x32_bf16 v[8:11], v[116:119], v[108:111], v[8:11]
	v_mfma_f32_16x16x32_bf16 v[4:7], v[120:123], v[108:111], v[4:7]
	v_mfma_f32_16x16x32_bf16 v[0:3], v[124:127], v[108:111], v[0:3]
	s_waitcnt lgkmcnt(0)
	v_mfma_f32_16x16x32_bf16 v[80:83], v[232:235], v[204:207], v[16:19]
	s_nop 2
	v_lshl_add_u64 v[16:17], v[140:141], 0, s[92:93]
	v_add_co_u32_e32 v18, vcc, s11, v16
	v_mfma_f32_16x16x32_bf16 v[92:95], v[220:223], v[204:207], v[36:39]
	s_nop 0
	v_addc_co_u32_e32 v19, vcc, 0, v17, vcc
	v_mfma_f32_16x16x32_bf16 v[88:91], v[224:227], v[204:207], v[40:43]
	v_mfma_f32_16x16x32_bf16 v[84:87], v[228:231], v[204:207], v[44:47]
	v_mfma_f32_16x16x32_bf16 v[76:79], v[220:223], v[208:211], v[76:79]
	v_mfma_f32_16x16x32_bf16 v[72:75], v[224:227], v[208:211], v[72:75]
	v_mfma_f32_16x16x32_bf16 v[68:71], v[228:231], v[208:211], v[68:71]
	v_mfma_f32_16x16x32_bf16 v[64:67], v[232:235], v[208:211], v[20:23]
	v_add_co_u32_e32 v18, vcc, s33, v16
	s_nop 1
	v_addc_co_u32_e32 v19, vcc, 0, v17, vcc
	v_add_co_u32_e32 v16, vcc, s59, v16
	v_mfma_f32_16x16x32_bf16 v[60:63], v[220:223], v[212:215], v[60:63]
	s_nop 0
	v_addc_co_u32_e32 v17, vcc, 0, v17, vcc
	v_mfma_f32_16x16x32_bf16 v[56:59], v[224:227], v[212:215], v[56:59]
	v_mfma_f32_16x16x32_bf16 v[52:55], v[228:231], v[212:215], v[52:55]
	v_mfma_f32_16x16x32_bf16 v[24:27], v[232:235], v[212:215], v[24:27]
	v_mfma_f32_16x16x32_bf16 v[12:15], v[220:223], v[216:219], v[12:15]
	v_mfma_f32_16x16x32_bf16 v[8:11], v[224:227], v[216:219], v[8:11]
	v_mfma_f32_16x16x32_bf16 v[4:7], v[228:231], v[216:219], v[4:7]
	v_mfma_f32_16x16x32_bf16 v[0:3], v[232:235], v[216:219], v[0:3]
	s_mov_b32 s24, s3
	s_waitcnt lgkmcnt(0)
	s_and_saveexec_b64 s[24:25], s[36:37]
	s_cbranch_execz .LBB0_631
	v_add_f32_e32 v16, 0, v128
	v_add_f32_e32 v16, v16, v157
	v_add_f32_e32 v16, v16, v158
	v_add_f32_e32 v16, v16, v159
	v_add_f32_e32 v16, v16, v160
	v_add_f32_e32 v16, v16, v161
	v_add_f32_e32 v16, v16, v162
	v_add_f32_e32 v16, v16, v163
	v_add_f32_e32 v16, v16, v164
	v_add_f32_e32 v16, v16, v165
	v_add_f32_e32 v16, v16, v168
	v_add_f32_e32 v16, v16, v175
	v_add_f32_e32 v16, v16, v179
	v_add_f32_e32 v16, v16, v183
	v_add_f32_e32 v16, v16, v190
	v_add_f32_e32 v16, v16, v191
	v_fmamk_f32 v16, v16, 0x3a800000, v167
	s_mov_b32 s3, 0x800000
	v_mul_f32_e32 v17, 0x4b800000, v16
	v_cmp_gt_f32_e32 vcc, s3, v16
	s_nop 1
	v_cndmask_b32_e32 v16, v16, v17, vcc
	v_rsq_f32_e32 v16, v16
	s_nop 0
	v_mul_f32_e32 v17, 0x45800000, v16
	v_cndmask_b32_e32 v16, v16, v17, vcc
	ds_write_b32 v155, v16

.Ltail666:
	s_add_i32 s2, s3, 2
	v_add_u32_e32 v123, v111, v126
	ds_read_b128 v[154:157], v123 offset:16384
	ds_read_b128 v[158:161], v123 offset:18432
	ds_read_b128 v[162:165], v123 offset:20480
	ds_read_b128 v[190:193], v123 offset:22528
	v_add_u32_e32 v122, v110, v126
	ds_read_b128 v[138:141], v122
	ds_read_b128 v[142:145], v122 offset:2048
	v_add_u32_e32 v125, v111, v137
	s_add_i32 s3, s3, 4
	ds_read_b128 v[146:149], v122 offset:4096
	ds_read_b128 v[214:217], v125 offset:18432
	s_min_u32 s3, s3, 15
	ds_read_b128 v[210:213], v125 offset:16384
	ds_read_b128 v[218:221], v125 offset:20480
	ds_read_b128 v[222:225], v125 offset:22528
	s_lshl_b32 s92, s3, 7
	v_add_u32_e32 v124, v110, v137
	v_lshl_add_u64 v[226:227], v[102:103], 0, s[92:93]
	ds_read_b128 v[150:153], v122 offset:6144
	ds_read_b128 v[194:197], v124
	ds_read_b128 v[198:201], v124 offset:2048
	ds_read_b128 v[202:205], v124 offset:4096
	ds_read_b128 v[206:209], v124 offset:6144
	s_waitcnt lgkmcnt(11)
	v_mfma_f32_16x16x32_bf16 v[92:95], v[154:157], v[138:141], v[92:95]
	v_mfma_f32_16x16x32_bf16 v[88:91], v[158:161], v[138:141], v[88:91]
	v_mfma_f32_16x16x32_bf16 v[84:87], v[162:165], v[138:141], v[84:87]
	v_mfma_f32_16x16x32_bf16 v[80:83], v[190:193], v[138:141], v[80:83]
	s_waitcnt vmcnt(7)
	ds_write_b128 v121, v[28:31] offset:32768
	s_waitcnt lgkmcnt(11)
	v_mfma_f32_16x16x32_bf16 v[28:31], v[154:157], v[142:145], v[76:79]
	s_nop 2
	v_add_co_u32_e32 v76, vcc, s11, v226
	v_mfma_f32_16x16x32_bf16 v[72:75], v[158:161], v[142:145], v[72:75]
	s_nop 0
	v_addc_co_u32_e32 v77, vcc, 0, v227, vcc
	v_mfma_f32_16x16x32_bf16 v[68:71], v[162:165], v[142:145], v[68:71]
	v_mfma_f32_16x16x32_bf16 v[64:67], v[190:193], v[142:145], v[64:67]
	s_waitcnt vmcnt(6)
	ds_write_b128 v121, v[32:35] offset:36864
	s_waitcnt lgkmcnt(11)
	v_mfma_f32_16x16x32_bf16 v[32:35], v[154:157], v[146:149], v[48:51]
	s_nop 2
	v_add_co_u32_e32 v48, vcc, s33, v226
	v_mfma_f32_16x16x32_bf16 v[24:27], v[158:161], v[146:149], v[24:27]
	s_nop 0
	v_addc_co_u32_e32 v49, vcc, 0, v227, vcc
	v_mfma_f32_16x16x32_bf16 v[20:23], v[162:165], v[146:149], v[20:23]
	v_mfma_f32_16x16x32_bf16 v[16:19], v[190:193], v[146:149], v[16:19]
	s_waitcnt vmcnt(5)
	ds_write_b128 v121, v[36:39] offset:40960
	v_add_co_u32_e32 v36, vcc, s59, v226
	s_waitcnt lgkmcnt(7)
	v_mfma_f32_16x16x32_bf16 v[12:15], v[154:157], v[150:153], v[12:15]
	v_addc_co_u32_e32 v37, vcc, 0, v227, vcc
	v_mfma_f32_16x16x32_bf16 v[8:11], v[158:161], v[150:153], v[8:11]
	v_mfma_f32_16x16x32_bf16 v[4:7], v[162:165], v[150:153], v[4:7]
	v_mfma_f32_16x16x32_bf16 v[0:3], v[190:193], v[150:153], v[0:3]
	s_waitcnt vmcnt(4)
	ds_write_b128 v121, v[44:47] offset:45056
	s_waitcnt lgkmcnt(7)
	v_mfma_f32_16x16x32_bf16 v[44:47], v[214:217], v[194:197], v[88:91]
	s_nop 2
	v_lshl_add_u64 v[88:89], v[104:105], 0, s[92:93]
	v_mfma_f32_16x16x32_bf16 v[36:39], v[210:213], v[194:197], v[92:95]
	v_mfma_f32_16x16x32_bf16 v[84:87], v[218:221], v[194:197], v[84:87]
	v_mfma_f32_16x16x32_bf16 v[80:83], v[222:225], v[194:197], v[80:83]
	s_waitcnt vmcnt(3)
	ds_write_b128 v121, v[40:43] offset:49152
	s_waitcnt lgkmcnt(7)
	v_mfma_f32_16x16x32_bf16 v[40:43], v[210:213], v[198:201], v[28:31]
	s_nop 2
	v_add_co_u32_e32 v28, vcc, s11, v88
	v_mfma_f32_16x16x32_bf16 v[72:75], v[214:217], v[198:201], v[72:75]
	s_nop 0
	v_addc_co_u32_e32 v29, vcc, 0, v89, vcc
	v_mfma_f32_16x16x32_bf16 v[68:71], v[218:221], v[198:201], v[68:71]
	v_mfma_f32_16x16x32_bf16 v[64:67], v[222:225], v[198:201], v[64:67]
	v_add_co_u32_e32 v28, vcc, s33, v88
	s_waitcnt vmcnt(2)
	ds_write_b128 v121, v[52:55] offset:53248
	v_addc_co_u32_e32 v29, vcc, 0, v89, vcc
	s_waitcnt lgkmcnt(7)
	v_mfma_f32_16x16x32_bf16 v[52:55], v[210:213], v[202:205], v[32:35]
	v_mfma_f32_16x16x32_bf16 v[24:27], v[214:217], v[202:205], v[24:27]
	v_mfma_f32_16x16x32_bf16 v[20:23], v[218:221], v[202:205], v[20:23]
	v_mfma_f32_16x16x32_bf16 v[16:19], v[222:225], v[202:205], v[16:19]
	v_add_co_u32_e32 v28, vcc, s59, v88
	s_waitcnt vmcnt(1)
	ds_write_b128 v121, v[56:59] offset:57344
	v_addc_co_u32_e32 v29, vcc, 0, v89, vcc
	s_waitcnt lgkmcnt(7)
	v_mfma_f32_16x16x32_bf16 v[12:15], v[210:213], v[206:209], v[12:15]
	v_mfma_f32_16x16x32_bf16 v[8:11], v[214:217], v[206:209], v[8:11]
	v_mfma_f32_16x16x32_bf16 v[4:7], v[218:221], v[206:209], v[4:7]
	v_mfma_f32_16x16x32_bf16 v[0:3], v[222:225], v[206:209], v[0:3]
	s_waitcnt vmcnt(0)
	ds_write_b128 v121, v[60:63] offset:61440
	s_waitcnt lgkmcnt(0)
	s_barrier
	ds_read_b128 v[92:95], v123 offset:51200
	ds_read_b128 v[88:91], v123 offset:49152
	ds_read_b128 v[162:165], v123 offset:53248
	ds_read_b128 v[190:193], v123 offset:55296
	ds_read_b128 v[28:31], v122 offset:32768
	ds_read_b128 v[32:35], v122 offset:34816
	s_min_u32 s3, s2, 12
	s_lshl_b32 s92, s3, 7
	ds_read_b128 v[56:59], v122 offset:36864
	ds_read_b128 v[60:63], v122 offset:38912
	ds_read_b128 v[194:197], v124 offset:32768
	ds_read_b128 v[198:201], v124 offset:34816
	ds_read_b128 v[202:205], v124 offset:36864
	ds_read_b128 v[206:209], v124 offset:38912
	ds_read_b128 v[210:213], v125 offset:49152
	ds_read_b128 v[214:217], v125 offset:51200
	ds_read_b128 v[218:221], v125 offset:53248
	ds_read_b128 v[222:225], v125 offset:55296
	s_waitcnt lgkmcnt(11)
	v_mfma_f32_16x16x32_bf16 v[230:233], v[92:95], v[28:31], v[44:47]
	v_mfma_f32_16x16x32_bf16 v[226:229], v[88:91], v[28:31], v[36:39]
	s_nop 1
	v_lshl_add_u64 v[44:45], v[102:103], 0, s[92:93]
	v_add_co_u32_e32 v36, vcc, s11, v44
	v_mfma_f32_16x16x32_bf16 v[84:87], v[162:165], v[28:31], v[84:87]
	s_nop 0
	v_addc_co_u32_e32 v37, vcc, 0, v45, vcc
	v_mfma_f32_16x16x32_bf16 v[80:83], v[190:193], v[28:31], v[80:83]
	s_waitcnt lgkmcnt(10)
	v_mfma_f32_16x16x32_bf16 v[138:141], v[88:91], v[32:35], v[40:43]
	v_mfma_f32_16x16x32_bf16 v[72:75], v[92:95], v[32:35], v[72:75]
	v_mfma_f32_16x16x32_bf16 v[68:71], v[162:165], v[32:35], v[68:71]
	v_mfma_f32_16x16x32_bf16 v[64:67], v[190:193], v[32:35], v[64:67]
	v_add_co_u32_e32 v36, vcc, s33, v44
	s_nop 1
	v_addc_co_u32_e32 v37, vcc, 0, v45, vcc
	v_add_co_u32_e32 v40, vcc, s59, v44
	s_waitcnt lgkmcnt(9)
	v_mfma_f32_16x16x32_bf16 v[234:237], v[88:91], v[56:59], v[52:55]
	v_addc_co_u32_e32 v41, vcc, 0, v45, vcc
	v_mfma_f32_16x16x32_bf16 v[24:27], v[92:95], v[56:59], v[24:27]
	v_mfma_f32_16x16x32_bf16 v[20:23], v[162:165], v[56:59], v[20:23]
	v_mfma_f32_16x16x32_bf16 v[16:19], v[190:193], v[56:59], v[16:19]
	s_waitcnt lgkmcnt(8)
	v_mfma_f32_16x16x32_bf16 v[12:15], v[88:91], v[60:63], v[12:15]
	v_mfma_f32_16x16x32_bf16 v[8:11], v[92:95], v[60:63], v[8:11]
	v_mfma_f32_16x16x32_bf16 v[4:7], v[162:165], v[60:63], v[4:7]
	v_mfma_f32_16x16x32_bf16 v[0:3], v[190:193], v[60:63], v[0:3]
	v_lshl_add_u64 v[60:61], v[104:105], 0, s[92:93]
	v_add_co_u32_e32 v48, vcc, s11, v60
	s_nop 0
	s_nop 0
	v_addc_co_u32_e32 v49, vcc, 0, v61, vcc
	v_add_co_u32_e32 v56, vcc, s33, v60
	s_nop 1
	v_addc_co_u32_e32 v57, vcc, 0, v61, vcc
	s_waitcnt lgkmcnt(3)
	v_mfma_f32_16x16x32_bf16 v[92:95], v[210:213], v[194:197], v[226:229]
	s_waitcnt lgkmcnt(2)
	v_mfma_f32_16x16x32_bf16 v[88:91], v[214:217], v[194:197], v[230:233]
	s_waitcnt lgkmcnt(1)
	v_mfma_f32_16x16x32_bf16 v[84:87], v[218:221], v[194:197], v[84:87]
	s_waitcnt lgkmcnt(0)
	v_mfma_f32_16x16x32_bf16 v[80:83], v[222:225], v[194:197], v[80:83]
	v_add_co_u32_e32 v60, vcc, s59, v60
	s_nop 1
	v_addc_co_u32_e32 v61, vcc, 0, v61, vcc
	v_mfma_f32_16x16x32_bf16 v[76:79], v[210:213], v[198:201], v[138:141]
	v_mfma_f32_16x16x32_bf16 v[72:75], v[214:217], v[198:201], v[72:75]
	v_mfma_f32_16x16x32_bf16 v[68:71], v[218:221], v[198:201], v[68:71]
	v_mfma_f32_16x16x32_bf16 v[64:67], v[222:225], v[198:201], v[64:67]
	v_mfma_f32_16x16x32_bf16 v[48:51], v[210:213], v[202:205], v[234:237]
	v_mfma_f32_16x16x32_bf16 v[24:27], v[214:217], v[202:205], v[24:27]
	v_mfma_f32_16x16x32_bf16 v[20:23], v[218:221], v[202:205], v[20:23]
	v_mfma_f32_16x16x32_bf16 v[16:19], v[222:225], v[202:205], v[16:19]
	v_mfma_f32_16x16x32_bf16 v[12:15], v[210:213], v[206:209], v[12:15]
	v_mfma_f32_16x16x32_bf16 v[8:11], v[214:217], v[206:209], v[8:11]
	v_mfma_f32_16x16x32_bf16 v[4:7], v[218:221], v[206:209], v[4:7]
	v_mfma_f32_16x16x32_bf16 v[0:3], v[222:225], v[206:209], v[0:3]
	s_mov_b32 s3, s2
	s_waitcnt lgkmcnt(0)
	s_movk_i32 s2, 0x80
	v_cmp_gt_i32_e64 s[36:37], s2, v109
	s_add_i32 s2, 0, 0x10000
	v_lshl_add_u32 v126, v109, 2, s2
	s_and_saveexec_b64 s[2:3], s[36:37]
	v_readlane_b32 s16, v251, 44
	v_readlane_b32 s17, v251, 45
	s_cbranch_execz .LBB0_669
	s_waitcnt vmcnt(7)
	v_add_f32_e32 v28, 0, v112
	v_add_f32_e32 v28, v28, v113
	v_add_f32_e32 v28, v28, v114
	v_add_f32_e32 v28, v28, v115
	v_add_f32_e32 v28, v28, v116
	v_add_f32_e32 v28, v28, v117
	v_add_f32_e32 v28, v28, v118
	v_add_f32_e32 v28, v28, v119
	v_add_f32_e32 v28, v28, v127
	v_add_f32_e32 v28, v28, v128
	v_add_f32_e32 v28, v28, v130
	v_add_f32_e32 v28, v28, v132
	v_add_f32_e32 v28, v28, v133
	v_add_f32_e32 v28, v28, v134
	v_add_f32_e32 v28, v28, v135
	v_add_f32_e32 v28, v28, v136
	v_fmamk_f32 v28, v28, 0x3a800000, v167
	s_mov_b32 s21, 0x800000
	v_mul_f32_e32 v29, 0x4b800000, v28
	v_cmp_gt_f32_e32 vcc, s21, v28
	s_nop 1
	v_cndmask_b32_e32 v28, v28, v29, vcc
	v_rsq_f32_e32 v28, v28
	s_nop 0
	v_mul_f32_e32 v29, 0x45800000, v28
	v_cndmask_b32_e32 v28, v28, v29, vcc
	ds_write_b32 v126, v28

.Ltail702:
	s_add_i32 s2, s3, 2
	ds_read_b128 v[152:155], v123 offset:16384
	ds_read_b128 v[156:159], v123 offset:18432
	ds_read_b128 v[160:163], v123 offset:20480
	ds_read_b128 v[190:193], v123 offset:22528
	ds_read_b128 v[102:105], v122
	s_add_i32 s3, s3, 4
	ds_read_b128 v[140:143], v122 offset:2048
	s_min_u32 s3, s3, 15
	s_lshl_b32 s92, s3, 7
	ds_read_b128 v[144:147], v122 offset:4096
	v_lshl_add_u64 v[106:107], v[98:99], 0, s[92:93]
	ds_read_b128 v[148:151], v122 offset:6144
	ds_read_b128 v[194:197], v124
	ds_read_b128 v[198:201], v124 offset:2048
	ds_read_b128 v[202:205], v124 offset:4096
	ds_read_b128 v[206:209], v124 offset:6144
	ds_read_b128 v[210:213], v125 offset:16384
	ds_read_b128 v[214:217], v125 offset:18432
	ds_read_b128 v[218:221], v125 offset:20480
	ds_read_b128 v[222:225], v125 offset:22528
	s_waitcnt lgkmcnt(11)
	v_mfma_f32_16x16x32_bf16 v[60:63], v[152:155], v[102:105], v[60:63]
	v_mfma_f32_16x16x32_bf16 v[56:59], v[156:159], v[102:105], v[56:59]
	v_mfma_f32_16x16x32_bf16 v[52:55], v[160:163], v[102:105], v[52:55]
	v_mfma_f32_16x16x32_bf16 v[48:51], v[190:193], v[102:105], v[48:51]
	s_waitcnt vmcnt(7)
	ds_write_b128 v121, v[64:67] offset:32768
	v_add_co_u32_e32 v64, vcc, s11, v106
	s_waitcnt lgkmcnt(11)
	v_mfma_f32_16x16x32_bf16 v[44:47], v[152:155], v[140:143], v[44:47]
	v_addc_co_u32_e32 v65, vcc, 0, v107, vcc
	v_mfma_f32_16x16x32_bf16 v[40:43], v[156:159], v[140:143], v[40:43]
	v_mfma_f32_16x16x32_bf16 v[36:39], v[160:163], v[140:143], v[36:39]
	v_mfma_f32_16x16x32_bf16 v[32:35], v[190:193], v[140:143], v[32:35]
	v_add_co_u32_e32 v64, vcc, s33, v106
	s_waitcnt vmcnt(6)
	ds_write_b128 v121, v[68:71] offset:36864
	s_nop 0
	v_addc_co_u32_e32 v65, vcc, 0, v107, vcc
	s_waitcnt lgkmcnt(11)
	v_mfma_f32_16x16x32_bf16 v[28:31], v[152:155], v[144:147], v[28:31]
	v_mfma_f32_16x16x32_bf16 v[24:27], v[156:159], v[144:147], v[24:27]
	v_mfma_f32_16x16x32_bf16 v[20:23], v[160:163], v[144:147], v[20:23]
	v_mfma_f32_16x16x32_bf16 v[16:19], v[190:193], v[144:147], v[16:19]
	v_add_co_u32_e32 v64, vcc, s59, v106
	s_waitcnt vmcnt(5)
	ds_write_b128 v121, v[72:75] offset:40960
	s_nop 0
	v_addc_co_u32_e32 v65, vcc, 0, v107, vcc
	s_waitcnt lgkmcnt(11)
	v_mfma_f32_16x16x32_bf16 v[12:15], v[152:155], v[148:151], v[12:15]
	v_mfma_f32_16x16x32_bf16 v[8:11], v[156:159], v[148:151], v[8:11]
	v_mfma_f32_16x16x32_bf16 v[4:7], v[160:163], v[148:151], v[4:7]
	v_mfma_f32_16x16x32_bf16 v[0:3], v[190:193], v[148:151], v[0:3]
	v_lshl_add_u64 v[64:65], v[100:101], 0, s[92:93]
	v_add_co_u32_e32 v66, vcc, s11, v64
	s_waitcnt vmcnt(4)
	ds_write_b128 v121, v[80:83] offset:45056
	v_addc_co_u32_e32 v67, vcc, 0, v65, vcc
	s_waitcnt lgkmcnt(7)
	v_mfma_f32_16x16x32_bf16 v[60:63], v[210:213], v[194:197], v[60:63]
	s_waitcnt lgkmcnt(6)
	v_mfma_f32_16x16x32_bf16 v[56:59], v[214:217], v[194:197], v[56:59]
	s_waitcnt lgkmcnt(5)
	v_mfma_f32_16x16x32_bf16 v[52:55], v[218:221], v[194:197], v[52:55]
	s_waitcnt lgkmcnt(4)
	v_mfma_f32_16x16x32_bf16 v[48:51], v[222:225], v[194:197], v[48:51]
	s_waitcnt vmcnt(3)
	ds_write_b128 v121, v[76:79] offset:49152
	v_mfma_f32_16x16x32_bf16 v[44:47], v[210:213], v[198:201], v[44:47]
	v_mfma_f32_16x16x32_bf16 v[40:43], v[214:217], v[198:201], v[40:43]
	v_mfma_f32_16x16x32_bf16 v[36:39], v[218:221], v[198:201], v[36:39]
	v_mfma_f32_16x16x32_bf16 v[32:35], v[222:225], v[198:201], v[32:35]
	v_add_co_u32_e32 v66, vcc, s33, v64
	s_waitcnt vmcnt(2)
	ds_write_b128 v121, v[84:87] offset:53248
	v_addc_co_u32_e32 v67, vcc, 0, v65, vcc
	v_add_co_u32_e32 v64, vcc, s59, v64
	v_mfma_f32_16x16x32_bf16 v[28:31], v[210:213], v[202:205], v[28:31]
	s_nop 0
	v_addc_co_u32_e32 v65, vcc, 0, v65, vcc
	v_mfma_f32_16x16x32_bf16 v[24:27], v[214:217], v[202:205], v[24:27]
	v_mfma_f32_16x16x32_bf16 v[20:23], v[218:221], v[202:205], v[20:23]
	v_mfma_f32_16x16x32_bf16 v[16:19], v[222:225], v[202:205], v[16:19]
	s_waitcnt vmcnt(1)
	ds_write_b128 v121, v[88:91] offset:57344
	v_mfma_f32_16x16x32_bf16 v[12:15], v[210:213], v[206:209], v[12:15]
	v_mfma_f32_16x16x32_bf16 v[8:11], v[214:217], v[206:209], v[8:11]
	v_mfma_f32_16x16x32_bf16 v[4:7], v[218:221], v[206:209], v[4:7]
	v_mfma_f32_16x16x32_bf16 v[0:3], v[222:225], v[206:209], v[0:3]
	s_waitcnt vmcnt(0)
	ds_write_b128 v121, v[92:95] offset:61440
	s_waitcnt lgkmcnt(0)
	s_barrier
	ds_read_b128 v[80:83], v123 offset:49152
	ds_read_b128 v[84:87], v123 offset:51200
	ds_read_b128 v[88:91], v123 offset:53248
	ds_read_b128 v[92:95], v123 offset:55296
	ds_read_b128 v[64:67], v122 offset:32768
	ds_read_b128 v[68:71], v122 offset:34816
	s_min_u32 s3, s2, 12
	s_lshl_b32 s92, s3, 7
	ds_read_b128 v[72:75], v122 offset:36864
	ds_read_b128 v[76:79], v122 offset:38912
	v_lshl_add_u64 v[106:107], v[98:99], 0, s[92:93]
	ds_read_b128 v[194:197], v124 offset:32768
	ds_read_b128 v[198:201], v124 offset:34816
	ds_read_b128 v[202:205], v124 offset:36864
	ds_read_b128 v[206:209], v124 offset:38912
	ds_read_b128 v[210:213], v125 offset:49152
	ds_read_b128 v[214:217], v125 offset:51200
	ds_read_b128 v[218:221], v125 offset:53248
	ds_read_b128 v[222:225], v125 offset:55296
	s_waitcnt lgkmcnt(11)
	v_mfma_f32_16x16x32_bf16 v[60:63], v[80:83], v[64:67], v[60:63]
	v_mfma_f32_16x16x32_bf16 v[56:59], v[84:87], v[64:67], v[56:59]
	v_mfma_f32_16x16x32_bf16 v[52:55], v[88:91], v[64:67], v[52:55]
	v_mfma_f32_16x16x32_bf16 v[48:51], v[92:95], v[64:67], v[48:51]
	v_add_co_u32_e32 v102, vcc, s11, v106
	s_waitcnt lgkmcnt(10)
	v_mfma_f32_16x16x32_bf16 v[44:47], v[80:83], v[68:71], v[44:47]
	v_addc_co_u32_e32 v103, vcc, 0, v107, vcc
	v_mfma_f32_16x16x32_bf16 v[40:43], v[84:87], v[68:71], v[40:43]
	v_mfma_f32_16x16x32_bf16 v[36:39], v[88:91], v[68:71], v[36:39]
	v_mfma_f32_16x16x32_bf16 v[32:35], v[92:95], v[68:71], v[32:35]
	v_add_co_u32_e32 v102, vcc, s33, v106
	s_nop 1
	v_addc_co_u32_e32 v103, vcc, 0, v107, vcc
	s_waitcnt lgkmcnt(9)
	v_mfma_f32_16x16x32_bf16 v[28:31], v[80:83], v[72:75], v[28:31]
	v_mfma_f32_16x16x32_bf16 v[24:27], v[84:87], v[72:75], v[24:27]
	v_mfma_f32_16x16x32_bf16 v[20:23], v[88:91], v[72:75], v[20:23]
	v_mfma_f32_16x16x32_bf16 v[16:19], v[92:95], v[72:75], v[16:19]
	s_waitcnt lgkmcnt(8)
	v_mfma_f32_16x16x32_bf16 v[12:15], v[80:83], v[76:79], v[12:15]
	v_add_co_u32_e32 v80, vcc, s59, v106
	v_mfma_f32_16x16x32_bf16 v[0:3], v[92:95], v[76:79], v[0:3]
	s_nop 0
	v_addc_co_u32_e32 v81, vcc, 0, v107, vcc
	v_lshl_add_u64 v[92:93], v[100:101], 0, s[92:93]
	v_mfma_f32_16x16x32_bf16 v[8:11], v[84:87], v[76:79], v[8:11]
	v_add_co_u32_e32 v84, vcc, s11, v92
	s_nop 1
	v_addc_co_u32_e32 v85, vcc, 0, v93, vcc
	v_mfma_f32_16x16x32_bf16 v[4:7], v[88:91], v[76:79], v[4:7]
	v_add_co_u32_e32 v88, vcc, s33, v92
	s_nop 0
	s_nop 0
	v_addc_co_u32_e32 v89, vcc, 0, v93, vcc
	s_waitcnt lgkmcnt(3)
	v_mfma_f32_16x16x32_bf16 v[60:63], v[210:213], v[194:197], v[60:63]
	s_waitcnt lgkmcnt(2)
	v_mfma_f32_16x16x32_bf16 v[56:59], v[214:217], v[194:197], v[56:59]
	s_waitcnt lgkmcnt(1)
	v_mfma_f32_16x16x32_bf16 v[52:55], v[218:221], v[194:197], v[52:55]
	s_waitcnt lgkmcnt(0)
	v_mfma_f32_16x16x32_bf16 v[48:51], v[222:225], v[194:197], v[48:51]
	v_add_co_u32_e32 v92, vcc, s59, v92
	s_nop 1
	v_addc_co_u32_e32 v93, vcc, 0, v93, vcc
	v_mfma_f32_16x16x32_bf16 v[44:47], v[210:213], v[198:201], v[44:47]
	v_mfma_f32_16x16x32_bf16 v[40:43], v[214:217], v[198:201], v[40:43]
	v_mfma_f32_16x16x32_bf16 v[36:39], v[218:221], v[198:201], v[36:39]
	v_mfma_f32_16x16x32_bf16 v[32:35], v[222:225], v[198:201], v[32:35]
	v_mfma_f32_16x16x32_bf16 v[28:31], v[210:213], v[202:205], v[28:31]
	v_mfma_f32_16x16x32_bf16 v[24:27], v[214:217], v[202:205], v[24:27]
	v_mfma_f32_16x16x32_bf16 v[20:23], v[218:221], v[202:205], v[20:23]
	v_mfma_f32_16x16x32_bf16 v[16:19], v[222:225], v[202:205], v[16:19]
	v_mfma_f32_16x16x32_bf16 v[12:15], v[210:213], v[206:209], v[12:15]
	v_mfma_f32_16x16x32_bf16 v[8:11], v[214:217], v[206:209], v[8:11]
	v_mfma_f32_16x16x32_bf16 v[4:7], v[218:221], v[206:209], v[4:7]
	v_mfma_f32_16x16x32_bf16 v[0:3], v[222:225], v[206:209], v[0:3]
	s_mov_b32 s3, s2
	s_waitcnt lgkmcnt(0)
	s_and_saveexec_b64 s[2:3], s[36:37]
	s_cbranch_execz .LBB0_705
	s_waitcnt vmcnt(7)
	v_add_f32_e32 v64, 0, v96
	v_add_f32_e32 v64, v64, v97
	v_add_f32_e32 v64, v64, v108
	v_add_f32_e32 v64, v64, v109
	v_add_f32_e32 v64, v64, v110
	v_add_f32_e32 v64, v64, v111
	v_add_f32_e32 v64, v64, v118
	v_add_f32_e32 v64, v64, v119
	v_add_f32_e32 v64, v64, v128
	v_add_f32_e32 v64, v64, v132
	v_add_f32_e32 v64, v64, v133
	v_add_f32_e32 v64, v64, v134
	v_add_f32_e32 v64, v64, v135
	v_add_f32_e32 v64, v64, v136
	v_add_f32_e32 v64, v64, v137
	v_add_f32_e32 v64, v64, v138
	v_fmamk_f32 v64, v64, 0x3a800000, v167
	s_mov_b32 s17, 0x800000
	v_mul_f32_e32 v65, 0x4b800000, v64
	v_cmp_gt_f32_e32 vcc, s17, v64
	s_nop 1
	v_cndmask_b32_e32 v64, v64, v65, vcc
	v_rsq_f32_e32 v64, v64
	s_nop 0
	v_mul_f32_e32 v65, 0x45800000, v64
	v_cndmask_b32_e32 v64, v64, v65, vcc
	ds_write_b32 v126, v64

.Ltail739:
	s_add_i32 s2, s3, 2
	v_add_u32_e32 v130, v105, v106
	ds_read_b128 v[116:119], v130 offset:16384
	ds_read_b128 v[120:123], v130 offset:18432
	ds_read_b128 v[124:127], v130 offset:20480
	ds_read_b128 v[132:135], v130 offset:22528
	v_add_u32_e32 v128, v104, v106
	ds_read_b128 v[108:111], v128
	ds_read_b128 v[112:115], v128 offset:2048
	s_add_i32 s3, s3, 4
	s_min_u32 s3, s3, 15
	v_add_u32_e32 v148, v104, v107
	v_add_u32_e32 v149, v105, v107
	s_lshl_b32 s92, s3, 7
	ds_read_b128 v[136:139], v149 offset:18432
	ds_read_b128 v[140:143], v149 offset:20480
	ds_read_b128 v[144:147], v149 offset:22528
	s_waitcnt lgkmcnt(4)
	v_mfma_f32_16x16x32_bf16 v[72:75], v[116:119], v[108:111], v[72:75]
	v_lshl_add_u64 v[52:53], v[80:81], 0, s[92:93]
	v_add_co_u32_e32 v54, vcc, s11, v52
	v_mfma_f32_16x16x32_bf16 v[48:51], v[120:123], v[108:111], v[48:51]
	s_nop 0
	v_addc_co_u32_e32 v55, vcc, 0, v53, vcc
	v_mfma_f32_16x16x32_bf16 v[44:47], v[124:127], v[108:111], v[44:47]
	v_mfma_f32_16x16x32_bf16 v[40:43], v[132:135], v[108:111], v[40:43]
	s_waitcnt lgkmcnt(3)
	v_mfma_f32_16x16x32_bf16 v[108:111], v[116:119], v[112:115], v[16:19]
	s_nop 2
	ds_read_b128 v[16:19], v148
	v_mfma_f32_16x16x32_bf16 v[116:119], v[120:123], v[112:115], v[8:11]
	v_mfma_f32_16x16x32_bf16 v[120:123], v[124:127], v[112:115], v[4:7]
	ds_read_b128 v[124:127], v148 offset:2048
	v_mfma_f32_16x16x32_bf16 v[112:115], v[132:135], v[112:115], v[0:3]
	ds_read_b128 v[132:135], v149 offset:16384
	s_waitcnt vmcnt(0)
	ds_write_b128 v103, v[12:15] offset:53248
	v_add_co_u32_e32 v54, vcc, s33, v52
	s_waitcnt vmcnt(1)
	ds_write_b128 v103, v[20:23] offset:49152
	s_nop 0
	v_addc_co_u32_e32 v55, vcc, 0, v53, vcc
	v_add_co_u32_e32 v52, vcc, s59, v52
	s_nop 0
	s_nop 0
	v_addc_co_u32_e32 v53, vcc, 0, v53, vcc
	s_waitcnt vmcnt(2)
	ds_write_b128 v103, v[24:27] offset:45056
	v_lshl_add_u64 v[52:53], v[82:83], 0, s[92:93]
	s_waitcnt vmcnt(5)
	ds_write_b128 v103, v[36:39] offset:32768
	s_waitcnt lgkmcnt(4)
	v_mfma_f32_16x16x32_bf16 v[0:3], v[132:135], v[16:19], v[72:75]
	v_mfma_f32_16x16x32_bf16 v[4:7], v[136:139], v[16:19], v[48:51]
	v_add_co_u32_e32 v52, vcc, s11, v52
	s_waitcnt vmcnt(4)
	ds_write_b128 v103, v[32:35] offset:36864
	s_nop 0
	v_addc_co_u32_e32 v53, vcc, 0, v53, vcc
	v_mfma_f32_16x16x32_bf16 v[8:11], v[140:143], v[16:19], v[44:47]
	v_mfma_f32_16x16x32_bf16 v[16:19], v[144:147], v[16:19], v[40:43]
	s_waitcnt vmcnt(3)
	ds_write_b128 v103, v[28:31] offset:40960
	v_mfma_f32_16x16x32_bf16 v[40:43], v[132:135], v[124:127], v[108:111]
	v_mfma_f32_16x16x32_bf16 v[44:47], v[136:139], v[124:127], v[116:119]
	v_mfma_f32_16x16x32_bf16 v[48:51], v[140:143], v[124:127], v[120:123]
	v_mfma_f32_16x16x32_bf16 v[72:75], v[144:147], v[124:127], v[112:115]
	s_waitcnt lgkmcnt(0)
	s_barrier
	ds_read_b128 v[116:119], v130 offset:49152
	ds_read_b128 v[120:123], v130 offset:51200
	ds_read_b128 v[124:127], v130 offset:53248
	ds_read_b128 v[132:135], v130 offset:55296
	ds_read_b128 v[108:111], v128 offset:32768
	ds_read_b128 v[112:115], v128 offset:34816
	s_min_u32 s3, s2, 12
	s_lshl_b32 s92, s3, 7
	ds_read_b128 v[136:139], v149 offset:51200
	ds_read_b128 v[140:143], v149 offset:53248
	ds_read_b128 v[144:147], v149 offset:55296
	s_waitcnt lgkmcnt(4)
	v_mfma_f32_16x16x32_bf16 v[0:3], v[116:119], v[108:111], v[0:3]
	v_lshl_add_u64 v[12:13], v[80:81], 0, s[92:93]
	v_add_co_u32_e32 v14, vcc, s11, v12
	v_mfma_f32_16x16x32_bf16 v[4:7], v[120:123], v[108:111], v[4:7]
	s_nop 0
	v_addc_co_u32_e32 v15, vcc, 0, v13, vcc
	v_mfma_f32_16x16x32_bf16 v[8:11], v[124:127], v[108:111], v[8:11]
	v_mfma_f32_16x16x32_bf16 v[16:19], v[132:135], v[108:111], v[16:19]
	s_waitcnt lgkmcnt(3)
	v_mfma_f32_16x16x32_bf16 v[108:111], v[116:119], v[112:115], v[40:43]
	s_nop 2
	ds_read_b128 v[40:43], v148 offset:32768
	v_mfma_f32_16x16x32_bf16 v[116:119], v[120:123], v[112:115], v[44:47]
	v_mfma_f32_16x16x32_bf16 v[120:123], v[124:127], v[112:115], v[48:51]
	ds_read_b128 v[124:127], v148 offset:34816
	v_mfma_f32_16x16x32_bf16 v[112:115], v[132:135], v[112:115], v[72:75]
	ds_read_b128 v[132:135], v149 offset:49152
	v_add_co_u32_e32 v14, vcc, s33, v12
	s_nop 0
	s_nop 0
	v_addc_co_u32_e32 v15, vcc, 0, v13, vcc
	v_add_co_u32_e32 v12, vcc, s59, v12
	s_nop 0
	s_nop 0
	v_addc_co_u32_e32 v13, vcc, 0, v13, vcc
	v_lshl_add_u64 v[12:13], v[82:83], 0, s[92:93]
	s_waitcnt lgkmcnt(0)
	v_mfma_f32_16x16x32_bf16 v[72:75], v[132:135], v[40:43], v[0:3]
	v_mfma_f32_16x16x32_bf16 v[48:51], v[136:139], v[40:43], v[4:7]
	v_add_co_u32_e32 v12, vcc, s11, v12
	s_nop 0
	s_nop 0
	v_addc_co_u32_e32 v13, vcc, 0, v13, vcc
	v_mfma_f32_16x16x32_bf16 v[44:47], v[140:143], v[40:43], v[8:11]
	v_mfma_f32_16x16x32_bf16 v[40:43], v[144:147], v[40:43], v[16:19]
	v_mfma_f32_16x16x32_bf16 v[16:19], v[132:135], v[124:127], v[108:111]
	v_mfma_f32_16x16x32_bf16 v[8:11], v[136:139], v[124:127], v[116:119]
	v_mfma_f32_16x16x32_bf16 v[4:7], v[140:143], v[124:127], v[120:123]
	v_mfma_f32_16x16x32_bf16 v[0:3], v[144:147], v[124:127], v[112:115]
	s_mov_b32 s3, s2
	s_waitcnt lgkmcnt(0)
	s_movk_i32 s2, 0x80
	v_cmp_gt_i32_e32 vcc, s2, v85
	s_and_saveexec_b64 s[2:3], vcc
	s_cbranch_execz .LBB0_742
	s_waitcnt vmcnt(0)
	v_add_f32_e32 v12, 0, v102
	v_add_f32_e32 v12, v12, v86
	v_add_f32_e32 v12, v12, v87
	v_add_f32_e32 v12, v12, v88
	v_add_f32_e32 v12, v12, v89
	v_add_f32_e32 v12, v12, v90
	v_add_f32_e32 v12, v12, v91
	v_add_f32_e32 v12, v12, v92
	v_add_f32_e32 v12, v12, v93
	v_add_f32_e32 v12, v12, v95
	v_add_f32_e32 v12, v12, v96
	v_add_f32_e32 v12, v12, v97
	v_add_f32_e32 v12, v12, v98
	v_add_f32_e32 v12, v12, v99
	v_add_f32_e32 v12, v12, v100
	v_add_f32_e32 v12, v12, v101
	v_fmamk_f32 v12, v12, 0x3a800000, v167
	s_mov_b32 s16, 0x800000
	v_mul_f32_e32 v13, 0x4b800000, v12
	v_cmp_gt_f32_e32 vcc, s16, v12
	s_nop 1
	v_cndmask_b32_e32 v12, v12, v13, vcc
	v_rsq_f32_e32 v12, v12
	v_lshl_add_u32 v13, v85, 2, 0
	v_add_u32_e32 v13, 0x10000, v13
	v_mul_f32_e32 v14, 0x45800000, v12
	v_cndmask_b32_e32 v12, v12, v14, vcc
	ds_write_b32 v13, v12
